# v9 plus per-phase s_setprio flips removed from all GEMM K-loops
# speedup vs baseline: 1.0092x; 1.0092x over previous
; #define PG8_STAGE(bufoff, gbase, voff) do { _Pragma("unroll") for (int _i = 0; _i < 2; ++_i) \
;         __builtin_amdgcn_global_load_lds((const unsigned*)((const char*)(gbase) + (voff)[_i]), (LAS unsigned*)(lds + (bufoff) + ldsw + _i * 8192), 16, 0, 0); } while (0)
; #define PG8_LDA(dst, b, h) do { _Pragma("unroll") for (int m = 0; m < 4; ++m) _Pragma("unroll") for (int k = 0; k < 2; ++k) dst[m][k] = *(const LAS bf16x8*)(lds + PG8_SA(b, h) + aoff + m * 2048 + k * 1024); } while (0)
; #define PG8_LDB(dst, b, h) do { _Pragma("unroll") for (int n = 0; n < 2; ++n) _Pragma("unroll") for (int k = 0; k < 2; ++k) dst[n][k] = *(const LAS bf16x8*)(lds + PG8_SB(b, h) + boff + n * 2048 + k * 1024); } while (0)
; #define PG8_MMA(ai, bj, At, Bt) do { __builtin_amdgcn_s_setprio(1); _Pragma("unroll") for (int m = 0; m < 4; ++m) _Pragma("unroll") for (int n = 0; n < 2; ++n) _Pragma("unroll") for (int k = 0; k < 2; ++k) \
;         acc[ai][bj][m][n] = __builtin_amdgcn_mfma_f32_16x16x32_bf16(Bt[n][k], At[m][k], acc[ai][bj][m][n], 0, 0, 0); __builtin_amdgcn_s_setprio(0); } while (0)
; #define PG8_WAIT_L(n) asm volatile("s_waitcnt lgkmcnt(" #n ")" ::: "memory")
; #define PG8_BAR __builtin_amdgcn_s_barrier()
; #define PG8_SCHED __builtin_amdgcn_sched_barrier(0)
; template <class Epi>
; DEVI void gemm_phase(LAS unsigned char* lds, const bf16_t* gA, const bf16_t* gBt, const int lda, const int ldb, const int K, const StaticOrder S_, const Epi E) {
;     ...
;             PG8_LDB(B0, 0, 0); PG8_SCHED; PG8_LDA(At, 0, 0); PG8_STAGE(PG8_SA(1, 1), a1 + hstepA, voffA);
;             PG8_WAIT_L(8); PG8_BAR; PG8_WAIT_L(0); PG8_MMA(0, 0, At, B0); PG8_BAR; PG8_SCHED;
;             PG8_LDB(B1, 0, 1); PG8_STAGE(PG8_SB(0, 0), b2, voffB);
;             PG8_BAR; PG8_WAIT_L(0); PG8_MMA(0, 1, At, B1); PG8_BAR;
;             PG8_LDA(At, 0, 1); PG8_STAGE(PG8_SA(0, 0), a2, voffA);
;             PG8_BAR; PG8_WAIT_L(0); PG8_MMA(1, 0, At, B0); PG8_BAR; PG8_SCHED;
.LBB0_259:
	ds_read_b128 v[158:161], v151
	ds_read_b128 v[162:165], v151 offset:1024
	ds_read_b128 v[166:169], v151 offset:2048
	ds_read_b128 v[170:173], v151 offset:3072
	s_add_i32 s79, s26, 2
	s_add_u32 s28, s24, 0x80
	s_addc_u32 s27, s25, 0
	s_cmp_eq_u32 s96, s26
	s_cselect_b32 s26, s4, s28
	s_cselect_b32 s27, s5, s27
	s_cselect_b32 s29, s23, s78
	s_cselect_b32 s28, s22, s77
	v_lshl_add_u64 v[144:145], s[24:25], 0, v[138:139]
	s_add_i32 m0, s37, 0xc000
	ds_read_b128 v[174:177], v152
	ds_read_b128 v[178:181], v152 offset:1024
	ds_read_b128 v[182:185], v152 offset:2048
	ds_read_b128 v[186:189], v152 offset:3072
	ds_read_b128 v[190:193], v152 offset:4096
	ds_read_b128 v[198:201], v152 offset:5120
	ds_read_b128 v[202:205], v152 offset:6144
	ds_read_b128 v[206:209], v152 offset:7168
	global_load_lds_dwordx4 v[144:145], off
	v_lshl_add_u64 v[144:145], s[24:25], 0, v[140:141]
	s_add_i32 m0, s37, 0xe000
	s_nop 0
	global_load_lds_dwordx4 v[144:145], off
	s_waitcnt lgkmcnt(8)
	s_barrier
	s_waitcnt lgkmcnt(0)
	s_waitcnt lgkmcnt(0)
	v_mfma_f32_16x16x32_bf16 v[120:123], v[158:161], v[174:177], v[120:123]
	v_mfma_f32_16x16x32_bf16 v[116:119], v[166:169], v[174:177], v[116:119]
	v_mfma_f32_16x16x32_bf16 v[108:111], v[158:161], v[182:185], v[108:111]
	v_mfma_f32_16x16x32_bf16 v[100:103], v[166:169], v[182:185], v[100:103]
	v_mfma_f32_16x16x32_bf16 v[92:95], v[158:161], v[190:193], v[92:95]
	v_mfma_f32_16x16x32_bf16 v[84:87], v[166:169], v[190:193], v[84:87]
	v_mfma_f32_16x16x32_bf16 v[76:79], v[158:161], v[202:205], v[76:79]
	v_mfma_f32_16x16x32_bf16 v[68:71], v[166:169], v[202:205], v[68:71]
	v_mfma_f32_16x16x32_bf16 v[120:123], v[162:165], v[178:181], v[120:123]
	v_mfma_f32_16x16x32_bf16 v[116:119], v[170:173], v[178:181], v[116:119]
	v_mfma_f32_16x16x32_bf16 v[108:111], v[162:165], v[186:189], v[108:111]
	v_mfma_f32_16x16x32_bf16 v[100:103], v[170:173], v[186:189], v[100:103]
	v_mfma_f32_16x16x32_bf16 v[92:95], v[162:165], v[198:201], v[92:95]
	v_mfma_f32_16x16x32_bf16 v[84:87], v[170:173], v[198:201], v[84:87]
	v_mfma_f32_16x16x32_bf16 v[76:79], v[162:165], v[206:209], v[76:79]
	v_mfma_f32_16x16x32_bf16 v[68:71], v[170:173], v[206:209], v[68:71]
	s_barrier
	s_add_i32 vcc_lo, s41, s36
	v_lshl_add_u64 v[144:145], s[28:29], 0, v[130:131]
	s_mov_b32 m0, vcc_lo
	ds_read_b128 v[210:213], v153
	ds_read_b128 v[214:217], v153 offset:1024
	ds_read_b128 v[218:221], v153 offset:2048
	ds_read_b128 v[222:225], v153 offset:3072
	global_load_lds_dwordx4 v[144:145], off
	v_lshl_add_u64 v[194:195], s[28:29], 0, v[134:135]
	s_add_i32 m0, vcc_lo, 0x2000
	s_nop 0
	global_load_lds_dwordx4 v[194:195], off
	s_barrier
	s_waitcnt lgkmcnt(0)
	s_waitcnt lgkmcnt(0)
	v_mfma_f32_16x16x32_bf16 v[124:127], v[210:213], v[174:177], v[124:127]
	v_mfma_f32_16x16x32_bf16 v[112:115], v[218:221], v[174:177], v[112:115]
	v_mfma_f32_16x16x32_bf16 v[104:107], v[210:213], v[182:185], v[104:107]
	v_mfma_f32_16x16x32_bf16 v[96:99], v[218:221], v[182:185], v[96:99]
	v_mfma_f32_16x16x32_bf16 v[88:91], v[210:213], v[190:193], v[88:91]
	v_mfma_f32_16x16x32_bf16 v[80:83], v[218:221], v[190:193], v[80:83]
	v_mfma_f32_16x16x32_bf16 v[72:75], v[210:213], v[202:205], v[72:75]
	v_mfma_f32_16x16x32_bf16 v[64:67], v[218:221], v[202:205], v[64:67]
	v_mfma_f32_16x16x32_bf16 v[124:127], v[214:217], v[178:181], v[124:127]
	v_mfma_f32_16x16x32_bf16 v[112:115], v[222:225], v[178:181], v[112:115]
	v_mfma_f32_16x16x32_bf16 v[104:107], v[214:217], v[186:189], v[104:107]
	v_mfma_f32_16x16x32_bf16 v[96:99], v[222:225], v[186:189], v[96:99]
	v_mfma_f32_16x16x32_bf16 v[88:91], v[214:217], v[198:201], v[88:91]
	v_mfma_f32_16x16x32_bf16 v[80:83], v[222:225], v[198:201], v[80:83]
	v_mfma_f32_16x16x32_bf16 v[72:75], v[214:217], v[206:209], v[72:75]
	v_mfma_f32_16x16x32_bf16 v[64:67], v[222:225], v[206:209], v[64:67]
	s_mov_b32 m0, s37
	v_lshl_add_u64 v[226:227], s[26:27], 0, v[128:129]
	s_barrier
	ds_read_b128 v[174:177], v152 offset:16384
	ds_read_b128 v[178:181], v152 offset:17408
	ds_read_b128 v[182:185], v152 offset:18432
	ds_read_b128 v[186:189], v152 offset:19456
	ds_read_b128 v[190:193], v152 offset:20480
	ds_read_b128 v[198:201], v152 offset:21504
	ds_read_b128 v[202:205], v152 offset:22528
	ds_read_b128 v[206:209], v152 offset:23552
	global_load_lds_dwordx4 v[226:227], off
	v_lshl_add_u64 v[228:229], s[26:27], 0, v[132:133]
	s_mov_b32 m0, s48
	s_nop 0
	global_load_lds_dwordx4 v[228:229], off
	s_barrier
	s_waitcnt lgkmcnt(0)
	s_waitcnt lgkmcnt(0)
	v_mfma_f32_16x16x32_bf16 v[60:63], v[158:161], v[174:177], v[60:63]
	v_mfma_f32_16x16x32_bf16 v[56:59], v[166:169], v[174:177], v[56:59]
	v_mfma_f32_16x16x32_bf16 v[44:47], v[158:161], v[182:185], v[44:47]
	v_mfma_f32_16x16x32_bf16 v[40:43], v[166:169], v[182:185], v[40:43]
	v_mfma_f32_16x16x32_bf16 v[28:31], v[158:161], v[190:193], v[28:31]
	v_mfma_f32_16x16x32_bf16 v[24:27], v[166:169], v[190:193], v[24:27]
	v_mfma_f32_16x16x32_bf16 v[12:15], v[158:161], v[202:205], v[12:15]
	v_mfma_f32_16x16x32_bf16 v[8:11], v[166:169], v[202:205], v[8:11]
	v_mfma_f32_16x16x32_bf16 v[60:63], v[162:165], v[178:181], v[60:63]
	v_mfma_f32_16x16x32_bf16 v[56:59], v[170:173], v[178:181], v[56:59]
	v_mfma_f32_16x16x32_bf16 v[44:47], v[162:165], v[186:189], v[44:47]
	v_mfma_f32_16x16x32_bf16 v[40:43], v[170:173], v[186:189], v[40:43]
	v_mfma_f32_16x16x32_bf16 v[28:31], v[162:165], v[198:201], v[28:31]
	v_mfma_f32_16x16x32_bf16 v[24:27], v[170:173], v[198:201], v[24:27]
	v_mfma_f32_16x16x32_bf16 v[12:15], v[162:165], v[206:209], v[12:15]
	v_mfma_f32_16x16x32_bf16 v[8:11], v[170:173], v[206:209], v[8:11]
	s_barrier
; #define PG8_STAGE(bufoff, gbase, voff) do { _Pragma("unroll") for (int _i = 0; _i < 2; ++_i) \
;         __builtin_amdgcn_global_load_lds((const unsigned*)((const char*)(gbase) + (voff)[_i]), (LAS unsigned*)(lds + (bufoff) + ldsw + _i * 8192), 16, 0, 0); } while (0)
; #define PG8_LDA(dst, b, h) do { _Pragma("unroll") for (int m = 0; m < 4; ++m) _Pragma("unroll") for (int k = 0; k < 2; ++k) dst[m][k] = *(const LAS bf16x8*)(lds + PG8_SA(b, h) + aoff + m * 2048 + k * 1024); } while (0)
; #define PG8_LDB(dst, b, h) do { _Pragma("unroll") for (int n = 0; n < 2; ++n) _Pragma("unroll") for (int k = 0; k < 2; ++k) dst[n][k] = *(const LAS bf16x8*)(lds + PG8_SB(b, h) + boff + n * 2048 + k * 1024); } while (0)
; #define PG8_MMA(ai, bj, At, Bt) do { __builtin_amdgcn_s_setprio(1); _Pragma("unroll") for (int m = 0; m < 4; ++m) _Pragma("unroll") for (int n = 0; n < 2; ++n) _Pragma("unroll") for (int k = 0; k < 2; ++k) \
;         acc[ai][bj][m][n] = __builtin_amdgcn_mfma_f32_16x16x32_bf16(Bt[n][k], At[m][k], acc[ai][bj][m][n], 0, 0, 0); __builtin_amdgcn_s_setprio(0); } while (0)
; #define PG8_WAIT_V(n) asm volatile("s_waitcnt vmcnt(" #n ")" ::: "memory")
; #define PG8_WAIT_L(n) asm volatile("s_waitcnt lgkmcnt(" #n ")" ::: "memory")
; #define PG8_BAR __builtin_amdgcn_s_barrier()
; #define PG8_SCHED __builtin_amdgcn_sched_barrier(0)
; template <class Epi>
; DEVI void gemm_phase(LAS unsigned char* lds, const bf16_t* gA, const bf16_t* gBt, const int lda, const int ldb, const int K, const StaticOrder S_, const Epi E) {
;     ...
;             PG8_STAGE(PG8_SB(0, 1), b2 + hstepB, voffB);
;             PG8_WAIT_V(6); PG8_BAR; PG8_MMA(1, 1, At, B1); PG8_BAR;
;             PG8_LDB(B0, 1, 0); PG8_SCHED; PG8_LDA(At, 1, 0); PG8_STAGE(PG8_SA(0, 1), a2 + hstepA, voffA);
;             PG8_WAIT_L(8); PG8_BAR; PG8_WAIT_L(0); PG8_MMA(0, 0, At, B0); PG8_BAR; PG8_SCHED;
;             PG8_LDB(B1, 1, 1); PG8_STAGE(PG8_SB(1, 0), b3, voffB);
	s_add_u32 s28, s28, s8
	s_addc_u32 s29, s29, s9
	s_add_i32 vcc_lo, s0, s36
	v_lshl_add_u64 v[230:231], s[28:29], 0, v[130:131]
	s_mov_b32 m0, vcc_lo
	v_lshl_add_u64 v[232:233], s[28:29], 0, v[134:135]
	global_load_lds_dwordx4 v[230:231], off
	s_add_i32 m0, vcc_lo, 0x2000
	s_nop 0
	global_load_lds_dwordx4 v[232:233], off
	s_waitcnt vmcnt(6)
	s_barrier
	v_mfma_f32_16x16x32_bf16 v[52:55], v[210:213], v[174:177], v[52:55]
	v_mfma_f32_16x16x32_bf16 v[48:51], v[218:221], v[174:177], v[48:51]
	v_mfma_f32_16x16x32_bf16 v[36:39], v[210:213], v[182:185], v[36:39]
	v_mfma_f32_16x16x32_bf16 v[32:35], v[218:221], v[182:185], v[32:35]
	v_mfma_f32_16x16x32_bf16 v[20:23], v[210:213], v[190:193], v[20:23]
	v_mfma_f32_16x16x32_bf16 v[16:19], v[218:221], v[190:193], v[16:19]
	v_mfma_f32_16x16x32_bf16 v[4:7], v[210:213], v[202:205], v[4:7]
	v_mfma_f32_16x16x32_bf16 v[0:3], v[218:221], v[202:205], v[0:3]
	v_mfma_f32_16x16x32_bf16 v[52:55], v[214:217], v[178:181], v[52:55]
	v_mfma_f32_16x16x32_bf16 v[48:51], v[222:225], v[178:181], v[48:51]
	v_mfma_f32_16x16x32_bf16 v[36:39], v[214:217], v[186:189], v[36:39]
	v_mfma_f32_16x16x32_bf16 v[32:35], v[222:225], v[186:189], v[32:35]
	v_mfma_f32_16x16x32_bf16 v[20:23], v[214:217], v[198:201], v[20:23]
	v_mfma_f32_16x16x32_bf16 v[16:19], v[222:225], v[198:201], v[16:19]
	v_mfma_f32_16x16x32_bf16 v[4:7], v[214:217], v[206:209], v[4:7]
	v_mfma_f32_16x16x32_bf16 v[0:3], v[222:225], v[206:209], v[0:3]
	s_barrier
	ds_read_b128 v[158:161], v154
	ds_read_b128 v[162:165], v154 offset:1024
	ds_read_b128 v[166:169], v154 offset:2048
	ds_read_b128 v[170:173], v154 offset:3072
	s_add_u32 s26, s26, s2
	s_addc_u32 s27, s27, s3
	s_mov_b32 m0, s49
	v_lshl_add_u64 v[210:211], s[26:27], 0, v[128:129]
	ds_read_b128 v[174:177], v152 offset:32768
	ds_read_b128 v[178:181], v152 offset:33792
	ds_read_b128 v[182:185], v152 offset:34816
	ds_read_b128 v[186:189], v152 offset:35840
	ds_read_b128 v[190:193], v152 offset:36864
	ds_read_b128 v[198:201], v152 offset:37888
	ds_read_b128 v[202:205], v152 offset:38912
	ds_read_b128 v[206:209], v152 offset:39936
	global_load_lds_dwordx4 v[210:211], off
	v_lshl_add_u64 v[210:211], s[26:27], 0, v[132:133]
	s_mov_b32 m0, s51
	s_nop 0
	global_load_lds_dwordx4 v[210:211], off
	s_waitcnt lgkmcnt(8)
	s_barrier
	s_waitcnt lgkmcnt(0)
	s_waitcnt lgkmcnt(0)
	v_mfma_f32_16x16x32_bf16 v[120:123], v[158:161], v[174:177], v[120:123]
	v_mfma_f32_16x16x32_bf16 v[116:119], v[166:169], v[174:177], v[116:119]
	v_mfma_f32_16x16x32_bf16 v[108:111], v[158:161], v[182:185], v[108:111]
	v_mfma_f32_16x16x32_bf16 v[100:103], v[166:169], v[182:185], v[100:103]
	v_mfma_f32_16x16x32_bf16 v[92:95], v[158:161], v[190:193], v[92:95]
	v_mfma_f32_16x16x32_bf16 v[84:87], v[166:169], v[190:193], v[84:87]
	v_mfma_f32_16x16x32_bf16 v[76:79], v[158:161], v[202:205], v[76:79]
	v_mfma_f32_16x16x32_bf16 v[68:71], v[166:169], v[202:205], v[68:71]
	v_mfma_f32_16x16x32_bf16 v[120:123], v[162:165], v[178:181], v[120:123]
	v_mfma_f32_16x16x32_bf16 v[116:119], v[170:173], v[178:181], v[116:119]
	v_mfma_f32_16x16x32_bf16 v[108:111], v[162:165], v[186:189], v[108:111]
	v_mfma_f32_16x16x32_bf16 v[100:103], v[170:173], v[186:189], v[100:103]
	v_mfma_f32_16x16x32_bf16 v[92:95], v[162:165], v[198:201], v[92:95]
	v_mfma_f32_16x16x32_bf16 v[84:87], v[170:173], v[198:201], v[84:87]
	v_mfma_f32_16x16x32_bf16 v[76:79], v[162:165], v[206:209], v[76:79]
	v_mfma_f32_16x16x32_bf16 v[68:71], v[170:173], v[206:209], v[68:71]
	s_barrier
	s_add_i32 s26, s1, s36
	v_lshl_add_u64 v[144:145], v[144:145], 0, s[20:21]
	s_mov_b32 m0, s26
	ds_read_b128 v[210:213], v155
	ds_read_b128 v[214:217], v155 offset:1024
	ds_read_b128 v[218:221], v155 offset:2048
	ds_read_b128 v[222:225], v155 offset:3072
	global_load_lds_dwordx4 v[144:145], off
	v_lshl_add_u64 v[144:145], v[194:195], 0, s[20:21]
	s_add_i32 m0, s26, 0x2000
	s_nop 0
	global_load_lds_dwordx4 v[144:145], off
	s_barrier
; #define PG8_STAGE(bufoff, gbase, voff) do { _Pragma("unroll") for (int _i = 0; _i < 2; ++_i) \
;         __builtin_amdgcn_global_load_lds((const unsigned*)((const char*)(gbase) + (voff)[_i]), (LAS unsigned*)(lds + (bufoff) + ldsw + _i * 8192), 16, 0, 0); } while (0)
; #define PG8_LDA(dst, b, h) do { _Pragma("unroll") for (int m = 0; m < 4; ++m) _Pragma("unroll") for (int k = 0; k < 2; ++k) dst[m][k] = *(const LAS bf16x8*)(lds + PG8_SA(b, h) + aoff + m * 2048 + k * 1024); } while (0)
; #define PG8_MMA(ai, bj, At, Bt) do { __builtin_amdgcn_s_setprio(1); _Pragma("unroll") for (int m = 0; m < 4; ++m) _Pragma("unroll") for (int n = 0; n < 2; ++n) _Pragma("unroll") for (int k = 0; k < 2; ++k) \
;         acc[ai][bj][m][n] = __builtin_amdgcn_mfma_f32_16x16x32_bf16(Bt[n][k], At[m][k], acc[ai][bj][m][n], 0, 0, 0); __builtin_amdgcn_s_setprio(0); } while (0)
; #define PG8_WAIT_V(n) asm volatile("s_waitcnt vmcnt(" #n ")" ::: "memory")
; #define PG8_WAIT_L(n) asm volatile("s_waitcnt lgkmcnt(" #n ")" ::: "memory")
; #define PG8_BAR __builtin_amdgcn_s_barrier()
; #define PG8_SCHED __builtin_amdgcn_sched_barrier(0)
; template <class Epi>
; DEVI void gemm_phase(LAS unsigned char* lds, const bf16_t* gA, const bf16_t* gBt, const int lda, const int ldb, const int K, const StaticOrder S_, const Epi E) {
;     ...
;             PG8_BAR; PG8_WAIT_L(0); PG8_MMA(0, 1, At, B1); PG8_BAR;
;             PG8_LDA(At, 1, 1); PG8_STAGE(PG8_SA(1, 0), a3, voffA);
;             PG8_BAR; PG8_WAIT_L(0); PG8_MMA(1, 0, At, B0); PG8_BAR; PG8_SCHED;
;             PG8_STAGE(PG8_SB(1, 1), b3 + hstepB, voffB);
;             PG8_WAIT_V(6); PG8_BAR; PG8_MMA(1, 1, At, B1); PG8_BAR;
;         }
	s_waitcnt lgkmcnt(0)
	s_waitcnt lgkmcnt(0)
	v_mfma_f32_16x16x32_bf16 v[124:127], v[210:213], v[174:177], v[124:127]
	v_mfma_f32_16x16x32_bf16 v[112:115], v[218:221], v[174:177], v[112:115]
	v_mfma_f32_16x16x32_bf16 v[104:107], v[210:213], v[182:185], v[104:107]
	v_mfma_f32_16x16x32_bf16 v[96:99], v[218:221], v[182:185], v[96:99]
	v_mfma_f32_16x16x32_bf16 v[88:91], v[210:213], v[190:193], v[88:91]
	v_mfma_f32_16x16x32_bf16 v[80:83], v[218:221], v[190:193], v[80:83]
	v_mfma_f32_16x16x32_bf16 v[72:75], v[210:213], v[202:205], v[72:75]
	v_mfma_f32_16x16x32_bf16 v[64:67], v[218:221], v[202:205], v[64:67]
	v_mfma_f32_16x16x32_bf16 v[124:127], v[214:217], v[178:181], v[124:127]
	v_mfma_f32_16x16x32_bf16 v[112:115], v[222:225], v[178:181], v[112:115]
	v_mfma_f32_16x16x32_bf16 v[104:107], v[214:217], v[186:189], v[104:107]
	v_mfma_f32_16x16x32_bf16 v[96:99], v[222:225], v[186:189], v[96:99]
	v_mfma_f32_16x16x32_bf16 v[88:91], v[214:217], v[198:201], v[88:91]
	v_mfma_f32_16x16x32_bf16 v[80:83], v[222:225], v[198:201], v[80:83]
	v_mfma_f32_16x16x32_bf16 v[72:75], v[214:217], v[206:209], v[72:75]
	v_mfma_f32_16x16x32_bf16 v[64:67], v[222:225], v[206:209], v[64:67]
	s_mov_b32 m0, s50
	v_lshl_add_u64 v[144:145], v[226:227], 0, s[20:21]
	s_barrier
	ds_read_b128 v[174:177], v152 offset:49152
	ds_read_b128 v[178:181], v152 offset:50176
	ds_read_b128 v[182:185], v152 offset:51200
	ds_read_b128 v[186:189], v152 offset:52224
	ds_read_b128 v[190:193], v152 offset:53248
	ds_read_b128 v[198:201], v152 offset:54272
	ds_read_b128 v[202:205], v152 offset:55296
	ds_read_b128 v[206:209], v152 offset:56320
	global_load_lds_dwordx4 v[144:145], off
	v_lshl_add_u64 v[144:145], v[228:229], 0, s[20:21]
	s_mov_b32 m0, s60
	s_nop 0
	global_load_lds_dwordx4 v[144:145], off
	s_barrier
	s_waitcnt lgkmcnt(0)
	s_waitcnt lgkmcnt(0)
	v_mfma_f32_16x16x32_bf16 v[60:63], v[158:161], v[174:177], v[60:63]
	v_mfma_f32_16x16x32_bf16 v[56:59], v[166:169], v[174:177], v[56:59]
	v_mfma_f32_16x16x32_bf16 v[44:47], v[158:161], v[182:185], v[44:47]
	v_mfma_f32_16x16x32_bf16 v[40:43], v[166:169], v[182:185], v[40:43]
	v_mfma_f32_16x16x32_bf16 v[28:31], v[158:161], v[190:193], v[28:31]
	v_mfma_f32_16x16x32_bf16 v[24:27], v[166:169], v[190:193], v[24:27]
	v_mfma_f32_16x16x32_bf16 v[12:15], v[158:161], v[202:205], v[12:15]
	v_mfma_f32_16x16x32_bf16 v[8:11], v[166:169], v[202:205], v[8:11]
	v_mfma_f32_16x16x32_bf16 v[60:63], v[162:165], v[178:181], v[60:63]
	v_mfma_f32_16x16x32_bf16 v[56:59], v[170:173], v[178:181], v[56:59]
	v_mfma_f32_16x16x32_bf16 v[44:47], v[162:165], v[186:189], v[44:47]
	v_mfma_f32_16x16x32_bf16 v[40:43], v[170:173], v[186:189], v[40:43]
	v_mfma_f32_16x16x32_bf16 v[28:31], v[162:165], v[198:201], v[28:31]
	v_mfma_f32_16x16x32_bf16 v[24:27], v[170:173], v[198:201], v[24:27]
	v_mfma_f32_16x16x32_bf16 v[12:15], v[162:165], v[206:209], v[12:15]
	v_mfma_f32_16x16x32_bf16 v[8:11], v[170:173], v[206:209], v[8:11]
	s_barrier
	s_add_i32 s26, s31, s36
	v_lshl_add_u64 v[144:145], v[230:231], 0, s[20:21]
	s_mov_b32 m0, s26
	s_nop 0
	global_load_lds_dwordx4 v[144:145], off
	v_lshl_add_u64 v[144:145], v[232:233], 0, s[20:21]
	s_add_i32 m0, s26, 0x2000
	s_nop 0
	global_load_lds_dwordx4 v[144:145], off
	s_waitcnt vmcnt(6)
	s_barrier
	v_mfma_f32_16x16x32_bf16 v[52:55], v[210:213], v[174:177], v[52:55]
	v_mfma_f32_16x16x32_bf16 v[48:51], v[218:221], v[174:177], v[48:51]
	v_mfma_f32_16x16x32_bf16 v[36:39], v[210:213], v[182:185], v[36:39]
	v_mfma_f32_16x16x32_bf16 v[32:35], v[218:221], v[182:185], v[32:35]
	v_mfma_f32_16x16x32_bf16 v[20:23], v[210:213], v[190:193], v[20:23]
	v_mfma_f32_16x16x32_bf16 v[16:19], v[218:221], v[190:193], v[16:19]
	v_mfma_f32_16x16x32_bf16 v[4:7], v[210:213], v[202:205], v[4:7]
	v_mfma_f32_16x16x32_bf16 v[0:3], v[218:221], v[202:205], v[0:3]
	v_mfma_f32_16x16x32_bf16 v[52:55], v[214:217], v[178:181], v[52:55]
	v_mfma_f32_16x16x32_bf16 v[48:51], v[222:225], v[178:181], v[48:51]
	v_mfma_f32_16x16x32_bf16 v[36:39], v[214:217], v[186:189], v[36:39]
	v_mfma_f32_16x16x32_bf16 v[32:35], v[222:225], v[186:189], v[32:35]
	v_mfma_f32_16x16x32_bf16 v[20:23], v[214:217], v[198:201], v[20:23]
	v_mfma_f32_16x16x32_bf16 v[16:19], v[222:225], v[198:201], v[16:19]
	v_mfma_f32_16x16x32_bf16 v[4:7], v[214:217], v[206:209], v[4:7]
	v_mfma_f32_16x16x32_bf16 v[0:3], v[222:225], v[206:209], v[0:3]
	s_add_u32 s24, s24, 0x100
	s_addc_u32 s25, s25, 0
	s_add_u32 s77, s77, 0x100
	s_addc_u32 s78, s78, 0
	s_cmp_ge_i32 s79, s61
	s_mov_b32 s26, s79
	s_barrier
	s_cbranch_scc0 .LBB0_259

; #define PG8_STAGE(bufoff, gbase, voff) do { _Pragma("unroll") for (int _i = 0; _i < 2; ++_i) \
;         __builtin_amdgcn_global_load_lds((const unsigned*)((const char*)(gbase) + (voff)[_i]), (LAS unsigned*)(lds + (bufoff) + ldsw + _i * 8192), 16, 0, 0); } while (0)
; #define PG8_LDA(dst, b, h) do { _Pragma("unroll") for (int m = 0; m < 4; ++m) _Pragma("unroll") for (int k = 0; k < 2; ++k) dst[m][k] = *(const LAS bf16x8*)(lds + PG8_SA(b, h) + aoff + m * 2048 + k * 1024); } while (0)
; #define PG8_LDB(dst, b, h) do { _Pragma("unroll") for (int n = 0; n < 2; ++n) _Pragma("unroll") for (int k = 0; k < 2; ++k) dst[n][k] = *(const LAS bf16x8*)(lds + PG8_SB(b, h) + boff + n * 2048 + k * 1024); } while (0)
; #define PG8_MMA(ai, bj, At, Bt) do { __builtin_amdgcn_s_setprio(1); _Pragma("unroll") for (int m = 0; m < 4; ++m) _Pragma("unroll") for (int n = 0; n < 2; ++n) _Pragma("unroll") for (int k = 0; k < 2; ++k) \
;         acc[ai][bj][m][n] = __builtin_amdgcn_mfma_f32_16x16x32_bf16(Bt[n][k], At[m][k], acc[ai][bj][m][n], 0, 0, 0); __builtin_amdgcn_s_setprio(0); } while (0)
; #define PG8_WAIT_L(n) asm volatile("s_waitcnt lgkmcnt(" #n ")" ::: "memory")
; #define PG8_BAR __builtin_amdgcn_s_barrier()
; #define PG8_SCHED __builtin_amdgcn_sched_barrier(0)
; template <class Epi>
; DEVI void gemm_phase(LAS unsigned char* lds, const bf16_t* gA, const bf16_t* gBt, const int lda, const int ldb, const int K, const StaticOrder S_, const Epi E) {
;     ...
;             PG8_LDB(B0, 0, 0); PG8_SCHED; PG8_LDA(At, 0, 0); PG8_STAGE(PG8_SA(1, 1), a1 + hstepA, voffA);
;             PG8_WAIT_L(8); PG8_BAR; PG8_WAIT_L(0); PG8_MMA(0, 0, At, B0); PG8_BAR; PG8_SCHED;
;             PG8_LDB(B1, 0, 1); PG8_STAGE(PG8_SB(0, 0), b2, voffB);
;             PG8_BAR; PG8_WAIT_L(0); PG8_MMA(0, 1, At, B1); PG8_BAR;
;             PG8_LDA(At, 0, 1); PG8_STAGE(PG8_SA(0, 0), a2, voffA);
;             PG8_BAR; PG8_WAIT_L(0); PG8_MMA(1, 0, At, B0); PG8_BAR; PG8_SCHED;
.LBB0_388:
	ds_read_b128 v[128:131], v201
	ds_read_b128 v[132:135], v201 offset:1024
	ds_read_b128 v[136:139], v201 offset:2048
	ds_read_b128 v[140:143], v201 offset:3072
	s_add_i32 s74, s16, 2
	s_add_u32 s40, s14, 0x80
	s_addc_u32 s17, s15, 0
	s_cmp_eq_u32 s29, s16
	s_cselect_b32 s16, s12, s40
	s_cselect_b32 s17, s13, s17
	s_cselect_b32 s41, s43, s73
	s_cselect_b32 s40, s42, s72
	v_lshl_add_u64 v[164:165], s[14:15], 0, v[174:175]
	s_add_i32 m0, s24, 0xc000
	ds_read_b128 v[144:147], v202
	ds_read_b128 v[148:151], v202 offset:1024
	ds_read_b128 v[152:155], v202 offset:2048
	ds_read_b128 v[156:159], v202 offset:3072
	ds_read_b128 v[160:163], v202 offset:4096
	ds_read_b128 v[180:183], v202 offset:5120
	ds_read_b128 v[184:187], v202 offset:6144
	ds_read_b128 v[188:191], v202 offset:7168
	global_load_lds_dwordx4 v[164:165], off
	v_lshl_add_u64 v[164:165], s[14:15], 0, v[176:177]
	s_add_i32 m0, s24, 0xe000
	s_nop 0
	global_load_lds_dwordx4 v[164:165], off
	s_waitcnt lgkmcnt(8)
	s_barrier
	s_waitcnt lgkmcnt(0)
	s_waitcnt lgkmcnt(0)
	v_mfma_f32_16x16x32_bf16 v[124:127], v[128:131], v[144:147], v[124:127]
	v_mfma_f32_16x16x32_bf16 v[120:123], v[136:139], v[144:147], v[120:123]
	v_mfma_f32_16x16x32_bf16 v[108:111], v[128:131], v[152:155], v[108:111]
	v_mfma_f32_16x16x32_bf16 v[104:107], v[136:139], v[152:155], v[104:107]
	v_mfma_f32_16x16x32_bf16 v[92:95], v[128:131], v[160:163], v[92:95]
	v_mfma_f32_16x16x32_bf16 v[88:91], v[136:139], v[160:163], v[88:91]
	v_mfma_f32_16x16x32_bf16 v[76:79], v[128:131], v[184:187], v[76:79]
	v_mfma_f32_16x16x32_bf16 v[72:75], v[136:139], v[184:187], v[72:75]
	v_mfma_f32_16x16x32_bf16 v[124:127], v[132:135], v[148:151], v[124:127]
	v_mfma_f32_16x16x32_bf16 v[120:123], v[140:143], v[148:151], v[120:123]
	v_mfma_f32_16x16x32_bf16 v[108:111], v[132:135], v[156:159], v[108:111]
	v_mfma_f32_16x16x32_bf16 v[104:107], v[140:143], v[156:159], v[104:107]
	v_mfma_f32_16x16x32_bf16 v[92:95], v[132:135], v[180:183], v[92:95]
	v_mfma_f32_16x16x32_bf16 v[88:91], v[140:143], v[180:183], v[88:91]
	v_mfma_f32_16x16x32_bf16 v[76:79], v[132:135], v[188:191], v[76:79]
	v_mfma_f32_16x16x32_bf16 v[72:75], v[140:143], v[188:191], v[72:75]
	s_barrier
	s_add_i32 s75, s97, s22
	v_lshl_add_u64 v[164:165], s[40:41], 0, v[168:169]
	s_mov_b32 m0, s75
	ds_read_b128 v[192:195], v203
	ds_read_b128 v[206:209], v203 offset:1024
	ds_read_b128 v[210:213], v203 offset:2048
	ds_read_b128 v[214:217], v203 offset:3072
	global_load_lds_dwordx4 v[164:165], off
	v_lshl_add_u64 v[218:219], s[40:41], 0, v[172:173]
	s_add_i32 m0, s75, 0x2000
	s_nop 0
	global_load_lds_dwordx4 v[218:219], off
	s_barrier
	s_waitcnt lgkmcnt(0)
	s_waitcnt lgkmcnt(0)
	v_mfma_f32_16x16x32_bf16 v[116:119], v[192:195], v[144:147], v[116:119]
	v_mfma_f32_16x16x32_bf16 v[112:115], v[210:213], v[144:147], v[112:115]
	v_mfma_f32_16x16x32_bf16 v[100:103], v[192:195], v[152:155], v[100:103]
	v_mfma_f32_16x16x32_bf16 v[96:99], v[210:213], v[152:155], v[96:99]
	v_mfma_f32_16x16x32_bf16 v[84:87], v[192:195], v[160:163], v[84:87]
	v_mfma_f32_16x16x32_bf16 v[80:83], v[210:213], v[160:163], v[80:83]
	v_mfma_f32_16x16x32_bf16 v[68:71], v[192:195], v[184:187], v[68:71]
	v_mfma_f32_16x16x32_bf16 v[64:67], v[210:213], v[184:187], v[64:67]
	v_mfma_f32_16x16x32_bf16 v[116:119], v[206:209], v[148:151], v[116:119]
	v_mfma_f32_16x16x32_bf16 v[112:115], v[214:217], v[148:151], v[112:115]
	v_mfma_f32_16x16x32_bf16 v[100:103], v[206:209], v[156:159], v[100:103]
	v_mfma_f32_16x16x32_bf16 v[96:99], v[214:217], v[156:159], v[96:99]
	v_mfma_f32_16x16x32_bf16 v[84:87], v[206:209], v[180:183], v[84:87]
	v_mfma_f32_16x16x32_bf16 v[80:83], v[214:217], v[180:183], v[80:83]
	v_mfma_f32_16x16x32_bf16 v[68:71], v[206:209], v[188:191], v[68:71]
	v_mfma_f32_16x16x32_bf16 v[64:67], v[214:217], v[188:191], v[64:67]
	s_mov_b32 m0, s24
	v_lshl_add_u64 v[220:221], s[16:17], 0, v[166:167]
	s_barrier
	ds_read_b128 v[144:147], v202 offset:16384
	ds_read_b128 v[148:151], v202 offset:17408
	ds_read_b128 v[152:155], v202 offset:18432
	ds_read_b128 v[156:159], v202 offset:19456
	ds_read_b128 v[160:163], v202 offset:20480
	ds_read_b128 v[180:183], v202 offset:21504
	ds_read_b128 v[184:187], v202 offset:22528
	ds_read_b128 v[188:191], v202 offset:23552
	global_load_lds_dwordx4 v[220:221], off
	v_lshl_add_u64 v[222:223], s[16:17], 0, v[170:171]
	s_mov_b32 m0, s25
	s_nop 0
	global_load_lds_dwordx4 v[222:223], off
	s_barrier
	s_waitcnt lgkmcnt(0)
	s_waitcnt lgkmcnt(0)
	v_mfma_f32_16x16x32_bf16 v[60:63], v[128:131], v[144:147], v[60:63]
	v_mfma_f32_16x16x32_bf16 v[56:59], v[136:139], v[144:147], v[56:59]
	v_mfma_f32_16x16x32_bf16 v[44:47], v[128:131], v[152:155], v[44:47]
	v_mfma_f32_16x16x32_bf16 v[40:43], v[136:139], v[152:155], v[40:43]
	v_mfma_f32_16x16x32_bf16 v[28:31], v[128:131], v[160:163], v[28:31]
	v_mfma_f32_16x16x32_bf16 v[24:27], v[136:139], v[160:163], v[24:27]
	v_mfma_f32_16x16x32_bf16 v[12:15], v[128:131], v[184:187], v[12:15]
	v_mfma_f32_16x16x32_bf16 v[8:11], v[136:139], v[184:187], v[8:11]
	v_mfma_f32_16x16x32_bf16 v[60:63], v[132:135], v[148:151], v[60:63]
	v_mfma_f32_16x16x32_bf16 v[56:59], v[140:143], v[148:151], v[56:59]
	v_mfma_f32_16x16x32_bf16 v[44:47], v[132:135], v[156:159], v[44:47]
	v_mfma_f32_16x16x32_bf16 v[40:43], v[140:143], v[156:159], v[40:43]
	v_mfma_f32_16x16x32_bf16 v[28:31], v[132:135], v[180:183], v[28:31]
	v_mfma_f32_16x16x32_bf16 v[24:27], v[140:143], v[180:183], v[24:27]
	v_mfma_f32_16x16x32_bf16 v[12:15], v[132:135], v[188:191], v[12:15]
	v_mfma_f32_16x16x32_bf16 v[8:11], v[140:143], v[188:191], v[8:11]
	s_barrier
; #define PG8_STAGE(bufoff, gbase, voff) do { _Pragma("unroll") for (int _i = 0; _i < 2; ++_i) \
;         __builtin_amdgcn_global_load_lds((const unsigned*)((const char*)(gbase) + (voff)[_i]), (LAS unsigned*)(lds + (bufoff) + ldsw + _i * 8192), 16, 0, 0); } while (0)
; #define PG8_LDA(dst, b, h) do { _Pragma("unroll") for (int m = 0; m < 4; ++m) _Pragma("unroll") for (int k = 0; k < 2; ++k) dst[m][k] = *(const LAS bf16x8*)(lds + PG8_SA(b, h) + aoff + m * 2048 + k * 1024); } while (0)
; #define PG8_LDB(dst, b, h) do { _Pragma("unroll") for (int n = 0; n < 2; ++n) _Pragma("unroll") for (int k = 0; k < 2; ++k) dst[n][k] = *(const LAS bf16x8*)(lds + PG8_SB(b, h) + boff + n * 2048 + k * 1024); } while (0)
; #define PG8_MMA(ai, bj, At, Bt) do { __builtin_amdgcn_s_setprio(1); _Pragma("unroll") for (int m = 0; m < 4; ++m) _Pragma("unroll") for (int n = 0; n < 2; ++n) _Pragma("unroll") for (int k = 0; k < 2; ++k) \
;         acc[ai][bj][m][n] = __builtin_amdgcn_mfma_f32_16x16x32_bf16(Bt[n][k], At[m][k], acc[ai][bj][m][n], 0, 0, 0); __builtin_amdgcn_s_setprio(0); } while (0)
; #define PG8_WAIT_V(n) asm volatile("s_waitcnt vmcnt(" #n ")" ::: "memory")
; #define PG8_WAIT_L(n) asm volatile("s_waitcnt lgkmcnt(" #n ")" ::: "memory")
; #define PG8_BAR __builtin_amdgcn_s_barrier()
; #define PG8_SCHED __builtin_amdgcn_sched_barrier(0)
; template <class Epi>
; DEVI void gemm_phase(LAS unsigned char* lds, const bf16_t* gA, const bf16_t* gBt, const int lda, const int ldb, const int K, const StaticOrder S_, const Epi E) {
;     ...
;             PG8_STAGE(PG8_SB(0, 1), b2 + hstepB, voffB);
;             PG8_WAIT_V(6); PG8_BAR; PG8_MMA(1, 1, At, B1); PG8_BAR;
;             PG8_LDB(B0, 1, 0); PG8_SCHED; PG8_LDA(At, 1, 0); PG8_STAGE(PG8_SA(0, 1), a2 + hstepA, voffA);
;             PG8_WAIT_L(8); PG8_BAR; PG8_WAIT_L(0); PG8_MMA(0, 0, At, B0); PG8_BAR; PG8_SCHED;
;             PG8_LDB(B1, 1, 1); PG8_STAGE(PG8_SB(1, 0), b3, voffB);
	s_add_u32 s40, s40, s0
	s_addc_u32 s41, s41, s1
	s_add_i32 s75, s50, s22
	v_lshl_add_u64 v[224:225], s[40:41], 0, v[168:169]
	s_mov_b32 m0, s75
	v_lshl_add_u64 v[226:227], s[40:41], 0, v[172:173]
	global_load_lds_dwordx4 v[224:225], off
	s_add_i32 m0, s75, 0x2000
	s_nop 0
	global_load_lds_dwordx4 v[226:227], off
	s_waitcnt vmcnt(6)
	s_barrier
	v_mfma_f32_16x16x32_bf16 v[52:55], v[192:195], v[144:147], v[52:55]
	v_mfma_f32_16x16x32_bf16 v[48:51], v[210:213], v[144:147], v[48:51]
	v_mfma_f32_16x16x32_bf16 v[36:39], v[192:195], v[152:155], v[36:39]
	v_mfma_f32_16x16x32_bf16 v[32:35], v[210:213], v[152:155], v[32:35]
	v_mfma_f32_16x16x32_bf16 v[20:23], v[192:195], v[160:163], v[20:23]
	v_mfma_f32_16x16x32_bf16 v[16:19], v[210:213], v[160:163], v[16:19]
	v_mfma_f32_16x16x32_bf16 v[4:7], v[192:195], v[184:187], v[4:7]
	v_mfma_f32_16x16x32_bf16 v[0:3], v[210:213], v[184:187], v[0:3]
	v_mfma_f32_16x16x32_bf16 v[52:55], v[206:209], v[148:151], v[52:55]
	v_mfma_f32_16x16x32_bf16 v[48:51], v[214:217], v[148:151], v[48:51]
	v_mfma_f32_16x16x32_bf16 v[36:39], v[206:209], v[156:159], v[36:39]
	v_mfma_f32_16x16x32_bf16 v[32:35], v[214:217], v[156:159], v[32:35]
	v_mfma_f32_16x16x32_bf16 v[20:23], v[206:209], v[180:183], v[20:23]
	v_mfma_f32_16x16x32_bf16 v[16:19], v[214:217], v[180:183], v[16:19]
	v_mfma_f32_16x16x32_bf16 v[4:7], v[206:209], v[188:191], v[4:7]
	v_mfma_f32_16x16x32_bf16 v[0:3], v[214:217], v[188:191], v[0:3]
	s_add_i32 s40, 0, 0x18000
	v_add_u32_e32 v140, s40, v199
	s_barrier
	ds_read_b128 v[128:131], v140
	ds_read_b128 v[132:135], v140 offset:1024
	ds_read_b128 v[136:139], v140 offset:2048
	ds_read_b128 v[140:143], v140 offset:3072
	s_add_u32 s16, s16, s48
	s_addc_u32 s17, s17, s49
	s_mov_b32 m0, s26
	v_lshl_add_u64 v[192:193], s[16:17], 0, v[166:167]
	ds_read_b128 v[144:147], v202 offset:32768
	ds_read_b128 v[148:151], v202 offset:33792
	ds_read_b128 v[152:155], v202 offset:34816
	ds_read_b128 v[156:159], v202 offset:35840
	ds_read_b128 v[160:163], v202 offset:36864
	ds_read_b128 v[180:183], v202 offset:37888
	ds_read_b128 v[184:187], v202 offset:38912
	ds_read_b128 v[188:191], v202 offset:39936
	global_load_lds_dwordx4 v[192:193], off
	v_lshl_add_u64 v[192:193], s[16:17], 0, v[170:171]
	s_mov_b32 m0, s27
	s_nop 0
	global_load_lds_dwordx4 v[192:193], off
	s_waitcnt lgkmcnt(8)
	s_barrier
	s_waitcnt lgkmcnt(0)
	s_waitcnt lgkmcnt(0)
	v_mfma_f32_16x16x32_bf16 v[124:127], v[128:131], v[144:147], v[124:127]
	v_mfma_f32_16x16x32_bf16 v[120:123], v[136:139], v[144:147], v[120:123]
	v_mfma_f32_16x16x32_bf16 v[108:111], v[128:131], v[152:155], v[108:111]
	v_mfma_f32_16x16x32_bf16 v[104:107], v[136:139], v[152:155], v[104:107]
	v_mfma_f32_16x16x32_bf16 v[92:95], v[128:131], v[160:163], v[92:95]
	v_mfma_f32_16x16x32_bf16 v[88:91], v[136:139], v[160:163], v[88:91]
	v_mfma_f32_16x16x32_bf16 v[76:79], v[128:131], v[184:187], v[76:79]
	v_mfma_f32_16x16x32_bf16 v[72:75], v[136:139], v[184:187], v[72:75]
	v_mfma_f32_16x16x32_bf16 v[124:127], v[132:135], v[148:151], v[124:127]
	v_mfma_f32_16x16x32_bf16 v[120:123], v[140:143], v[148:151], v[120:123]
	v_mfma_f32_16x16x32_bf16 v[108:111], v[132:135], v[156:159], v[108:111]
	v_mfma_f32_16x16x32_bf16 v[104:107], v[140:143], v[156:159], v[104:107]
	v_mfma_f32_16x16x32_bf16 v[92:95], v[132:135], v[180:183], v[92:95]
	v_mfma_f32_16x16x32_bf16 v[88:91], v[140:143], v[180:183], v[88:91]
	v_mfma_f32_16x16x32_bf16 v[76:79], v[132:135], v[188:191], v[76:79]
	v_mfma_f32_16x16x32_bf16 v[72:75], v[140:143], v[188:191], v[72:75]
	s_barrier
	s_add_i32 s16, 0, 0x1c000
	s_add_i32 s17, s40, s22
	v_add_u32_e32 v214, s16, v199
	v_lshl_add_u64 v[164:165], v[164:165], 0, s[10:11]
	s_mov_b32 m0, s17
	ds_read_b128 v[192:195], v214
	ds_read_b128 v[206:209], v214 offset:1024
	ds_read_b128 v[210:213], v214 offset:2048
	ds_read_b128 v[214:217], v214 offset:3072
	global_load_lds_dwordx4 v[164:165], off
	v_lshl_add_u64 v[164:165], v[218:219], 0, s[10:11]
	s_add_i32 m0, s17, 0x2000
	s_nop 0
	global_load_lds_dwordx4 v[164:165], off
	s_barrier
; #define PG8_STAGE(bufoff, gbase, voff) do { _Pragma("unroll") for (int _i = 0; _i < 2; ++_i) \
;         __builtin_amdgcn_global_load_lds((const unsigned*)((const char*)(gbase) + (voff)[_i]), (LAS unsigned*)(lds + (bufoff) + ldsw + _i * 8192), 16, 0, 0); } while (0)
; #define PG8_LDA(dst, b, h) do { _Pragma("unroll") for (int m = 0; m < 4; ++m) _Pragma("unroll") for (int k = 0; k < 2; ++k) dst[m][k] = *(const LAS bf16x8*)(lds + PG8_SA(b, h) + aoff + m * 2048 + k * 1024); } while (0)
; #define PG8_MMA(ai, bj, At, Bt) do { __builtin_amdgcn_s_setprio(1); _Pragma("unroll") for (int m = 0; m < 4; ++m) _Pragma("unroll") for (int n = 0; n < 2; ++n) _Pragma("unroll") for (int k = 0; k < 2; ++k) \
;         acc[ai][bj][m][n] = __builtin_amdgcn_mfma_f32_16x16x32_bf16(Bt[n][k], At[m][k], acc[ai][bj][m][n], 0, 0, 0); __builtin_amdgcn_s_setprio(0); } while (0)
; #define PG8_WAIT_V(n) asm volatile("s_waitcnt vmcnt(" #n ")" ::: "memory")
; #define PG8_WAIT_L(n) asm volatile("s_waitcnt lgkmcnt(" #n ")" ::: "memory")
; #define PG8_BAR __builtin_amdgcn_s_barrier()
; #define PG8_SCHED __builtin_amdgcn_sched_barrier(0)
; template <class Epi>
; DEVI void gemm_phase(LAS unsigned char* lds, const bf16_t* gA, const bf16_t* gBt, const int lda, const int ldb, const int K, const StaticOrder S_, const Epi E) {
;     ...
;             PG8_BAR; PG8_WAIT_L(0); PG8_MMA(0, 1, At, B1); PG8_BAR;
;             PG8_LDA(At, 1, 1); PG8_STAGE(PG8_SA(1, 0), a3, voffA);
;             PG8_BAR; PG8_WAIT_L(0); PG8_MMA(1, 0, At, B0); PG8_BAR; PG8_SCHED;
;             PG8_STAGE(PG8_SB(1, 1), b3 + hstepB, voffB);
;             PG8_WAIT_V(6); PG8_BAR; PG8_MMA(1, 1, At, B1); PG8_BAR;
;         }
	s_waitcnt lgkmcnt(0)
	s_waitcnt lgkmcnt(0)
	v_mfma_f32_16x16x32_bf16 v[116:119], v[192:195], v[144:147], v[116:119]
	v_mfma_f32_16x16x32_bf16 v[112:115], v[210:213], v[144:147], v[112:115]
	v_mfma_f32_16x16x32_bf16 v[100:103], v[192:195], v[152:155], v[100:103]
	v_mfma_f32_16x16x32_bf16 v[96:99], v[210:213], v[152:155], v[96:99]
	v_mfma_f32_16x16x32_bf16 v[84:87], v[192:195], v[160:163], v[84:87]
	v_mfma_f32_16x16x32_bf16 v[80:83], v[210:213], v[160:163], v[80:83]
	v_mfma_f32_16x16x32_bf16 v[68:71], v[192:195], v[184:187], v[68:71]
	v_mfma_f32_16x16x32_bf16 v[64:67], v[210:213], v[184:187], v[64:67]
	v_mfma_f32_16x16x32_bf16 v[116:119], v[206:209], v[148:151], v[116:119]
	v_mfma_f32_16x16x32_bf16 v[112:115], v[214:217], v[148:151], v[112:115]
	v_mfma_f32_16x16x32_bf16 v[100:103], v[206:209], v[156:159], v[100:103]
	v_mfma_f32_16x16x32_bf16 v[96:99], v[214:217], v[156:159], v[96:99]
	v_mfma_f32_16x16x32_bf16 v[84:87], v[206:209], v[180:183], v[84:87]
	v_mfma_f32_16x16x32_bf16 v[80:83], v[214:217], v[180:183], v[80:83]
	v_mfma_f32_16x16x32_bf16 v[68:71], v[206:209], v[188:191], v[68:71]
	v_mfma_f32_16x16x32_bf16 v[64:67], v[214:217], v[188:191], v[64:67]
	s_mov_b32 m0, s18
	v_lshl_add_u64 v[164:165], v[220:221], 0, s[10:11]
	s_barrier
	ds_read_b128 v[144:147], v202 offset:49152
	ds_read_b128 v[148:151], v202 offset:50176
	ds_read_b128 v[152:155], v202 offset:51200
	ds_read_b128 v[156:159], v202 offset:52224
	ds_read_b128 v[160:163], v202 offset:53248
	ds_read_b128 v[180:183], v202 offset:54272
	ds_read_b128 v[184:187], v202 offset:55296
	ds_read_b128 v[188:191], v202 offset:56320
	global_load_lds_dwordx4 v[164:165], off
	v_lshl_add_u64 v[164:165], v[222:223], 0, s[10:11]
	s_mov_b32 m0, s19
	s_nop 0
	global_load_lds_dwordx4 v[164:165], off
	s_barrier
	s_waitcnt lgkmcnt(0)
	s_waitcnt lgkmcnt(0)
	v_mfma_f32_16x16x32_bf16 v[60:63], v[128:131], v[144:147], v[60:63]
	v_mfma_f32_16x16x32_bf16 v[56:59], v[136:139], v[144:147], v[56:59]
	v_mfma_f32_16x16x32_bf16 v[44:47], v[128:131], v[152:155], v[44:47]
	v_mfma_f32_16x16x32_bf16 v[40:43], v[136:139], v[152:155], v[40:43]
	v_mfma_f32_16x16x32_bf16 v[28:31], v[128:131], v[160:163], v[28:31]
	v_mfma_f32_16x16x32_bf16 v[24:27], v[136:139], v[160:163], v[24:27]
	v_mfma_f32_16x16x32_bf16 v[12:15], v[128:131], v[184:187], v[12:15]
	v_mfma_f32_16x16x32_bf16 v[8:11], v[136:139], v[184:187], v[8:11]
	v_mfma_f32_16x16x32_bf16 v[60:63], v[132:135], v[148:151], v[60:63]
	v_mfma_f32_16x16x32_bf16 v[56:59], v[140:143], v[148:151], v[56:59]
	v_mfma_f32_16x16x32_bf16 v[44:47], v[132:135], v[156:159], v[44:47]
	v_mfma_f32_16x16x32_bf16 v[40:43], v[140:143], v[156:159], v[40:43]
	v_mfma_f32_16x16x32_bf16 v[28:31], v[132:135], v[180:183], v[28:31]
	v_mfma_f32_16x16x32_bf16 v[24:27], v[140:143], v[180:183], v[24:27]
	v_mfma_f32_16x16x32_bf16 v[12:15], v[132:135], v[188:191], v[12:15]
	v_mfma_f32_16x16x32_bf16 v[8:11], v[140:143], v[188:191], v[8:11]
	s_barrier
	s_add_i32 s16, s16, s22
	v_lshl_add_u64 v[128:129], v[224:225], 0, s[10:11]
	s_mov_b32 m0, s16
	s_nop 0
	global_load_lds_dwordx4 v[128:129], off
	v_lshl_add_u64 v[128:129], v[226:227], 0, s[10:11]
	s_add_i32 m0, s16, 0x2000
	s_nop 0
	global_load_lds_dwordx4 v[128:129], off
	s_waitcnt vmcnt(6)
	s_barrier
	v_mfma_f32_16x16x32_bf16 v[52:55], v[192:195], v[144:147], v[52:55]
	v_mfma_f32_16x16x32_bf16 v[48:51], v[210:213], v[144:147], v[48:51]
	v_mfma_f32_16x16x32_bf16 v[36:39], v[192:195], v[152:155], v[36:39]
	v_mfma_f32_16x16x32_bf16 v[32:35], v[210:213], v[152:155], v[32:35]
	v_mfma_f32_16x16x32_bf16 v[20:23], v[192:195], v[160:163], v[20:23]
	v_mfma_f32_16x16x32_bf16 v[16:19], v[210:213], v[160:163], v[16:19]
	v_mfma_f32_16x16x32_bf16 v[4:7], v[192:195], v[184:187], v[4:7]
	v_mfma_f32_16x16x32_bf16 v[0:3], v[210:213], v[184:187], v[0:3]
	v_mfma_f32_16x16x32_bf16 v[52:55], v[206:209], v[148:151], v[52:55]
	v_mfma_f32_16x16x32_bf16 v[48:51], v[214:217], v[148:151], v[48:51]
	v_mfma_f32_16x16x32_bf16 v[36:39], v[206:209], v[156:159], v[36:39]
	v_mfma_f32_16x16x32_bf16 v[32:35], v[214:217], v[156:159], v[32:35]
	v_mfma_f32_16x16x32_bf16 v[20:23], v[206:209], v[180:183], v[20:23]
	v_mfma_f32_16x16x32_bf16 v[16:19], v[214:217], v[180:183], v[16:19]
	v_mfma_f32_16x16x32_bf16 v[4:7], v[206:209], v[188:191], v[4:7]
	v_mfma_f32_16x16x32_bf16 v[0:3], v[214:217], v[188:191], v[0:3]
	s_add_u32 s14, s14, 0x100
	s_addc_u32 s15, s15, 0
	s_add_u32 s72, s72, 0x100
	s_addc_u32 s73, s73, 0
	s_cmp_ge_i32 s74, s28
	s_mov_b32 s16, s74
	s_barrier
	s_cbranch_scc0 .LBB0_388

; #define PG8_STAGE(bufoff, gbase, voff) do { _Pragma("unroll") for (int _i = 0; _i < 2; ++_i) \
;         __builtin_amdgcn_global_load_lds((const unsigned*)((const char*)(gbase) + (voff)[_i]), (LAS unsigned*)(lds + (bufoff) + ldsw + _i * 8192), 16, 0, 0); } while (0)
; #define PG8_LDA(dst, b, h) do { _Pragma("unroll") for (int m = 0; m < 4; ++m) _Pragma("unroll") for (int k = 0; k < 2; ++k) dst[m][k] = *(const LAS bf16x8*)(lds + PG8_SA(b, h) + aoff + m * 2048 + k * 1024); } while (0)
; #define PG8_LDB(dst, b, h) do { _Pragma("unroll") for (int n = 0; n < 2; ++n) _Pragma("unroll") for (int k = 0; k < 2; ++k) dst[n][k] = *(const LAS bf16x8*)(lds + PG8_SB(b, h) + boff + n * 2048 + k * 1024); } while (0)
; #define PG8_MMA(ai, bj, At, Bt) do { __builtin_amdgcn_s_setprio(1); _Pragma("unroll") for (int m = 0; m < 4; ++m) _Pragma("unroll") for (int n = 0; n < 2; ++n) _Pragma("unroll") for (int k = 0; k < 2; ++k) \
;         acc[ai][bj][m][n] = __builtin_amdgcn_mfma_f32_16x16x32_bf16(Bt[n][k], At[m][k], acc[ai][bj][m][n], 0, 0, 0); __builtin_amdgcn_s_setprio(0); } while (0)
; #define PG8_WAIT_L(n) asm volatile("s_waitcnt lgkmcnt(" #n ")" ::: "memory")
; #define PG8_BAR __builtin_amdgcn_s_barrier()
; #define PG8_SCHED __builtin_amdgcn_sched_barrier(0)
; template <class Epi>
; DEVI void gemm_phase(LAS unsigned char* lds, const bf16_t* gA, const bf16_t* gBt, const int lda, const int ldb, const int K, const StaticOrder S_, const Epi E) {
;     ...
;             PG8_LDB(B0, 0, 0); PG8_SCHED; PG8_LDA(At, 0, 0); PG8_STAGE(PG8_SA(1, 1), a1 + hstepA, voffA);
;             PG8_WAIT_L(8); PG8_BAR; PG8_WAIT_L(0); PG8_MMA(0, 0, At, B0); PG8_BAR; PG8_SCHED;
;             PG8_LDB(B1, 0, 1); PG8_STAGE(PG8_SB(0, 0), b2, voffB);
;             PG8_BAR; PG8_WAIT_L(0); PG8_MMA(0, 1, At, B1); PG8_BAR;
;             PG8_LDA(At, 0, 1); PG8_STAGE(PG8_SA(0, 0), a2, voffA);
;             PG8_BAR; PG8_WAIT_L(0); PG8_MMA(1, 0, At, B0); PG8_BAR; PG8_SCHED;
.LBB0_519:
	ds_read_b128 v[160:163], v153
	ds_read_b128 v[164:167], v153 offset:1024
	ds_read_b128 v[168:171], v153 offset:2048
	ds_read_b128 v[172:175], v153 offset:3072
	s_add_i32 s77, s16, 2
	s_add_u32 s40, s14, 0x80
	s_addc_u32 s17, s15, 0
	s_cmp_eq_u32 s26, s16
	s_cselect_b32 s16, s48, s40
	s_cselect_b32 s17, s49, s17
	s_cselect_b32 s41, s61, s69
	s_cselect_b32 s40, s60, s68
	v_lshl_add_u64 v[144:145], s[14:15], 0, v[138:139]
	s_add_i32 m0, s19, 0xc000
	ds_read_b128 v[176:179], v154
	ds_read_b128 v[180:183], v154 offset:1024
	ds_read_b128 v[184:187], v154 offset:2048
	ds_read_b128 v[188:191], v154 offset:3072
	ds_read_b128 v[192:195], v154 offset:4096
	ds_read_b128 v[198:201], v154 offset:5120
	ds_read_b128 v[202:205], v154 offset:6144
	ds_read_b128 v[206:209], v154 offset:7168
	global_load_lds_dwordx4 v[144:145], off
	v_lshl_add_u64 v[144:145], s[14:15], 0, v[140:141]
	s_add_i32 m0, s19, 0xe000
	s_nop 0
	global_load_lds_dwordx4 v[144:145], off
	s_waitcnt lgkmcnt(8)
	s_barrier
	s_waitcnt lgkmcnt(0)
	s_waitcnt lgkmcnt(0)
	v_mfma_f32_16x16x32_bf16 v[124:127], v[160:163], v[176:179], v[124:127]
	v_mfma_f32_16x16x32_bf16 v[120:123], v[168:171], v[176:179], v[120:123]
	v_mfma_f32_16x16x32_bf16 v[108:111], v[160:163], v[184:187], v[108:111]
	v_mfma_f32_16x16x32_bf16 v[104:107], v[168:171], v[184:187], v[104:107]
	v_mfma_f32_16x16x32_bf16 v[92:95], v[160:163], v[192:195], v[92:95]
	v_mfma_f32_16x16x32_bf16 v[88:91], v[168:171], v[192:195], v[88:91]
	v_mfma_f32_16x16x32_bf16 v[76:79], v[160:163], v[202:205], v[76:79]
	v_mfma_f32_16x16x32_bf16 v[72:75], v[168:171], v[202:205], v[72:75]
	v_mfma_f32_16x16x32_bf16 v[124:127], v[164:167], v[180:183], v[124:127]
	v_mfma_f32_16x16x32_bf16 v[120:123], v[172:175], v[180:183], v[120:123]
	v_mfma_f32_16x16x32_bf16 v[108:111], v[164:167], v[188:191], v[108:111]
	v_mfma_f32_16x16x32_bf16 v[104:107], v[172:175], v[188:191], v[104:107]
	v_mfma_f32_16x16x32_bf16 v[92:95], v[164:167], v[198:201], v[92:95]
	v_mfma_f32_16x16x32_bf16 v[88:91], v[172:175], v[198:201], v[88:91]
	v_mfma_f32_16x16x32_bf16 v[76:79], v[164:167], v[206:209], v[76:79]
	v_mfma_f32_16x16x32_bf16 v[72:75], v[172:175], v[206:209], v[72:75]
	s_barrier
	s_add_i32 s78, s31, s18
	v_lshl_add_u64 v[144:145], s[40:41], 0, v[130:131]
	s_mov_b32 m0, s78
	ds_read_b128 v[210:213], v155
	ds_read_b128 v[214:217], v155 offset:1024
	ds_read_b128 v[218:221], v155 offset:2048
	ds_read_b128 v[222:225], v155 offset:3072
	global_load_lds_dwordx4 v[144:145], off
	v_lshl_add_u64 v[226:227], s[40:41], 0, v[134:135]
	s_add_i32 m0, s78, 0x2000
	s_nop 0
	global_load_lds_dwordx4 v[226:227], off
	s_barrier
	s_waitcnt lgkmcnt(0)
	s_waitcnt lgkmcnt(0)
	v_mfma_f32_16x16x32_bf16 v[116:119], v[210:213], v[176:179], v[116:119]
	v_mfma_f32_16x16x32_bf16 v[112:115], v[218:221], v[176:179], v[112:115]
	v_mfma_f32_16x16x32_bf16 v[100:103], v[210:213], v[184:187], v[100:103]
	v_mfma_f32_16x16x32_bf16 v[96:99], v[218:221], v[184:187], v[96:99]
	v_mfma_f32_16x16x32_bf16 v[84:87], v[210:213], v[192:195], v[84:87]
	v_mfma_f32_16x16x32_bf16 v[80:83], v[218:221], v[192:195], v[80:83]
	v_mfma_f32_16x16x32_bf16 v[68:71], v[210:213], v[202:205], v[68:71]
	v_mfma_f32_16x16x32_bf16 v[64:67], v[218:221], v[202:205], v[64:67]
	v_mfma_f32_16x16x32_bf16 v[116:119], v[214:217], v[180:183], v[116:119]
	v_mfma_f32_16x16x32_bf16 v[112:115], v[222:225], v[180:183], v[112:115]
	v_mfma_f32_16x16x32_bf16 v[100:103], v[214:217], v[188:191], v[100:103]
	v_mfma_f32_16x16x32_bf16 v[96:99], v[222:225], v[188:191], v[96:99]
	v_mfma_f32_16x16x32_bf16 v[84:87], v[214:217], v[198:201], v[84:87]
	v_mfma_f32_16x16x32_bf16 v[80:83], v[222:225], v[198:201], v[80:83]
	v_mfma_f32_16x16x32_bf16 v[68:71], v[214:217], v[206:209], v[68:71]
	v_mfma_f32_16x16x32_bf16 v[64:67], v[222:225], v[206:209], v[64:67]
	s_mov_b32 m0, s19
	v_lshl_add_u64 v[228:229], s[16:17], 0, v[128:129]
	s_barrier
	ds_read_b128 v[176:179], v154 offset:16384
	ds_read_b128 v[180:183], v154 offset:17408
	ds_read_b128 v[184:187], v154 offset:18432
	ds_read_b128 v[188:191], v154 offset:19456
	ds_read_b128 v[192:195], v154 offset:20480
	ds_read_b128 v[198:201], v154 offset:21504
	ds_read_b128 v[202:205], v154 offset:22528
	ds_read_b128 v[206:209], v154 offset:23552
	global_load_lds_dwordx4 v[228:229], off
	v_lshl_add_u64 v[230:231], s[16:17], 0, v[132:133]
	s_mov_b32 m0, s20
	s_nop 0
	global_load_lds_dwordx4 v[230:231], off
	s_barrier
	s_waitcnt lgkmcnt(0)
	s_waitcnt lgkmcnt(0)
	v_mfma_f32_16x16x32_bf16 v[60:63], v[160:163], v[176:179], v[60:63]
	v_mfma_f32_16x16x32_bf16 v[56:59], v[168:171], v[176:179], v[56:59]
	v_mfma_f32_16x16x32_bf16 v[44:47], v[160:163], v[184:187], v[44:47]
	v_mfma_f32_16x16x32_bf16 v[40:43], v[168:171], v[184:187], v[40:43]
	v_mfma_f32_16x16x32_bf16 v[28:31], v[160:163], v[192:195], v[28:31]
	v_mfma_f32_16x16x32_bf16 v[24:27], v[168:171], v[192:195], v[24:27]
	v_mfma_f32_16x16x32_bf16 v[12:15], v[160:163], v[202:205], v[12:15]
	v_mfma_f32_16x16x32_bf16 v[8:11], v[168:171], v[202:205], v[8:11]
	v_mfma_f32_16x16x32_bf16 v[60:63], v[164:167], v[180:183], v[60:63]
	v_mfma_f32_16x16x32_bf16 v[56:59], v[172:175], v[180:183], v[56:59]
	v_mfma_f32_16x16x32_bf16 v[44:47], v[164:167], v[188:191], v[44:47]
	v_mfma_f32_16x16x32_bf16 v[40:43], v[172:175], v[188:191], v[40:43]
	v_mfma_f32_16x16x32_bf16 v[28:31], v[164:167], v[198:201], v[28:31]
	v_mfma_f32_16x16x32_bf16 v[24:27], v[172:175], v[198:201], v[24:27]
	v_mfma_f32_16x16x32_bf16 v[12:15], v[164:167], v[206:209], v[12:15]
	v_mfma_f32_16x16x32_bf16 v[8:11], v[172:175], v[206:209], v[8:11]
	s_barrier
; #define PG8_STAGE(bufoff, gbase, voff) do { _Pragma("unroll") for (int _i = 0; _i < 2; ++_i) \
;         __builtin_amdgcn_global_load_lds((const unsigned*)((const char*)(gbase) + (voff)[_i]), (LAS unsigned*)(lds + (bufoff) + ldsw + _i * 8192), 16, 0, 0); } while (0)
; #define PG8_LDA(dst, b, h) do { _Pragma("unroll") for (int m = 0; m < 4; ++m) _Pragma("unroll") for (int k = 0; k < 2; ++k) dst[m][k] = *(const LAS bf16x8*)(lds + PG8_SA(b, h) + aoff + m * 2048 + k * 1024); } while (0)
; #define PG8_LDB(dst, b, h) do { _Pragma("unroll") for (int n = 0; n < 2; ++n) _Pragma("unroll") for (int k = 0; k < 2; ++k) dst[n][k] = *(const LAS bf16x8*)(lds + PG8_SB(b, h) + boff + n * 2048 + k * 1024); } while (0)
; #define PG8_MMA(ai, bj, At, Bt) do { __builtin_amdgcn_s_setprio(1); _Pragma("unroll") for (int m = 0; m < 4; ++m) _Pragma("unroll") for (int n = 0; n < 2; ++n) _Pragma("unroll") for (int k = 0; k < 2; ++k) \
;         acc[ai][bj][m][n] = __builtin_amdgcn_mfma_f32_16x16x32_bf16(Bt[n][k], At[m][k], acc[ai][bj][m][n], 0, 0, 0); __builtin_amdgcn_s_setprio(0); } while (0)
; #define PG8_WAIT_V(n) asm volatile("s_waitcnt vmcnt(" #n ")" ::: "memory")
; #define PG8_WAIT_L(n) asm volatile("s_waitcnt lgkmcnt(" #n ")" ::: "memory")
; #define PG8_BAR __builtin_amdgcn_s_barrier()
; #define PG8_SCHED __builtin_amdgcn_sched_barrier(0)
; template <class Epi>
; DEVI void gemm_phase(LAS unsigned char* lds, const bf16_t* gA, const bf16_t* gBt, const int lda, const int ldb, const int K, const StaticOrder S_, const Epi E) {
;     ...
;             PG8_STAGE(PG8_SB(0, 1), b2 + hstepB, voffB);
;             PG8_WAIT_V(6); PG8_BAR; PG8_MMA(1, 1, At, B1); PG8_BAR;
;             PG8_LDB(B0, 1, 0); PG8_SCHED; PG8_LDA(At, 1, 0); PG8_STAGE(PG8_SA(0, 1), a2 + hstepA, voffA);
;             PG8_WAIT_L(8); PG8_BAR; PG8_WAIT_L(0); PG8_MMA(0, 0, At, B0); PG8_BAR; PG8_SCHED;
;             PG8_LDB(B1, 1, 1); PG8_STAGE(PG8_SB(1, 0), b3, voffB);
	s_add_u32 s40, s40, s2
	s_addc_u32 s41, s41, s3
	s_add_i32 s78, s34, s18
	v_lshl_add_u64 v[232:233], s[40:41], 0, v[130:131]
	s_mov_b32 m0, s78
	v_lshl_add_u64 v[234:235], s[40:41], 0, v[134:135]
	global_load_lds_dwordx4 v[232:233], off
	s_add_i32 m0, s78, 0x2000
	s_nop 0
	global_load_lds_dwordx4 v[234:235], off
	s_waitcnt vmcnt(6)
	s_barrier
	v_mfma_f32_16x16x32_bf16 v[52:55], v[210:213], v[176:179], v[52:55]
	v_mfma_f32_16x16x32_bf16 v[48:51], v[218:221], v[176:179], v[48:51]
	v_mfma_f32_16x16x32_bf16 v[36:39], v[210:213], v[184:187], v[36:39]
	v_mfma_f32_16x16x32_bf16 v[32:35], v[218:221], v[184:187], v[32:35]
	v_mfma_f32_16x16x32_bf16 v[20:23], v[210:213], v[192:195], v[20:23]
	v_mfma_f32_16x16x32_bf16 v[16:19], v[218:221], v[192:195], v[16:19]
	v_mfma_f32_16x16x32_bf16 v[4:7], v[210:213], v[202:205], v[4:7]
	v_mfma_f32_16x16x32_bf16 v[0:3], v[218:221], v[202:205], v[0:3]
	v_mfma_f32_16x16x32_bf16 v[52:55], v[214:217], v[180:183], v[52:55]
	v_mfma_f32_16x16x32_bf16 v[48:51], v[222:225], v[180:183], v[48:51]
	v_mfma_f32_16x16x32_bf16 v[36:39], v[214:217], v[188:191], v[36:39]
	v_mfma_f32_16x16x32_bf16 v[32:35], v[222:225], v[188:191], v[32:35]
	v_mfma_f32_16x16x32_bf16 v[20:23], v[214:217], v[198:201], v[20:23]
	v_mfma_f32_16x16x32_bf16 v[16:19], v[222:225], v[198:201], v[16:19]
	v_mfma_f32_16x16x32_bf16 v[4:7], v[214:217], v[206:209], v[4:7]
	v_mfma_f32_16x16x32_bf16 v[0:3], v[222:225], v[206:209], v[0:3]
	s_barrier
	ds_read_b128 v[160:163], v156
	ds_read_b128 v[164:167], v156 offset:1024
	ds_read_b128 v[168:171], v156 offset:2048
	ds_read_b128 v[172:175], v156 offset:3072
	s_add_u32 s16, s16, s0
	s_addc_u32 s17, s17, s1
	s_mov_b32 m0, s21
	v_lshl_add_u64 v[210:211], s[16:17], 0, v[128:129]
	ds_read_b128 v[176:179], v154 offset:32768
	ds_read_b128 v[180:183], v154 offset:33792
	ds_read_b128 v[184:187], v154 offset:34816
	ds_read_b128 v[188:191], v154 offset:35840
	ds_read_b128 v[192:195], v154 offset:36864
	ds_read_b128 v[198:201], v154 offset:37888
	ds_read_b128 v[202:205], v154 offset:38912
	ds_read_b128 v[206:209], v154 offset:39936
	global_load_lds_dwordx4 v[210:211], off
	v_lshl_add_u64 v[210:211], s[16:17], 0, v[132:133]
	s_mov_b32 m0, s22
	s_nop 0
	global_load_lds_dwordx4 v[210:211], off
	s_waitcnt lgkmcnt(8)
	s_barrier
	s_waitcnt lgkmcnt(0)
	s_waitcnt lgkmcnt(0)
	v_mfma_f32_16x16x32_bf16 v[124:127], v[160:163], v[176:179], v[124:127]
	v_mfma_f32_16x16x32_bf16 v[120:123], v[168:171], v[176:179], v[120:123]
	v_mfma_f32_16x16x32_bf16 v[108:111], v[160:163], v[184:187], v[108:111]
	v_mfma_f32_16x16x32_bf16 v[104:107], v[168:171], v[184:187], v[104:107]
	v_mfma_f32_16x16x32_bf16 v[92:95], v[160:163], v[192:195], v[92:95]
	v_mfma_f32_16x16x32_bf16 v[88:91], v[168:171], v[192:195], v[88:91]
	v_mfma_f32_16x16x32_bf16 v[76:79], v[160:163], v[202:205], v[76:79]
	v_mfma_f32_16x16x32_bf16 v[72:75], v[168:171], v[202:205], v[72:75]
	v_mfma_f32_16x16x32_bf16 v[124:127], v[164:167], v[180:183], v[124:127]
	v_mfma_f32_16x16x32_bf16 v[120:123], v[172:175], v[180:183], v[120:123]
	v_mfma_f32_16x16x32_bf16 v[108:111], v[164:167], v[188:191], v[108:111]
	v_mfma_f32_16x16x32_bf16 v[104:107], v[172:175], v[188:191], v[104:107]
	v_mfma_f32_16x16x32_bf16 v[92:95], v[164:167], v[198:201], v[92:95]
	v_mfma_f32_16x16x32_bf16 v[88:91], v[172:175], v[198:201], v[88:91]
	v_mfma_f32_16x16x32_bf16 v[76:79], v[164:167], v[206:209], v[76:79]
	v_mfma_f32_16x16x32_bf16 v[72:75], v[172:175], v[206:209], v[72:75]
	s_barrier
	s_add_i32 s16, s35, s18
	v_lshl_add_u64 v[144:145], v[144:145], 0, s[46:47]
	s_mov_b32 m0, s16
	ds_read_b128 v[210:213], v157
	ds_read_b128 v[214:217], v157 offset:1024
	ds_read_b128 v[218:221], v157 offset:2048
	ds_read_b128 v[222:225], v157 offset:3072
	global_load_lds_dwordx4 v[144:145], off
	v_lshl_add_u64 v[144:145], v[226:227], 0, s[46:47]
	s_add_i32 m0, s16, 0x2000
	s_nop 0
	global_load_lds_dwordx4 v[144:145], off
	s_barrier
; #define PG8_STAGE(bufoff, gbase, voff) do { _Pragma("unroll") for (int _i = 0; _i < 2; ++_i) \
;         __builtin_amdgcn_global_load_lds((const unsigned*)((const char*)(gbase) + (voff)[_i]), (LAS unsigned*)(lds + (bufoff) + ldsw + _i * 8192), 16, 0, 0); } while (0)
; #define PG8_LDA(dst, b, h) do { _Pragma("unroll") for (int m = 0; m < 4; ++m) _Pragma("unroll") for (int k = 0; k < 2; ++k) dst[m][k] = *(const LAS bf16x8*)(lds + PG8_SA(b, h) + aoff + m * 2048 + k * 1024); } while (0)
; #define PG8_MMA(ai, bj, At, Bt) do { __builtin_amdgcn_s_setprio(1); _Pragma("unroll") for (int m = 0; m < 4; ++m) _Pragma("unroll") for (int n = 0; n < 2; ++n) _Pragma("unroll") for (int k = 0; k < 2; ++k) \
;         acc[ai][bj][m][n] = __builtin_amdgcn_mfma_f32_16x16x32_bf16(Bt[n][k], At[m][k], acc[ai][bj][m][n], 0, 0, 0); __builtin_amdgcn_s_setprio(0); } while (0)
; #define PG8_WAIT_V(n) asm volatile("s_waitcnt vmcnt(" #n ")" ::: "memory")
; #define PG8_WAIT_L(n) asm volatile("s_waitcnt lgkmcnt(" #n ")" ::: "memory")
; #define PG8_BAR __builtin_amdgcn_s_barrier()
; #define PG8_SCHED __builtin_amdgcn_sched_barrier(0)
; template <class Epi>
; DEVI void gemm_phase(LAS unsigned char* lds, const bf16_t* gA, const bf16_t* gBt, const int lda, const int ldb, const int K, const StaticOrder S_, const Epi E) {
;     ...
;             PG8_BAR; PG8_WAIT_L(0); PG8_MMA(0, 1, At, B1); PG8_BAR;
;             PG8_LDA(At, 1, 1); PG8_STAGE(PG8_SA(1, 0), a3, voffA);
;             PG8_BAR; PG8_WAIT_L(0); PG8_MMA(1, 0, At, B0); PG8_BAR; PG8_SCHED;
;             PG8_STAGE(PG8_SB(1, 1), b3 + hstepB, voffB);
;             PG8_WAIT_V(6); PG8_BAR; PG8_MMA(1, 1, At, B1); PG8_BAR;
;         }
	s_waitcnt lgkmcnt(0)
	s_waitcnt lgkmcnt(0)
	v_mfma_f32_16x16x32_bf16 v[116:119], v[210:213], v[176:179], v[116:119]
	v_mfma_f32_16x16x32_bf16 v[112:115], v[218:221], v[176:179], v[112:115]
	v_mfma_f32_16x16x32_bf16 v[100:103], v[210:213], v[184:187], v[100:103]
	v_mfma_f32_16x16x32_bf16 v[96:99], v[218:221], v[184:187], v[96:99]
	v_mfma_f32_16x16x32_bf16 v[84:87], v[210:213], v[192:195], v[84:87]
	v_mfma_f32_16x16x32_bf16 v[80:83], v[218:221], v[192:195], v[80:83]
	v_mfma_f32_16x16x32_bf16 v[68:71], v[210:213], v[202:205], v[68:71]
	v_mfma_f32_16x16x32_bf16 v[64:67], v[218:221], v[202:205], v[64:67]
	v_mfma_f32_16x16x32_bf16 v[116:119], v[214:217], v[180:183], v[116:119]
	v_mfma_f32_16x16x32_bf16 v[112:115], v[222:225], v[180:183], v[112:115]
	v_mfma_f32_16x16x32_bf16 v[100:103], v[214:217], v[188:191], v[100:103]
	v_mfma_f32_16x16x32_bf16 v[96:99], v[222:225], v[188:191], v[96:99]
	v_mfma_f32_16x16x32_bf16 v[84:87], v[214:217], v[198:201], v[84:87]
	v_mfma_f32_16x16x32_bf16 v[80:83], v[222:225], v[198:201], v[80:83]
	v_mfma_f32_16x16x32_bf16 v[68:71], v[214:217], v[206:209], v[68:71]
	v_mfma_f32_16x16x32_bf16 v[64:67], v[222:225], v[206:209], v[64:67]
	s_mov_b32 m0, s23
	v_lshl_add_u64 v[144:145], v[228:229], 0, s[46:47]
	s_barrier
	ds_read_b128 v[176:179], v154 offset:49152
	ds_read_b128 v[180:183], v154 offset:50176
	ds_read_b128 v[184:187], v154 offset:51200
	ds_read_b128 v[188:191], v154 offset:52224
	ds_read_b128 v[192:195], v154 offset:53248
	ds_read_b128 v[198:201], v154 offset:54272
	ds_read_b128 v[202:205], v154 offset:55296
	ds_read_b128 v[206:209], v154 offset:56320
	global_load_lds_dwordx4 v[144:145], off
	v_lshl_add_u64 v[144:145], v[230:231], 0, s[46:47]
	s_mov_b32 m0, s24
	s_nop 0
	global_load_lds_dwordx4 v[144:145], off
	s_barrier
	s_waitcnt lgkmcnt(0)
	s_waitcnt lgkmcnt(0)
	v_mfma_f32_16x16x32_bf16 v[60:63], v[160:163], v[176:179], v[60:63]
	v_mfma_f32_16x16x32_bf16 v[56:59], v[168:171], v[176:179], v[56:59]
	v_mfma_f32_16x16x32_bf16 v[44:47], v[160:163], v[184:187], v[44:47]
	v_mfma_f32_16x16x32_bf16 v[40:43], v[168:171], v[184:187], v[40:43]
	v_mfma_f32_16x16x32_bf16 v[28:31], v[160:163], v[192:195], v[28:31]
	v_mfma_f32_16x16x32_bf16 v[24:27], v[168:171], v[192:195], v[24:27]
	v_mfma_f32_16x16x32_bf16 v[12:15], v[160:163], v[202:205], v[12:15]
	v_mfma_f32_16x16x32_bf16 v[8:11], v[168:171], v[202:205], v[8:11]
	v_mfma_f32_16x16x32_bf16 v[60:63], v[164:167], v[180:183], v[60:63]
	v_mfma_f32_16x16x32_bf16 v[56:59], v[172:175], v[180:183], v[56:59]
	v_mfma_f32_16x16x32_bf16 v[44:47], v[164:167], v[188:191], v[44:47]
	v_mfma_f32_16x16x32_bf16 v[40:43], v[172:175], v[188:191], v[40:43]
	v_mfma_f32_16x16x32_bf16 v[28:31], v[164:167], v[198:201], v[28:31]
	v_mfma_f32_16x16x32_bf16 v[24:27], v[172:175], v[198:201], v[24:27]
	v_mfma_f32_16x16x32_bf16 v[12:15], v[164:167], v[206:209], v[12:15]
	v_mfma_f32_16x16x32_bf16 v[8:11], v[172:175], v[206:209], v[8:11]
	s_barrier
	s_add_i32 s16, s50, s18
	v_lshl_add_u64 v[144:145], v[232:233], 0, s[46:47]
	s_mov_b32 m0, s16
	s_nop 0
	global_load_lds_dwordx4 v[144:145], off
	v_lshl_add_u64 v[144:145], v[234:235], 0, s[46:47]
	s_add_i32 m0, s16, 0x2000
	s_nop 0
	global_load_lds_dwordx4 v[144:145], off
	s_waitcnt vmcnt(6)
	s_barrier
	v_mfma_f32_16x16x32_bf16 v[52:55], v[210:213], v[176:179], v[52:55]
	v_mfma_f32_16x16x32_bf16 v[48:51], v[218:221], v[176:179], v[48:51]
	v_mfma_f32_16x16x32_bf16 v[36:39], v[210:213], v[184:187], v[36:39]
	v_mfma_f32_16x16x32_bf16 v[32:35], v[218:221], v[184:187], v[32:35]
	v_mfma_f32_16x16x32_bf16 v[20:23], v[210:213], v[192:195], v[20:23]
	v_mfma_f32_16x16x32_bf16 v[16:19], v[218:221], v[192:195], v[16:19]
	v_mfma_f32_16x16x32_bf16 v[4:7], v[210:213], v[202:205], v[4:7]
	v_mfma_f32_16x16x32_bf16 v[0:3], v[218:221], v[202:205], v[0:3]
	v_mfma_f32_16x16x32_bf16 v[52:55], v[214:217], v[180:183], v[52:55]
	v_mfma_f32_16x16x32_bf16 v[48:51], v[222:225], v[180:183], v[48:51]
	v_mfma_f32_16x16x32_bf16 v[36:39], v[214:217], v[188:191], v[36:39]
	v_mfma_f32_16x16x32_bf16 v[32:35], v[222:225], v[188:191], v[32:35]
	v_mfma_f32_16x16x32_bf16 v[20:23], v[214:217], v[198:201], v[20:23]
	v_mfma_f32_16x16x32_bf16 v[16:19], v[222:225], v[198:201], v[16:19]
	v_mfma_f32_16x16x32_bf16 v[4:7], v[214:217], v[206:209], v[4:7]
	v_mfma_f32_16x16x32_bf16 v[0:3], v[222:225], v[206:209], v[0:3]
	s_add_u32 s14, s14, 0x100
	s_addc_u32 s15, s15, 0
	s_add_u32 s68, s68, 0x100
	s_addc_u32 s69, s69, 0
	s_cmp_ge_i32 s77, s25
	s_mov_b32 s16, s77
	s_barrier
	s_cbranch_scc0 .LBB0_519
	v_readlane_b32 s78, v240, 54
	v_readlane_b32 s79, v240, 55

; #define PG8_STAGE(bufoff, gbase, voff) do { _Pragma("unroll") for (int _i = 0; _i < 2; ++_i) \
;         __builtin_amdgcn_global_load_lds((const unsigned*)((const char*)(gbase) + (voff)[_i]), (LAS unsigned*)(lds + (bufoff) + ldsw + _i * 8192), 16, 0, 0); } while (0)
; #define PG8_LDA(dst, b, h) do { _Pragma("unroll") for (int m = 0; m < 4; ++m) _Pragma("unroll") for (int k = 0; k < 2; ++k) dst[m][k] = *(const LAS bf16x8*)(lds + PG8_SA(b, h) + aoff + m * 2048 + k * 1024); } while (0)
; #define PG8_LDB(dst, b, h) do { _Pragma("unroll") for (int n = 0; n < 2; ++n) _Pragma("unroll") for (int k = 0; k < 2; ++k) dst[n][k] = *(const LAS bf16x8*)(lds + PG8_SB(b, h) + boff + n * 2048 + k * 1024); } while (0)
; #define PG8_MMA(ai, bj, At, Bt) do { __builtin_amdgcn_s_setprio(1); _Pragma("unroll") for (int m = 0; m < 4; ++m) _Pragma("unroll") for (int n = 0; n < 2; ++n) _Pragma("unroll") for (int k = 0; k < 2; ++k) \
;         acc[ai][bj][m][n] = __builtin_amdgcn_mfma_f32_16x16x32_bf16(Bt[n][k], At[m][k], acc[ai][bj][m][n], 0, 0, 0); __builtin_amdgcn_s_setprio(0); } while (0)
; #define PG8_WAIT_L(n) asm volatile("s_waitcnt lgkmcnt(" #n ")" ::: "memory")
; #define PG8_BAR __builtin_amdgcn_s_barrier()
; #define PG8_SCHED __builtin_amdgcn_sched_barrier(0)
; template <class Epi>
; DEVI void gemm_phase(LAS unsigned char* lds, const bf16_t* gA, const bf16_t* gBt, const int lda, const int ldb, const int K, const StaticOrder S_, const Epi E) {
;     ...
;             PG8_LDB(B0, 0, 0); PG8_SCHED; PG8_LDA(At, 0, 0); PG8_STAGE(PG8_SA(1, 1), a1 + hstepA, voffA);
;             PG8_WAIT_L(8); PG8_BAR; PG8_WAIT_L(0); PG8_MMA(0, 0, At, B0); PG8_BAR; PG8_SCHED;
;             PG8_LDB(B1, 0, 1); PG8_STAGE(PG8_SB(0, 0), b2, voffB);
;             PG8_BAR; PG8_WAIT_L(0); PG8_MMA(0, 1, At, B1); PG8_BAR;
;             PG8_LDA(At, 0, 1); PG8_STAGE(PG8_SA(0, 0), a2, voffA);
;             PG8_BAR; PG8_WAIT_L(0); PG8_MMA(1, 0, At, B0); PG8_BAR; PG8_SCHED;
.LBB0_744:
	ds_read_b128 v[160:163], v153
	ds_read_b128 v[164:167], v153 offset:1024
	ds_read_b128 v[168:171], v153 offset:2048
	ds_read_b128 v[172:175], v153 offset:3072
	s_add_i32 s77, s16, 2
	s_add_u32 s40, s14, 0x80
	s_addc_u32 s17, s15, 0
	s_cmp_eq_u32 s26, s16
	s_cselect_b32 s16, s48, s40
	s_cselect_b32 s17, s49, s17
	s_cselect_b32 s41, s61, s65
	s_cselect_b32 s40, s60, s64
	v_lshl_add_u64 v[144:145], s[14:15], 0, v[138:139]
	s_add_i32 m0, s19, 0xc000
	ds_read_b128 v[176:179], v154
	ds_read_b128 v[180:183], v154 offset:1024
	ds_read_b128 v[184:187], v154 offset:2048
	ds_read_b128 v[188:191], v154 offset:3072
	ds_read_b128 v[192:195], v154 offset:4096
	ds_read_b128 v[198:201], v154 offset:5120
	ds_read_b128 v[202:205], v154 offset:6144
	ds_read_b128 v[206:209], v154 offset:7168
	global_load_lds_dwordx4 v[144:145], off
	v_lshl_add_u64 v[144:145], s[14:15], 0, v[140:141]
	s_add_i32 m0, s19, 0xe000
	s_nop 0
	global_load_lds_dwordx4 v[144:145], off
	s_waitcnt lgkmcnt(8)
	s_barrier
	s_waitcnt lgkmcnt(0)
	s_waitcnt lgkmcnt(0)
	v_mfma_f32_16x16x32_bf16 v[124:127], v[160:163], v[176:179], v[124:127]
	v_mfma_f32_16x16x32_bf16 v[120:123], v[168:171], v[176:179], v[120:123]
	v_mfma_f32_16x16x32_bf16 v[108:111], v[160:163], v[184:187], v[108:111]
	v_mfma_f32_16x16x32_bf16 v[104:107], v[168:171], v[184:187], v[104:107]
	v_mfma_f32_16x16x32_bf16 v[92:95], v[160:163], v[192:195], v[92:95]
	v_mfma_f32_16x16x32_bf16 v[88:91], v[168:171], v[192:195], v[88:91]
	v_mfma_f32_16x16x32_bf16 v[76:79], v[160:163], v[202:205], v[76:79]
	v_mfma_f32_16x16x32_bf16 v[72:75], v[168:171], v[202:205], v[72:75]
	v_mfma_f32_16x16x32_bf16 v[124:127], v[164:167], v[180:183], v[124:127]
	v_mfma_f32_16x16x32_bf16 v[120:123], v[172:175], v[180:183], v[120:123]
	v_mfma_f32_16x16x32_bf16 v[108:111], v[164:167], v[188:191], v[108:111]
	v_mfma_f32_16x16x32_bf16 v[104:107], v[172:175], v[188:191], v[104:107]
	v_mfma_f32_16x16x32_bf16 v[92:95], v[164:167], v[198:201], v[92:95]
	v_mfma_f32_16x16x32_bf16 v[88:91], v[172:175], v[198:201], v[88:91]
	v_mfma_f32_16x16x32_bf16 v[76:79], v[164:167], v[206:209], v[76:79]
	v_mfma_f32_16x16x32_bf16 v[72:75], v[172:175], v[206:209], v[72:75]
	s_barrier
	s_add_i32 s78, s31, s18
	v_lshl_add_u64 v[144:145], s[40:41], 0, v[130:131]
	s_mov_b32 m0, s78
	ds_read_b128 v[210:213], v155
	ds_read_b128 v[214:217], v155 offset:1024
	ds_read_b128 v[218:221], v155 offset:2048
	ds_read_b128 v[222:225], v155 offset:3072
	global_load_lds_dwordx4 v[144:145], off
	v_lshl_add_u64 v[226:227], s[40:41], 0, v[134:135]
	s_add_i32 m0, s78, 0x2000
	s_nop 0
	global_load_lds_dwordx4 v[226:227], off
	s_barrier
	s_waitcnt lgkmcnt(0)
	s_waitcnt lgkmcnt(0)
	v_mfma_f32_16x16x32_bf16 v[116:119], v[210:213], v[176:179], v[116:119]
	v_mfma_f32_16x16x32_bf16 v[112:115], v[218:221], v[176:179], v[112:115]
	v_mfma_f32_16x16x32_bf16 v[100:103], v[210:213], v[184:187], v[100:103]
	v_mfma_f32_16x16x32_bf16 v[96:99], v[218:221], v[184:187], v[96:99]
	v_mfma_f32_16x16x32_bf16 v[84:87], v[210:213], v[192:195], v[84:87]
	v_mfma_f32_16x16x32_bf16 v[80:83], v[218:221], v[192:195], v[80:83]
	v_mfma_f32_16x16x32_bf16 v[68:71], v[210:213], v[202:205], v[68:71]
	v_mfma_f32_16x16x32_bf16 v[64:67], v[218:221], v[202:205], v[64:67]
	v_mfma_f32_16x16x32_bf16 v[116:119], v[214:217], v[180:183], v[116:119]
	v_mfma_f32_16x16x32_bf16 v[112:115], v[222:225], v[180:183], v[112:115]
	v_mfma_f32_16x16x32_bf16 v[100:103], v[214:217], v[188:191], v[100:103]
	v_mfma_f32_16x16x32_bf16 v[96:99], v[222:225], v[188:191], v[96:99]
	v_mfma_f32_16x16x32_bf16 v[84:87], v[214:217], v[198:201], v[84:87]
	v_mfma_f32_16x16x32_bf16 v[80:83], v[222:225], v[198:201], v[80:83]
	v_mfma_f32_16x16x32_bf16 v[68:71], v[214:217], v[206:209], v[68:71]
	v_mfma_f32_16x16x32_bf16 v[64:67], v[222:225], v[206:209], v[64:67]
	s_mov_b32 m0, s19
	v_lshl_add_u64 v[228:229], s[16:17], 0, v[128:129]
	s_barrier
	ds_read_b128 v[176:179], v154 offset:16384
	ds_read_b128 v[180:183], v154 offset:17408
	ds_read_b128 v[184:187], v154 offset:18432
	ds_read_b128 v[188:191], v154 offset:19456
	ds_read_b128 v[192:195], v154 offset:20480
	ds_read_b128 v[198:201], v154 offset:21504
	ds_read_b128 v[202:205], v154 offset:22528
	ds_read_b128 v[206:209], v154 offset:23552
	global_load_lds_dwordx4 v[228:229], off
	v_lshl_add_u64 v[230:231], s[16:17], 0, v[132:133]
	s_mov_b32 m0, s20
	s_nop 0
	global_load_lds_dwordx4 v[230:231], off
	s_barrier
	s_waitcnt lgkmcnt(0)
	s_waitcnt lgkmcnt(0)
	v_mfma_f32_16x16x32_bf16 v[60:63], v[160:163], v[176:179], v[60:63]
	v_mfma_f32_16x16x32_bf16 v[56:59], v[168:171], v[176:179], v[56:59]
	v_mfma_f32_16x16x32_bf16 v[44:47], v[160:163], v[184:187], v[44:47]
	v_mfma_f32_16x16x32_bf16 v[40:43], v[168:171], v[184:187], v[40:43]
	v_mfma_f32_16x16x32_bf16 v[28:31], v[160:163], v[192:195], v[28:31]
	v_mfma_f32_16x16x32_bf16 v[24:27], v[168:171], v[192:195], v[24:27]
	v_mfma_f32_16x16x32_bf16 v[12:15], v[160:163], v[202:205], v[12:15]
	v_mfma_f32_16x16x32_bf16 v[8:11], v[168:171], v[202:205], v[8:11]
	v_mfma_f32_16x16x32_bf16 v[60:63], v[164:167], v[180:183], v[60:63]
	v_mfma_f32_16x16x32_bf16 v[56:59], v[172:175], v[180:183], v[56:59]
	v_mfma_f32_16x16x32_bf16 v[44:47], v[164:167], v[188:191], v[44:47]
	v_mfma_f32_16x16x32_bf16 v[40:43], v[172:175], v[188:191], v[40:43]
	v_mfma_f32_16x16x32_bf16 v[28:31], v[164:167], v[198:201], v[28:31]
	v_mfma_f32_16x16x32_bf16 v[24:27], v[172:175], v[198:201], v[24:27]
	v_mfma_f32_16x16x32_bf16 v[12:15], v[164:167], v[206:209], v[12:15]
	v_mfma_f32_16x16x32_bf16 v[8:11], v[172:175], v[206:209], v[8:11]
	s_barrier
; #define PG8_STAGE(bufoff, gbase, voff) do { _Pragma("unroll") for (int _i = 0; _i < 2; ++_i) \
;         __builtin_amdgcn_global_load_lds((const unsigned*)((const char*)(gbase) + (voff)[_i]), (LAS unsigned*)(lds + (bufoff) + ldsw + _i * 8192), 16, 0, 0); } while (0)
; #define PG8_LDA(dst, b, h) do { _Pragma("unroll") for (int m = 0; m < 4; ++m) _Pragma("unroll") for (int k = 0; k < 2; ++k) dst[m][k] = *(const LAS bf16x8*)(lds + PG8_SA(b, h) + aoff + m * 2048 + k * 1024); } while (0)
; #define PG8_LDB(dst, b, h) do { _Pragma("unroll") for (int n = 0; n < 2; ++n) _Pragma("unroll") for (int k = 0; k < 2; ++k) dst[n][k] = *(const LAS bf16x8*)(lds + PG8_SB(b, h) + boff + n * 2048 + k * 1024); } while (0)
; #define PG8_MMA(ai, bj, At, Bt) do { __builtin_amdgcn_s_setprio(1); _Pragma("unroll") for (int m = 0; m < 4; ++m) _Pragma("unroll") for (int n = 0; n < 2; ++n) _Pragma("unroll") for (int k = 0; k < 2; ++k) \
;         acc[ai][bj][m][n] = __builtin_amdgcn_mfma_f32_16x16x32_bf16(Bt[n][k], At[m][k], acc[ai][bj][m][n], 0, 0, 0); __builtin_amdgcn_s_setprio(0); } while (0)
; #define PG8_WAIT_V(n) asm volatile("s_waitcnt vmcnt(" #n ")" ::: "memory")
; #define PG8_WAIT_L(n) asm volatile("s_waitcnt lgkmcnt(" #n ")" ::: "memory")
; #define PG8_BAR __builtin_amdgcn_s_barrier()
; #define PG8_SCHED __builtin_amdgcn_sched_barrier(0)
; template <class Epi>
; DEVI void gemm_phase(LAS unsigned char* lds, const bf16_t* gA, const bf16_t* gBt, const int lda, const int ldb, const int K, const StaticOrder S_, const Epi E) {
;     ...
;             PG8_STAGE(PG8_SB(0, 1), b2 + hstepB, voffB);
;             PG8_WAIT_V(6); PG8_BAR; PG8_MMA(1, 1, At, B1); PG8_BAR;
;             PG8_LDB(B0, 1, 0); PG8_SCHED; PG8_LDA(At, 1, 0); PG8_STAGE(PG8_SA(0, 1), a2 + hstepA, voffA);
;             PG8_WAIT_L(8); PG8_BAR; PG8_WAIT_L(0); PG8_MMA(0, 0, At, B0); PG8_BAR; PG8_SCHED;
;             PG8_LDB(B1, 1, 1); PG8_STAGE(PG8_SB(1, 0), b3, voffB);
	s_add_u32 s40, s40, s2
	s_addc_u32 s41, s41, s3
	s_add_i32 s78, s34, s18
	v_lshl_add_u64 v[232:233], s[40:41], 0, v[130:131]
	s_mov_b32 m0, s78
	v_lshl_add_u64 v[234:235], s[40:41], 0, v[134:135]
	global_load_lds_dwordx4 v[232:233], off
	s_add_i32 m0, s78, 0x2000
	s_nop 0
	global_load_lds_dwordx4 v[234:235], off
	s_waitcnt vmcnt(6)
	s_barrier
	v_mfma_f32_16x16x32_bf16 v[52:55], v[210:213], v[176:179], v[52:55]
	v_mfma_f32_16x16x32_bf16 v[48:51], v[218:221], v[176:179], v[48:51]
	v_mfma_f32_16x16x32_bf16 v[36:39], v[210:213], v[184:187], v[36:39]
	v_mfma_f32_16x16x32_bf16 v[32:35], v[218:221], v[184:187], v[32:35]
	v_mfma_f32_16x16x32_bf16 v[20:23], v[210:213], v[192:195], v[20:23]
	v_mfma_f32_16x16x32_bf16 v[16:19], v[218:221], v[192:195], v[16:19]
	v_mfma_f32_16x16x32_bf16 v[4:7], v[210:213], v[202:205], v[4:7]
	v_mfma_f32_16x16x32_bf16 v[0:3], v[218:221], v[202:205], v[0:3]
	v_mfma_f32_16x16x32_bf16 v[52:55], v[214:217], v[180:183], v[52:55]
	v_mfma_f32_16x16x32_bf16 v[48:51], v[222:225], v[180:183], v[48:51]
	v_mfma_f32_16x16x32_bf16 v[36:39], v[214:217], v[188:191], v[36:39]
	v_mfma_f32_16x16x32_bf16 v[32:35], v[222:225], v[188:191], v[32:35]
	v_mfma_f32_16x16x32_bf16 v[20:23], v[214:217], v[198:201], v[20:23]
	v_mfma_f32_16x16x32_bf16 v[16:19], v[222:225], v[198:201], v[16:19]
	v_mfma_f32_16x16x32_bf16 v[4:7], v[214:217], v[206:209], v[4:7]
	v_mfma_f32_16x16x32_bf16 v[0:3], v[222:225], v[206:209], v[0:3]
	s_barrier
	ds_read_b128 v[160:163], v156
	ds_read_b128 v[164:167], v156 offset:1024
	ds_read_b128 v[168:171], v156 offset:2048
	ds_read_b128 v[172:175], v156 offset:3072
	s_add_u32 s16, s16, s0
	s_addc_u32 s17, s17, s1
	s_mov_b32 m0, s21
	v_lshl_add_u64 v[210:211], s[16:17], 0, v[128:129]
	ds_read_b128 v[176:179], v154 offset:32768
	ds_read_b128 v[180:183], v154 offset:33792
	ds_read_b128 v[184:187], v154 offset:34816
	ds_read_b128 v[188:191], v154 offset:35840
	ds_read_b128 v[192:195], v154 offset:36864
	ds_read_b128 v[198:201], v154 offset:37888
	ds_read_b128 v[202:205], v154 offset:38912
	ds_read_b128 v[206:209], v154 offset:39936
	global_load_lds_dwordx4 v[210:211], off
	v_lshl_add_u64 v[210:211], s[16:17], 0, v[132:133]
	s_mov_b32 m0, s22
	s_nop 0
	global_load_lds_dwordx4 v[210:211], off
	s_waitcnt lgkmcnt(8)
	s_barrier
	s_waitcnt lgkmcnt(0)
	s_waitcnt lgkmcnt(0)
	v_mfma_f32_16x16x32_bf16 v[124:127], v[160:163], v[176:179], v[124:127]
	v_mfma_f32_16x16x32_bf16 v[120:123], v[168:171], v[176:179], v[120:123]
	v_mfma_f32_16x16x32_bf16 v[108:111], v[160:163], v[184:187], v[108:111]
	v_mfma_f32_16x16x32_bf16 v[104:107], v[168:171], v[184:187], v[104:107]
	v_mfma_f32_16x16x32_bf16 v[92:95], v[160:163], v[192:195], v[92:95]
	v_mfma_f32_16x16x32_bf16 v[88:91], v[168:171], v[192:195], v[88:91]
	v_mfma_f32_16x16x32_bf16 v[76:79], v[160:163], v[202:205], v[76:79]
	v_mfma_f32_16x16x32_bf16 v[72:75], v[168:171], v[202:205], v[72:75]
	v_mfma_f32_16x16x32_bf16 v[124:127], v[164:167], v[180:183], v[124:127]
	v_mfma_f32_16x16x32_bf16 v[120:123], v[172:175], v[180:183], v[120:123]
	v_mfma_f32_16x16x32_bf16 v[108:111], v[164:167], v[188:191], v[108:111]
	v_mfma_f32_16x16x32_bf16 v[104:107], v[172:175], v[188:191], v[104:107]
	v_mfma_f32_16x16x32_bf16 v[92:95], v[164:167], v[198:201], v[92:95]
	v_mfma_f32_16x16x32_bf16 v[88:91], v[172:175], v[198:201], v[88:91]
	v_mfma_f32_16x16x32_bf16 v[76:79], v[164:167], v[206:209], v[76:79]
	v_mfma_f32_16x16x32_bf16 v[72:75], v[172:175], v[206:209], v[72:75]
	s_barrier
	s_add_i32 s16, s35, s18
	v_lshl_add_u64 v[144:145], v[144:145], 0, s[46:47]
	s_mov_b32 m0, s16
	ds_read_b128 v[210:213], v157
	ds_read_b128 v[214:217], v157 offset:1024
	ds_read_b128 v[218:221], v157 offset:2048
	ds_read_b128 v[222:225], v157 offset:3072
	global_load_lds_dwordx4 v[144:145], off
	v_lshl_add_u64 v[144:145], v[226:227], 0, s[46:47]
	s_add_i32 m0, s16, 0x2000
	s_nop 0
	global_load_lds_dwordx4 v[144:145], off
	s_barrier
; #define PG8_STAGE(bufoff, gbase, voff) do { _Pragma("unroll") for (int _i = 0; _i < 2; ++_i) \
;         __builtin_amdgcn_global_load_lds((const unsigned*)((const char*)(gbase) + (voff)[_i]), (LAS unsigned*)(lds + (bufoff) + ldsw + _i * 8192), 16, 0, 0); } while (0)
; #define PG8_LDA(dst, b, h) do { _Pragma("unroll") for (int m = 0; m < 4; ++m) _Pragma("unroll") for (int k = 0; k < 2; ++k) dst[m][k] = *(const LAS bf16x8*)(lds + PG8_SA(b, h) + aoff + m * 2048 + k * 1024); } while (0)
; #define PG8_MMA(ai, bj, At, Bt) do { __builtin_amdgcn_s_setprio(1); _Pragma("unroll") for (int m = 0; m < 4; ++m) _Pragma("unroll") for (int n = 0; n < 2; ++n) _Pragma("unroll") for (int k = 0; k < 2; ++k) \
;         acc[ai][bj][m][n] = __builtin_amdgcn_mfma_f32_16x16x32_bf16(Bt[n][k], At[m][k], acc[ai][bj][m][n], 0, 0, 0); __builtin_amdgcn_s_setprio(0); } while (0)
; #define PG8_WAIT_V(n) asm volatile("s_waitcnt vmcnt(" #n ")" ::: "memory")
; #define PG8_WAIT_L(n) asm volatile("s_waitcnt lgkmcnt(" #n ")" ::: "memory")
; #define PG8_BAR __builtin_amdgcn_s_barrier()
; #define PG8_SCHED __builtin_amdgcn_sched_barrier(0)
; template <class Epi>
; DEVI void gemm_phase(LAS unsigned char* lds, const bf16_t* gA, const bf16_t* gBt, const int lda, const int ldb, const int K, const StaticOrder S_, const Epi E) {
;     ...
;             PG8_BAR; PG8_WAIT_L(0); PG8_MMA(0, 1, At, B1); PG8_BAR;
;             PG8_LDA(At, 1, 1); PG8_STAGE(PG8_SA(1, 0), a3, voffA);
;             PG8_BAR; PG8_WAIT_L(0); PG8_MMA(1, 0, At, B0); PG8_BAR; PG8_SCHED;
;             PG8_STAGE(PG8_SB(1, 1), b3 + hstepB, voffB);
;             PG8_WAIT_V(6); PG8_BAR; PG8_MMA(1, 1, At, B1); PG8_BAR;
;         }
	s_waitcnt lgkmcnt(0)
	s_waitcnt lgkmcnt(0)
	v_mfma_f32_16x16x32_bf16 v[116:119], v[210:213], v[176:179], v[116:119]
	v_mfma_f32_16x16x32_bf16 v[112:115], v[218:221], v[176:179], v[112:115]
	v_mfma_f32_16x16x32_bf16 v[100:103], v[210:213], v[184:187], v[100:103]
	v_mfma_f32_16x16x32_bf16 v[96:99], v[218:221], v[184:187], v[96:99]
	v_mfma_f32_16x16x32_bf16 v[84:87], v[210:213], v[192:195], v[84:87]
	v_mfma_f32_16x16x32_bf16 v[80:83], v[218:221], v[192:195], v[80:83]
	v_mfma_f32_16x16x32_bf16 v[68:71], v[210:213], v[202:205], v[68:71]
	v_mfma_f32_16x16x32_bf16 v[64:67], v[218:221], v[202:205], v[64:67]
	v_mfma_f32_16x16x32_bf16 v[116:119], v[214:217], v[180:183], v[116:119]
	v_mfma_f32_16x16x32_bf16 v[112:115], v[222:225], v[180:183], v[112:115]
	v_mfma_f32_16x16x32_bf16 v[100:103], v[214:217], v[188:191], v[100:103]
	v_mfma_f32_16x16x32_bf16 v[96:99], v[222:225], v[188:191], v[96:99]
	v_mfma_f32_16x16x32_bf16 v[84:87], v[214:217], v[198:201], v[84:87]
	v_mfma_f32_16x16x32_bf16 v[80:83], v[222:225], v[198:201], v[80:83]
	v_mfma_f32_16x16x32_bf16 v[68:71], v[214:217], v[206:209], v[68:71]
	v_mfma_f32_16x16x32_bf16 v[64:67], v[222:225], v[206:209], v[64:67]
	s_mov_b32 m0, s23
	v_lshl_add_u64 v[144:145], v[228:229], 0, s[46:47]
	s_barrier
	ds_read_b128 v[176:179], v154 offset:49152
	ds_read_b128 v[180:183], v154 offset:50176
	ds_read_b128 v[184:187], v154 offset:51200
	ds_read_b128 v[188:191], v154 offset:52224
	ds_read_b128 v[192:195], v154 offset:53248
	ds_read_b128 v[198:201], v154 offset:54272
	ds_read_b128 v[202:205], v154 offset:55296
	ds_read_b128 v[206:209], v154 offset:56320
	global_load_lds_dwordx4 v[144:145], off
	v_lshl_add_u64 v[144:145], v[230:231], 0, s[46:47]
	s_mov_b32 m0, s24
	s_nop 0
	global_load_lds_dwordx4 v[144:145], off
	s_barrier
	s_waitcnt lgkmcnt(0)
	s_waitcnt lgkmcnt(0)
	v_mfma_f32_16x16x32_bf16 v[60:63], v[160:163], v[176:179], v[60:63]
	v_mfma_f32_16x16x32_bf16 v[56:59], v[168:171], v[176:179], v[56:59]
	v_mfma_f32_16x16x32_bf16 v[44:47], v[160:163], v[184:187], v[44:47]
	v_mfma_f32_16x16x32_bf16 v[40:43], v[168:171], v[184:187], v[40:43]
	v_mfma_f32_16x16x32_bf16 v[28:31], v[160:163], v[192:195], v[28:31]
	v_mfma_f32_16x16x32_bf16 v[24:27], v[168:171], v[192:195], v[24:27]
	v_mfma_f32_16x16x32_bf16 v[12:15], v[160:163], v[202:205], v[12:15]
	v_mfma_f32_16x16x32_bf16 v[8:11], v[168:171], v[202:205], v[8:11]
	v_mfma_f32_16x16x32_bf16 v[60:63], v[164:167], v[180:183], v[60:63]
	v_mfma_f32_16x16x32_bf16 v[56:59], v[172:175], v[180:183], v[56:59]
	v_mfma_f32_16x16x32_bf16 v[44:47], v[164:167], v[188:191], v[44:47]
	v_mfma_f32_16x16x32_bf16 v[40:43], v[172:175], v[188:191], v[40:43]
	v_mfma_f32_16x16x32_bf16 v[28:31], v[164:167], v[198:201], v[28:31]
	v_mfma_f32_16x16x32_bf16 v[24:27], v[172:175], v[198:201], v[24:27]
	v_mfma_f32_16x16x32_bf16 v[12:15], v[164:167], v[206:209], v[12:15]
	v_mfma_f32_16x16x32_bf16 v[8:11], v[172:175], v[206:209], v[8:11]
	s_barrier
	s_add_i32 s16, s50, s18
	v_lshl_add_u64 v[144:145], v[232:233], 0, s[46:47]
	s_mov_b32 m0, s16
	s_nop 0
	global_load_lds_dwordx4 v[144:145], off
	v_lshl_add_u64 v[144:145], v[234:235], 0, s[46:47]
	s_add_i32 m0, s16, 0x2000
	s_nop 0
	global_load_lds_dwordx4 v[144:145], off
	s_waitcnt vmcnt(6)
	s_barrier
	v_mfma_f32_16x16x32_bf16 v[52:55], v[210:213], v[176:179], v[52:55]
	v_mfma_f32_16x16x32_bf16 v[48:51], v[218:221], v[176:179], v[48:51]
	v_mfma_f32_16x16x32_bf16 v[36:39], v[210:213], v[184:187], v[36:39]
	v_mfma_f32_16x16x32_bf16 v[32:35], v[218:221], v[184:187], v[32:35]
	v_mfma_f32_16x16x32_bf16 v[20:23], v[210:213], v[192:195], v[20:23]
	v_mfma_f32_16x16x32_bf16 v[16:19], v[218:221], v[192:195], v[16:19]
	v_mfma_f32_16x16x32_bf16 v[4:7], v[210:213], v[202:205], v[4:7]
	v_mfma_f32_16x16x32_bf16 v[0:3], v[218:221], v[202:205], v[0:3]
	v_mfma_f32_16x16x32_bf16 v[52:55], v[214:217], v[180:183], v[52:55]
	v_mfma_f32_16x16x32_bf16 v[48:51], v[222:225], v[180:183], v[48:51]
	v_mfma_f32_16x16x32_bf16 v[36:39], v[214:217], v[188:191], v[36:39]
	v_mfma_f32_16x16x32_bf16 v[32:35], v[222:225], v[188:191], v[32:35]
	v_mfma_f32_16x16x32_bf16 v[20:23], v[214:217], v[198:201], v[20:23]
	v_mfma_f32_16x16x32_bf16 v[16:19], v[222:225], v[198:201], v[16:19]
	v_mfma_f32_16x16x32_bf16 v[4:7], v[214:217], v[206:209], v[4:7]
	v_mfma_f32_16x16x32_bf16 v[0:3], v[222:225], v[206:209], v[0:3]
	s_add_u32 s14, s14, 0x100
	s_addc_u32 s15, s15, 0
	s_add_u32 s64, s64, 0x100
	s_addc_u32 s65, s65, 0
	s_cmp_ge_i32 s77, s25
	s_mov_b32 s16, s77
	s_barrier
	s_cbranch_scc0 .LBB0_744
	v_readlane_b32 s78, v240, 54
	v_readlane_b32 s79, v240, 55

; #define PG8_STAGE(bufoff, gbase, voff) do { _Pragma("unroll") for (int _i = 0; _i < 2; ++_i) \
;         __builtin_amdgcn_global_load_lds((const unsigned*)((const char*)(gbase) + (voff)[_i]), (LAS unsigned*)(lds + (bufoff) + ldsw + _i * 8192), 16, 0, 0); } while (0)
; #define PG8_LDA(dst, b, h) do { _Pragma("unroll") for (int m = 0; m < 4; ++m) _Pragma("unroll") for (int k = 0; k < 2; ++k) dst[m][k] = *(const LAS bf16x8*)(lds + PG8_SA(b, h) + aoff + m * 2048 + k * 1024); } while (0)
; #define PG8_LDB(dst, b, h) do { _Pragma("unroll") for (int n = 0; n < 2; ++n) _Pragma("unroll") for (int k = 0; k < 2; ++k) dst[n][k] = *(const LAS bf16x8*)(lds + PG8_SB(b, h) + boff + n * 2048 + k * 1024); } while (0)
; #define PG8_MMA(ai, bj, At, Bt) do { __builtin_amdgcn_s_setprio(1); _Pragma("unroll") for (int m = 0; m < 4; ++m) _Pragma("unroll") for (int n = 0; n < 2; ++n) _Pragma("unroll") for (int k = 0; k < 2; ++k) \
;         acc[ai][bj][m][n] = __builtin_amdgcn_mfma_f32_16x16x32_bf16(Bt[n][k], At[m][k], acc[ai][bj][m][n], 0, 0, 0); __builtin_amdgcn_s_setprio(0); } while (0)
; #define PG8_WAIT_L(n) asm volatile("s_waitcnt lgkmcnt(" #n ")" ::: "memory")
; #define PG8_BAR __builtin_amdgcn_s_barrier()
; #define PG8_SCHED __builtin_amdgcn_sched_barrier(0)
; template <class Epi>
; DEVI void gemm_phase(LAS unsigned char* lds, const bf16_t* gA, const bf16_t* gBt, const int lda, const int ldb, const int K, const StaticOrder S_, const Epi E) {
;     ...
;             PG8_LDB(B0, 0, 0); PG8_SCHED; PG8_LDA(At, 0, 0); PG8_STAGE(PG8_SA(1, 1), a1 + hstepA, voffA);
;             PG8_WAIT_L(8); PG8_BAR; PG8_WAIT_L(0); PG8_MMA(0, 0, At, B0); PG8_BAR; PG8_SCHED;
;             PG8_LDB(B1, 0, 1); PG8_STAGE(PG8_SB(0, 0), b2, voffB);
;             PG8_BAR; PG8_WAIT_L(0); PG8_MMA(0, 1, At, B1); PG8_BAR;
;             PG8_LDA(At, 0, 1); PG8_STAGE(PG8_SA(0, 0), a2, voffA);
;             PG8_BAR; PG8_WAIT_L(0); PG8_MMA(1, 0, At, B0); PG8_BAR; PG8_SCHED;
.LBB0_800:
	ds_read_b128 v[160:163], v153
	ds_read_b128 v[164:167], v153 offset:1024
	ds_read_b128 v[168:171], v153 offset:2048
	ds_read_b128 v[172:175], v153 offset:3072
	s_add_i32 s76, s16, 2
	s_add_u32 s40, s14, 0x80
	s_addc_u32 s17, s15, 0
	s_cmp_eq_u32 s26, s16
	s_cselect_b32 s16, s48, s40
	s_cselect_b32 s17, s49, s17
	s_cselect_b32 s41, s61, s65
	s_cselect_b32 s40, s60, s64
	v_lshl_add_u64 v[144:145], s[14:15], 0, v[138:139]
	s_add_i32 m0, s19, 0xc000
	ds_read_b128 v[176:179], v154
	ds_read_b128 v[180:183], v154 offset:1024
	ds_read_b128 v[184:187], v154 offset:2048
	ds_read_b128 v[188:191], v154 offset:3072
	ds_read_b128 v[192:195], v154 offset:4096
	ds_read_b128 v[198:201], v154 offset:5120
	ds_read_b128 v[202:205], v154 offset:6144
	ds_read_b128 v[206:209], v154 offset:7168
	global_load_lds_dwordx4 v[144:145], off
	v_lshl_add_u64 v[144:145], s[14:15], 0, v[140:141]
	s_add_i32 m0, s19, 0xe000
	s_nop 0
	global_load_lds_dwordx4 v[144:145], off
	s_waitcnt lgkmcnt(8)
	s_barrier
	s_waitcnt lgkmcnt(0)
	s_waitcnt lgkmcnt(0)
	v_mfma_f32_16x16x32_bf16 v[124:127], v[160:163], v[176:179], v[124:127]
	v_mfma_f32_16x16x32_bf16 v[120:123], v[168:171], v[176:179], v[120:123]
	v_mfma_f32_16x16x32_bf16 v[108:111], v[160:163], v[184:187], v[108:111]
	v_mfma_f32_16x16x32_bf16 v[104:107], v[168:171], v[184:187], v[104:107]
	v_mfma_f32_16x16x32_bf16 v[92:95], v[160:163], v[192:195], v[92:95]
	v_mfma_f32_16x16x32_bf16 v[88:91], v[168:171], v[192:195], v[88:91]
	v_mfma_f32_16x16x32_bf16 v[76:79], v[160:163], v[202:205], v[76:79]
	v_mfma_f32_16x16x32_bf16 v[72:75], v[168:171], v[202:205], v[72:75]
	v_mfma_f32_16x16x32_bf16 v[124:127], v[164:167], v[180:183], v[124:127]
	v_mfma_f32_16x16x32_bf16 v[120:123], v[172:175], v[180:183], v[120:123]
	v_mfma_f32_16x16x32_bf16 v[108:111], v[164:167], v[188:191], v[108:111]
	v_mfma_f32_16x16x32_bf16 v[104:107], v[172:175], v[188:191], v[104:107]
	v_mfma_f32_16x16x32_bf16 v[92:95], v[164:167], v[198:201], v[92:95]
	v_mfma_f32_16x16x32_bf16 v[88:91], v[172:175], v[198:201], v[88:91]
	v_mfma_f32_16x16x32_bf16 v[76:79], v[164:167], v[206:209], v[76:79]
	v_mfma_f32_16x16x32_bf16 v[72:75], v[172:175], v[206:209], v[72:75]
	s_barrier
	s_add_i32 s77, s31, s18
	v_lshl_add_u64 v[144:145], s[40:41], 0, v[130:131]
	s_mov_b32 m0, s77
	ds_read_b128 v[210:213], v155
	ds_read_b128 v[214:217], v155 offset:1024
	ds_read_b128 v[218:221], v155 offset:2048
	ds_read_b128 v[222:225], v155 offset:3072
	global_load_lds_dwordx4 v[144:145], off
	v_lshl_add_u64 v[226:227], s[40:41], 0, v[134:135]
	s_add_i32 m0, s77, 0x2000
	s_nop 0
	global_load_lds_dwordx4 v[226:227], off
	s_barrier
	s_waitcnt lgkmcnt(0)
	s_waitcnt lgkmcnt(0)
	v_mfma_f32_16x16x32_bf16 v[116:119], v[210:213], v[176:179], v[116:119]
	v_mfma_f32_16x16x32_bf16 v[112:115], v[218:221], v[176:179], v[112:115]
	v_mfma_f32_16x16x32_bf16 v[100:103], v[210:213], v[184:187], v[100:103]
	v_mfma_f32_16x16x32_bf16 v[96:99], v[218:221], v[184:187], v[96:99]
	v_mfma_f32_16x16x32_bf16 v[84:87], v[210:213], v[192:195], v[84:87]
	v_mfma_f32_16x16x32_bf16 v[80:83], v[218:221], v[192:195], v[80:83]
	v_mfma_f32_16x16x32_bf16 v[68:71], v[210:213], v[202:205], v[68:71]
	v_mfma_f32_16x16x32_bf16 v[64:67], v[218:221], v[202:205], v[64:67]
	v_mfma_f32_16x16x32_bf16 v[116:119], v[214:217], v[180:183], v[116:119]
	v_mfma_f32_16x16x32_bf16 v[112:115], v[222:225], v[180:183], v[112:115]
	v_mfma_f32_16x16x32_bf16 v[100:103], v[214:217], v[188:191], v[100:103]
	v_mfma_f32_16x16x32_bf16 v[96:99], v[222:225], v[188:191], v[96:99]
	v_mfma_f32_16x16x32_bf16 v[84:87], v[214:217], v[198:201], v[84:87]
	v_mfma_f32_16x16x32_bf16 v[80:83], v[222:225], v[198:201], v[80:83]
	v_mfma_f32_16x16x32_bf16 v[68:71], v[214:217], v[206:209], v[68:71]
	v_mfma_f32_16x16x32_bf16 v[64:67], v[222:225], v[206:209], v[64:67]
	s_mov_b32 m0, s19
	v_lshl_add_u64 v[228:229], s[16:17], 0, v[128:129]
	s_barrier
	ds_read_b128 v[176:179], v154 offset:16384
	ds_read_b128 v[180:183], v154 offset:17408
	ds_read_b128 v[184:187], v154 offset:18432
	ds_read_b128 v[188:191], v154 offset:19456
	ds_read_b128 v[192:195], v154 offset:20480
	ds_read_b128 v[198:201], v154 offset:21504
	ds_read_b128 v[202:205], v154 offset:22528
	ds_read_b128 v[206:209], v154 offset:23552
	global_load_lds_dwordx4 v[228:229], off
	v_lshl_add_u64 v[230:231], s[16:17], 0, v[132:133]
	s_mov_b32 m0, s20
	s_nop 0
	global_load_lds_dwordx4 v[230:231], off
	s_barrier
	s_waitcnt lgkmcnt(0)
	s_waitcnt lgkmcnt(0)
	v_mfma_f32_16x16x32_bf16 v[60:63], v[160:163], v[176:179], v[60:63]
	v_mfma_f32_16x16x32_bf16 v[56:59], v[168:171], v[176:179], v[56:59]
	v_mfma_f32_16x16x32_bf16 v[44:47], v[160:163], v[184:187], v[44:47]
	v_mfma_f32_16x16x32_bf16 v[40:43], v[168:171], v[184:187], v[40:43]
	v_mfma_f32_16x16x32_bf16 v[28:31], v[160:163], v[192:195], v[28:31]
	v_mfma_f32_16x16x32_bf16 v[24:27], v[168:171], v[192:195], v[24:27]
	v_mfma_f32_16x16x32_bf16 v[12:15], v[160:163], v[202:205], v[12:15]
	v_mfma_f32_16x16x32_bf16 v[8:11], v[168:171], v[202:205], v[8:11]
	v_mfma_f32_16x16x32_bf16 v[60:63], v[164:167], v[180:183], v[60:63]
	v_mfma_f32_16x16x32_bf16 v[56:59], v[172:175], v[180:183], v[56:59]
	v_mfma_f32_16x16x32_bf16 v[44:47], v[164:167], v[188:191], v[44:47]
	v_mfma_f32_16x16x32_bf16 v[40:43], v[172:175], v[188:191], v[40:43]
	v_mfma_f32_16x16x32_bf16 v[28:31], v[164:167], v[198:201], v[28:31]
	v_mfma_f32_16x16x32_bf16 v[24:27], v[172:175], v[198:201], v[24:27]
	v_mfma_f32_16x16x32_bf16 v[12:15], v[164:167], v[206:209], v[12:15]
	v_mfma_f32_16x16x32_bf16 v[8:11], v[172:175], v[206:209], v[8:11]
	s_barrier
; #define PG8_STAGE(bufoff, gbase, voff) do { _Pragma("unroll") for (int _i = 0; _i < 2; ++_i) \
;         __builtin_amdgcn_global_load_lds((const unsigned*)((const char*)(gbase) + (voff)[_i]), (LAS unsigned*)(lds + (bufoff) + ldsw + _i * 8192), 16, 0, 0); } while (0)
; #define PG8_LDA(dst, b, h) do { _Pragma("unroll") for (int m = 0; m < 4; ++m) _Pragma("unroll") for (int k = 0; k < 2; ++k) dst[m][k] = *(const LAS bf16x8*)(lds + PG8_SA(b, h) + aoff + m * 2048 + k * 1024); } while (0)
; #define PG8_LDB(dst, b, h) do { _Pragma("unroll") for (int n = 0; n < 2; ++n) _Pragma("unroll") for (int k = 0; k < 2; ++k) dst[n][k] = *(const LAS bf16x8*)(lds + PG8_SB(b, h) + boff + n * 2048 + k * 1024); } while (0)
; #define PG8_MMA(ai, bj, At, Bt) do { __builtin_amdgcn_s_setprio(1); _Pragma("unroll") for (int m = 0; m < 4; ++m) _Pragma("unroll") for (int n = 0; n < 2; ++n) _Pragma("unroll") for (int k = 0; k < 2; ++k) \
;         acc[ai][bj][m][n] = __builtin_amdgcn_mfma_f32_16x16x32_bf16(Bt[n][k], At[m][k], acc[ai][bj][m][n], 0, 0, 0); __builtin_amdgcn_s_setprio(0); } while (0)
; #define PG8_WAIT_V(n) asm volatile("s_waitcnt vmcnt(" #n ")" ::: "memory")
; #define PG8_WAIT_L(n) asm volatile("s_waitcnt lgkmcnt(" #n ")" ::: "memory")
; #define PG8_BAR __builtin_amdgcn_s_barrier()
; #define PG8_SCHED __builtin_amdgcn_sched_barrier(0)
; template <class Epi>
; DEVI void gemm_phase(LAS unsigned char* lds, const bf16_t* gA, const bf16_t* gBt, const int lda, const int ldb, const int K, const StaticOrder S_, const Epi E) {
;     ...
;             PG8_STAGE(PG8_SB(0, 1), b2 + hstepB, voffB);
;             PG8_WAIT_V(6); PG8_BAR; PG8_MMA(1, 1, At, B1); PG8_BAR;
;             PG8_LDB(B0, 1, 0); PG8_SCHED; PG8_LDA(At, 1, 0); PG8_STAGE(PG8_SA(0, 1), a2 + hstepA, voffA);
;             PG8_WAIT_L(8); PG8_BAR; PG8_WAIT_L(0); PG8_MMA(0, 0, At, B0); PG8_BAR; PG8_SCHED;
;             PG8_LDB(B1, 1, 1); PG8_STAGE(PG8_SB(1, 0), b3, voffB);
	s_add_u32 s40, s40, s2
	s_addc_u32 s41, s41, s3
	s_add_i32 s77, s34, s18
	v_lshl_add_u64 v[232:233], s[40:41], 0, v[130:131]
	s_mov_b32 m0, s77
	v_lshl_add_u64 v[234:235], s[40:41], 0, v[134:135]
	global_load_lds_dwordx4 v[232:233], off
	s_add_i32 m0, s77, 0x2000
	s_nop 0
	global_load_lds_dwordx4 v[234:235], off
	s_waitcnt vmcnt(6)
	s_barrier
	v_mfma_f32_16x16x32_bf16 v[52:55], v[210:213], v[176:179], v[52:55]
	v_mfma_f32_16x16x32_bf16 v[48:51], v[218:221], v[176:179], v[48:51]
	v_mfma_f32_16x16x32_bf16 v[36:39], v[210:213], v[184:187], v[36:39]
	v_mfma_f32_16x16x32_bf16 v[32:35], v[218:221], v[184:187], v[32:35]
	v_mfma_f32_16x16x32_bf16 v[20:23], v[210:213], v[192:195], v[20:23]
	v_mfma_f32_16x16x32_bf16 v[16:19], v[218:221], v[192:195], v[16:19]
	v_mfma_f32_16x16x32_bf16 v[4:7], v[210:213], v[202:205], v[4:7]
	v_mfma_f32_16x16x32_bf16 v[0:3], v[218:221], v[202:205], v[0:3]
	v_mfma_f32_16x16x32_bf16 v[52:55], v[214:217], v[180:183], v[52:55]
	v_mfma_f32_16x16x32_bf16 v[48:51], v[222:225], v[180:183], v[48:51]
	v_mfma_f32_16x16x32_bf16 v[36:39], v[214:217], v[188:191], v[36:39]
	v_mfma_f32_16x16x32_bf16 v[32:35], v[222:225], v[188:191], v[32:35]
	v_mfma_f32_16x16x32_bf16 v[20:23], v[214:217], v[198:201], v[20:23]
	v_mfma_f32_16x16x32_bf16 v[16:19], v[222:225], v[198:201], v[16:19]
	v_mfma_f32_16x16x32_bf16 v[4:7], v[214:217], v[206:209], v[4:7]
	v_mfma_f32_16x16x32_bf16 v[0:3], v[222:225], v[206:209], v[0:3]
	s_barrier
	ds_read_b128 v[160:163], v156
	ds_read_b128 v[164:167], v156 offset:1024
	ds_read_b128 v[168:171], v156 offset:2048
	ds_read_b128 v[172:175], v156 offset:3072
	s_add_u32 s16, s16, s0
	s_addc_u32 s17, s17, s1
	s_mov_b32 m0, s21
	v_lshl_add_u64 v[210:211], s[16:17], 0, v[128:129]
	ds_read_b128 v[176:179], v154 offset:32768
	ds_read_b128 v[180:183], v154 offset:33792
	ds_read_b128 v[184:187], v154 offset:34816
	ds_read_b128 v[188:191], v154 offset:35840
	ds_read_b128 v[192:195], v154 offset:36864
	ds_read_b128 v[198:201], v154 offset:37888
	ds_read_b128 v[202:205], v154 offset:38912
	ds_read_b128 v[206:209], v154 offset:39936
	global_load_lds_dwordx4 v[210:211], off
	v_lshl_add_u64 v[210:211], s[16:17], 0, v[132:133]
	s_mov_b32 m0, s22
	s_nop 0
	global_load_lds_dwordx4 v[210:211], off
	s_waitcnt lgkmcnt(8)
	s_barrier
	s_waitcnt lgkmcnt(0)
	s_waitcnt lgkmcnt(0)
	v_mfma_f32_16x16x32_bf16 v[124:127], v[160:163], v[176:179], v[124:127]
	v_mfma_f32_16x16x32_bf16 v[120:123], v[168:171], v[176:179], v[120:123]
	v_mfma_f32_16x16x32_bf16 v[108:111], v[160:163], v[184:187], v[108:111]
	v_mfma_f32_16x16x32_bf16 v[104:107], v[168:171], v[184:187], v[104:107]
	v_mfma_f32_16x16x32_bf16 v[92:95], v[160:163], v[192:195], v[92:95]
	v_mfma_f32_16x16x32_bf16 v[88:91], v[168:171], v[192:195], v[88:91]
	v_mfma_f32_16x16x32_bf16 v[76:79], v[160:163], v[202:205], v[76:79]
	v_mfma_f32_16x16x32_bf16 v[72:75], v[168:171], v[202:205], v[72:75]
	v_mfma_f32_16x16x32_bf16 v[124:127], v[164:167], v[180:183], v[124:127]
	v_mfma_f32_16x16x32_bf16 v[120:123], v[172:175], v[180:183], v[120:123]
	v_mfma_f32_16x16x32_bf16 v[108:111], v[164:167], v[188:191], v[108:111]
	v_mfma_f32_16x16x32_bf16 v[104:107], v[172:175], v[188:191], v[104:107]
	v_mfma_f32_16x16x32_bf16 v[92:95], v[164:167], v[198:201], v[92:95]
	v_mfma_f32_16x16x32_bf16 v[88:91], v[172:175], v[198:201], v[88:91]
	v_mfma_f32_16x16x32_bf16 v[76:79], v[164:167], v[206:209], v[76:79]
	v_mfma_f32_16x16x32_bf16 v[72:75], v[172:175], v[206:209], v[72:75]
	s_barrier
	s_add_i32 s16, s35, s18
	v_lshl_add_u64 v[144:145], v[144:145], 0, s[46:47]
	s_mov_b32 m0, s16
	ds_read_b128 v[210:213], v157
	ds_read_b128 v[214:217], v157 offset:1024
	ds_read_b128 v[218:221], v157 offset:2048
	ds_read_b128 v[222:225], v157 offset:3072
	global_load_lds_dwordx4 v[144:145], off
	v_lshl_add_u64 v[144:145], v[226:227], 0, s[46:47]
	s_add_i32 m0, s16, 0x2000
	s_nop 0
	global_load_lds_dwordx4 v[144:145], off
	s_barrier
; #define PG8_STAGE(bufoff, gbase, voff) do { _Pragma("unroll") for (int _i = 0; _i < 2; ++_i) \
;         __builtin_amdgcn_global_load_lds((const unsigned*)((const char*)(gbase) + (voff)[_i]), (LAS unsigned*)(lds + (bufoff) + ldsw + _i * 8192), 16, 0, 0); } while (0)
; #define PG8_LDA(dst, b, h) do { _Pragma("unroll") for (int m = 0; m < 4; ++m) _Pragma("unroll") for (int k = 0; k < 2; ++k) dst[m][k] = *(const LAS bf16x8*)(lds + PG8_SA(b, h) + aoff + m * 2048 + k * 1024); } while (0)
; #define PG8_MMA(ai, bj, At, Bt) do { __builtin_amdgcn_s_setprio(1); _Pragma("unroll") for (int m = 0; m < 4; ++m) _Pragma("unroll") for (int n = 0; n < 2; ++n) _Pragma("unroll") for (int k = 0; k < 2; ++k) \
;         acc[ai][bj][m][n] = __builtin_amdgcn_mfma_f32_16x16x32_bf16(Bt[n][k], At[m][k], acc[ai][bj][m][n], 0, 0, 0); __builtin_amdgcn_s_setprio(0); } while (0)
; #define PG8_WAIT_V(n) asm volatile("s_waitcnt vmcnt(" #n ")" ::: "memory")
; #define PG8_WAIT_L(n) asm volatile("s_waitcnt lgkmcnt(" #n ")" ::: "memory")
; #define PG8_BAR __builtin_amdgcn_s_barrier()
; #define PG8_SCHED __builtin_amdgcn_sched_barrier(0)
; template <class Epi>
; DEVI void gemm_phase(LAS unsigned char* lds, const bf16_t* gA, const bf16_t* gBt, const int lda, const int ldb, const int K, const StaticOrder S_, const Epi E) {
;     ...
;             PG8_BAR; PG8_WAIT_L(0); PG8_MMA(0, 1, At, B1); PG8_BAR;
;             PG8_LDA(At, 1, 1); PG8_STAGE(PG8_SA(1, 0), a3, voffA);
;             PG8_BAR; PG8_WAIT_L(0); PG8_MMA(1, 0, At, B0); PG8_BAR; PG8_SCHED;
;             PG8_STAGE(PG8_SB(1, 1), b3 + hstepB, voffB);
;             PG8_WAIT_V(6); PG8_BAR; PG8_MMA(1, 1, At, B1); PG8_BAR;
;         }
	s_waitcnt lgkmcnt(0)
	s_waitcnt lgkmcnt(0)
	v_mfma_f32_16x16x32_bf16 v[116:119], v[210:213], v[176:179], v[116:119]
	v_mfma_f32_16x16x32_bf16 v[112:115], v[218:221], v[176:179], v[112:115]
	v_mfma_f32_16x16x32_bf16 v[100:103], v[210:213], v[184:187], v[100:103]
	v_mfma_f32_16x16x32_bf16 v[96:99], v[218:221], v[184:187], v[96:99]
	v_mfma_f32_16x16x32_bf16 v[84:87], v[210:213], v[192:195], v[84:87]
	v_mfma_f32_16x16x32_bf16 v[80:83], v[218:221], v[192:195], v[80:83]
	v_mfma_f32_16x16x32_bf16 v[68:71], v[210:213], v[202:205], v[68:71]
	v_mfma_f32_16x16x32_bf16 v[64:67], v[218:221], v[202:205], v[64:67]
	v_mfma_f32_16x16x32_bf16 v[116:119], v[214:217], v[180:183], v[116:119]
	v_mfma_f32_16x16x32_bf16 v[112:115], v[222:225], v[180:183], v[112:115]
	v_mfma_f32_16x16x32_bf16 v[100:103], v[214:217], v[188:191], v[100:103]
	v_mfma_f32_16x16x32_bf16 v[96:99], v[222:225], v[188:191], v[96:99]
	v_mfma_f32_16x16x32_bf16 v[84:87], v[214:217], v[198:201], v[84:87]
	v_mfma_f32_16x16x32_bf16 v[80:83], v[222:225], v[198:201], v[80:83]
	v_mfma_f32_16x16x32_bf16 v[68:71], v[214:217], v[206:209], v[68:71]
	v_mfma_f32_16x16x32_bf16 v[64:67], v[222:225], v[206:209], v[64:67]
	s_mov_b32 m0, s23
	v_lshl_add_u64 v[144:145], v[228:229], 0, s[46:47]
	s_barrier
	ds_read_b128 v[176:179], v154 offset:49152
	ds_read_b128 v[180:183], v154 offset:50176
	ds_read_b128 v[184:187], v154 offset:51200
	ds_read_b128 v[188:191], v154 offset:52224
	ds_read_b128 v[192:195], v154 offset:53248
	ds_read_b128 v[198:201], v154 offset:54272
	ds_read_b128 v[202:205], v154 offset:55296
	ds_read_b128 v[206:209], v154 offset:56320
	global_load_lds_dwordx4 v[144:145], off
	v_lshl_add_u64 v[144:145], v[230:231], 0, s[46:47]
	s_mov_b32 m0, s24
	s_nop 0
	global_load_lds_dwordx4 v[144:145], off
	s_barrier
	s_waitcnt lgkmcnt(0)
	s_waitcnt lgkmcnt(0)
	v_mfma_f32_16x16x32_bf16 v[60:63], v[160:163], v[176:179], v[60:63]
	v_mfma_f32_16x16x32_bf16 v[56:59], v[168:171], v[176:179], v[56:59]
	v_mfma_f32_16x16x32_bf16 v[44:47], v[160:163], v[184:187], v[44:47]
	v_mfma_f32_16x16x32_bf16 v[40:43], v[168:171], v[184:187], v[40:43]
	v_mfma_f32_16x16x32_bf16 v[28:31], v[160:163], v[192:195], v[28:31]
	v_mfma_f32_16x16x32_bf16 v[24:27], v[168:171], v[192:195], v[24:27]
	v_mfma_f32_16x16x32_bf16 v[12:15], v[160:163], v[202:205], v[12:15]
	v_mfma_f32_16x16x32_bf16 v[8:11], v[168:171], v[202:205], v[8:11]
	v_mfma_f32_16x16x32_bf16 v[60:63], v[164:167], v[180:183], v[60:63]
	v_mfma_f32_16x16x32_bf16 v[56:59], v[172:175], v[180:183], v[56:59]
	v_mfma_f32_16x16x32_bf16 v[44:47], v[164:167], v[188:191], v[44:47]
	v_mfma_f32_16x16x32_bf16 v[40:43], v[172:175], v[188:191], v[40:43]
	v_mfma_f32_16x16x32_bf16 v[28:31], v[164:167], v[198:201], v[28:31]
	v_mfma_f32_16x16x32_bf16 v[24:27], v[172:175], v[198:201], v[24:27]
	v_mfma_f32_16x16x32_bf16 v[12:15], v[164:167], v[206:209], v[12:15]
	v_mfma_f32_16x16x32_bf16 v[8:11], v[172:175], v[206:209], v[8:11]
	s_barrier
	s_add_i32 s16, s50, s18
	v_lshl_add_u64 v[144:145], v[232:233], 0, s[46:47]
	s_mov_b32 m0, s16
	s_nop 0
	global_load_lds_dwordx4 v[144:145], off
	v_lshl_add_u64 v[144:145], v[234:235], 0, s[46:47]
	s_add_i32 m0, s16, 0x2000
	s_nop 0
	global_load_lds_dwordx4 v[144:145], off
	s_waitcnt vmcnt(6)
	s_barrier
	v_mfma_f32_16x16x32_bf16 v[52:55], v[210:213], v[176:179], v[52:55]
	v_mfma_f32_16x16x32_bf16 v[48:51], v[218:221], v[176:179], v[48:51]
	v_mfma_f32_16x16x32_bf16 v[36:39], v[210:213], v[184:187], v[36:39]
	v_mfma_f32_16x16x32_bf16 v[32:35], v[218:221], v[184:187], v[32:35]
	v_mfma_f32_16x16x32_bf16 v[20:23], v[210:213], v[192:195], v[20:23]
	v_mfma_f32_16x16x32_bf16 v[16:19], v[218:221], v[192:195], v[16:19]
	v_mfma_f32_16x16x32_bf16 v[4:7], v[210:213], v[202:205], v[4:7]
	v_mfma_f32_16x16x32_bf16 v[0:3], v[218:221], v[202:205], v[0:3]
	v_mfma_f32_16x16x32_bf16 v[52:55], v[214:217], v[180:183], v[52:55]
	v_mfma_f32_16x16x32_bf16 v[48:51], v[222:225], v[180:183], v[48:51]
	v_mfma_f32_16x16x32_bf16 v[36:39], v[214:217], v[188:191], v[36:39]
	v_mfma_f32_16x16x32_bf16 v[32:35], v[222:225], v[188:191], v[32:35]
	v_mfma_f32_16x16x32_bf16 v[20:23], v[214:217], v[198:201], v[20:23]
	v_mfma_f32_16x16x32_bf16 v[16:19], v[222:225], v[198:201], v[16:19]
	v_mfma_f32_16x16x32_bf16 v[4:7], v[214:217], v[206:209], v[4:7]
	v_mfma_f32_16x16x32_bf16 v[0:3], v[222:225], v[206:209], v[0:3]
	s_add_u32 s14, s14, 0x100
	s_addc_u32 s15, s15, 0
	s_add_u32 s64, s64, 0x100
	s_addc_u32 s65, s65, 0
	s_cmp_ge_i32 s76, s25
	s_mov_b32 s16, s76
	s_barrier
	s_cbranch_scc0 .LBB0_800

; #define PG8_STAGE(bufoff, gbase, voff) do { _Pragma("unroll") for (int _i = 0; _i < 2; ++_i) \
;         __builtin_amdgcn_global_load_lds((const unsigned*)((const char*)(gbase) + (voff)[_i]), (LAS unsigned*)(lds + (bufoff) + ldsw + _i * 8192), 16, 0, 0); } while (0)
; #define PG8_LDA(dst, b, h) do { _Pragma("unroll") for (int m = 0; m < 4; ++m) _Pragma("unroll") for (int k = 0; k < 2; ++k) dst[m][k] = *(const LAS bf16x8*)(lds + PG8_SA(b, h) + aoff + m * 2048 + k * 1024); } while (0)
; #define PG8_LDB(dst, b, h) do { _Pragma("unroll") for (int n = 0; n < 2; ++n) _Pragma("unroll") for (int k = 0; k < 2; ++k) dst[n][k] = *(const LAS bf16x8*)(lds + PG8_SB(b, h) + boff + n * 2048 + k * 1024); } while (0)
; #define PG8_MMA(ai, bj, At, Bt) do { __builtin_amdgcn_s_setprio(1); _Pragma("unroll") for (int m = 0; m < 4; ++m) _Pragma("unroll") for (int n = 0; n < 2; ++n) _Pragma("unroll") for (int k = 0; k < 2; ++k) \
;         acc[ai][bj][m][n] = __builtin_amdgcn_mfma_f32_16x16x32_bf16(Bt[n][k], At[m][k], acc[ai][bj][m][n], 0, 0, 0); __builtin_amdgcn_s_setprio(0); } while (0)
; #define PG8_WAIT_L(n) asm volatile("s_waitcnt lgkmcnt(" #n ")" ::: "memory")
; #define PG8_BAR __builtin_amdgcn_s_barrier()
; #define PG8_SCHED __builtin_amdgcn_sched_barrier(0)
; template <class Epi>
; DEVI void gemm_phase(LAS unsigned char* lds, const bf16_t* gA, const bf16_t* gBt, const int lda, const int ldb, const int K, const StaticOrder S_, const Epi E) {
;     ...
;             PG8_LDB(B0, 0, 0); PG8_SCHED; PG8_LDA(At, 0, 0); PG8_STAGE(PG8_SA(1, 1), a1 + hstepA, voffA);
;             PG8_WAIT_L(8); PG8_BAR; PG8_WAIT_L(0); PG8_MMA(0, 0, At, B0); PG8_BAR; PG8_SCHED;
;             PG8_LDB(B1, 0, 1); PG8_STAGE(PG8_SB(0, 0), b2, voffB);
;             PG8_BAR; PG8_WAIT_L(0); PG8_MMA(0, 1, At, B1); PG8_BAR;
;             PG8_LDA(At, 0, 1); PG8_STAGE(PG8_SA(0, 0), a2, voffA);
;             PG8_BAR; PG8_WAIT_L(0); PG8_MMA(1, 0, At, B0); PG8_BAR; PG8_SCHED;
.LBB0_1301:
	ds_read_b128 v[128:131], v201
	ds_read_b128 v[132:135], v201 offset:1024
	ds_read_b128 v[136:139], v201 offset:2048
	ds_read_b128 v[140:143], v201 offset:3072
	s_add_i32 s72, s16, 2
	s_add_u32 s40, s14, 0x80
	s_addc_u32 s17, s15, 0
	s_cmp_eq_u32 s19, s16
	s_cselect_b32 s16, s12, s40
	s_cselect_b32 s17, s13, s17
	s_cselect_b32 s41, s43, s71
	s_cselect_b32 s40, s42, s70
	v_lshl_add_u64 v[164:165], s[14:15], 0, v[174:175]
	s_add_i32 m0, s82, 0xc000
	ds_read_b128 v[144:147], v202
	ds_read_b128 v[148:151], v202 offset:1024
	ds_read_b128 v[152:155], v202 offset:2048
	ds_read_b128 v[156:159], v202 offset:3072
	ds_read_b128 v[160:163], v202 offset:4096
	ds_read_b128 v[180:183], v202 offset:5120
	ds_read_b128 v[184:187], v202 offset:6144
	ds_read_b128 v[188:191], v202 offset:7168
	global_load_lds_dwordx4 v[164:165], off
	v_lshl_add_u64 v[164:165], s[14:15], 0, v[176:177]
	s_add_i32 m0, s82, 0xe000
	s_nop 0
	global_load_lds_dwordx4 v[164:165], off
	s_waitcnt lgkmcnt(8)
	s_barrier
	s_waitcnt lgkmcnt(0)
	s_waitcnt lgkmcnt(0)
	v_mfma_f32_16x16x32_bf16 v[124:127], v[128:131], v[144:147], v[124:127]
	v_mfma_f32_16x16x32_bf16 v[120:123], v[136:139], v[144:147], v[120:123]
	v_mfma_f32_16x16x32_bf16 v[108:111], v[128:131], v[152:155], v[108:111]
	v_mfma_f32_16x16x32_bf16 v[104:107], v[136:139], v[152:155], v[104:107]
	v_mfma_f32_16x16x32_bf16 v[92:95], v[128:131], v[160:163], v[92:95]
	v_mfma_f32_16x16x32_bf16 v[88:91], v[136:139], v[160:163], v[88:91]
	v_mfma_f32_16x16x32_bf16 v[76:79], v[128:131], v[184:187], v[76:79]
	v_mfma_f32_16x16x32_bf16 v[72:75], v[136:139], v[184:187], v[72:75]
	v_mfma_f32_16x16x32_bf16 v[124:127], v[132:135], v[148:151], v[124:127]
	v_mfma_f32_16x16x32_bf16 v[120:123], v[140:143], v[148:151], v[120:123]
	v_mfma_f32_16x16x32_bf16 v[108:111], v[132:135], v[156:159], v[108:111]
	v_mfma_f32_16x16x32_bf16 v[104:107], v[140:143], v[156:159], v[104:107]
	v_mfma_f32_16x16x32_bf16 v[92:95], v[132:135], v[180:183], v[92:95]
	v_mfma_f32_16x16x32_bf16 v[88:91], v[140:143], v[180:183], v[88:91]
	v_mfma_f32_16x16x32_bf16 v[76:79], v[132:135], v[188:191], v[76:79]
	v_mfma_f32_16x16x32_bf16 v[72:75], v[140:143], v[188:191], v[72:75]
	s_barrier
	s_add_i32 s73, s29, s20
	v_lshl_add_u64 v[164:165], s[40:41], 0, v[168:169]
	s_mov_b32 m0, s73
	ds_read_b128 v[192:195], v203
	ds_read_b128 v[206:209], v203 offset:1024
	ds_read_b128 v[210:213], v203 offset:2048
	ds_read_b128 v[214:217], v203 offset:3072
	global_load_lds_dwordx4 v[164:165], off
	v_lshl_add_u64 v[218:219], s[40:41], 0, v[172:173]
	s_add_i32 m0, s73, 0x2000
	s_nop 0
	global_load_lds_dwordx4 v[218:219], off
	s_barrier
	s_waitcnt lgkmcnt(0)
	s_waitcnt lgkmcnt(0)
	v_mfma_f32_16x16x32_bf16 v[116:119], v[192:195], v[144:147], v[116:119]
	v_mfma_f32_16x16x32_bf16 v[112:115], v[210:213], v[144:147], v[112:115]
	v_mfma_f32_16x16x32_bf16 v[100:103], v[192:195], v[152:155], v[100:103]
	v_mfma_f32_16x16x32_bf16 v[96:99], v[210:213], v[152:155], v[96:99]
	v_mfma_f32_16x16x32_bf16 v[84:87], v[192:195], v[160:163], v[84:87]
	v_mfma_f32_16x16x32_bf16 v[80:83], v[210:213], v[160:163], v[80:83]
	v_mfma_f32_16x16x32_bf16 v[68:71], v[192:195], v[184:187], v[68:71]
	v_mfma_f32_16x16x32_bf16 v[64:67], v[210:213], v[184:187], v[64:67]
	v_mfma_f32_16x16x32_bf16 v[116:119], v[206:209], v[148:151], v[116:119]
	v_mfma_f32_16x16x32_bf16 v[112:115], v[214:217], v[148:151], v[112:115]
	v_mfma_f32_16x16x32_bf16 v[100:103], v[206:209], v[156:159], v[100:103]
	v_mfma_f32_16x16x32_bf16 v[96:99], v[214:217], v[156:159], v[96:99]
	v_mfma_f32_16x16x32_bf16 v[84:87], v[206:209], v[180:183], v[84:87]
	v_mfma_f32_16x16x32_bf16 v[80:83], v[214:217], v[180:183], v[80:83]
	v_mfma_f32_16x16x32_bf16 v[68:71], v[206:209], v[188:191], v[68:71]
	v_mfma_f32_16x16x32_bf16 v[64:67], v[214:217], v[188:191], v[64:67]
	s_mov_b32 m0, s82
	v_lshl_add_u64 v[220:221], s[16:17], 0, v[166:167]
	s_barrier
	ds_read_b128 v[144:147], v202 offset:16384
	ds_read_b128 v[148:151], v202 offset:17408
	ds_read_b128 v[152:155], v202 offset:18432
	ds_read_b128 v[156:159], v202 offset:19456
	ds_read_b128 v[160:163], v202 offset:20480
	ds_read_b128 v[180:183], v202 offset:21504
	ds_read_b128 v[184:187], v202 offset:22528
	ds_read_b128 v[188:191], v202 offset:23552
	global_load_lds_dwordx4 v[220:221], off
	v_lshl_add_u64 v[222:223], s[16:17], 0, v[170:171]
	s_mov_b32 m0, s22
	s_nop 0
	global_load_lds_dwordx4 v[222:223], off
	s_barrier
	s_waitcnt lgkmcnt(0)
	s_waitcnt lgkmcnt(0)
	v_mfma_f32_16x16x32_bf16 v[60:63], v[128:131], v[144:147], v[60:63]
	v_mfma_f32_16x16x32_bf16 v[56:59], v[136:139], v[144:147], v[56:59]
	v_mfma_f32_16x16x32_bf16 v[44:47], v[128:131], v[152:155], v[44:47]
	v_mfma_f32_16x16x32_bf16 v[40:43], v[136:139], v[152:155], v[40:43]
	v_mfma_f32_16x16x32_bf16 v[28:31], v[128:131], v[160:163], v[28:31]
	v_mfma_f32_16x16x32_bf16 v[24:27], v[136:139], v[160:163], v[24:27]
	v_mfma_f32_16x16x32_bf16 v[12:15], v[128:131], v[184:187], v[12:15]
	v_mfma_f32_16x16x32_bf16 v[8:11], v[136:139], v[184:187], v[8:11]
	v_mfma_f32_16x16x32_bf16 v[60:63], v[132:135], v[148:151], v[60:63]
	v_mfma_f32_16x16x32_bf16 v[56:59], v[140:143], v[148:151], v[56:59]
	v_mfma_f32_16x16x32_bf16 v[44:47], v[132:135], v[156:159], v[44:47]
	v_mfma_f32_16x16x32_bf16 v[40:43], v[140:143], v[156:159], v[40:43]
	v_mfma_f32_16x16x32_bf16 v[28:31], v[132:135], v[180:183], v[28:31]
	v_mfma_f32_16x16x32_bf16 v[24:27], v[140:143], v[180:183], v[24:27]
	v_mfma_f32_16x16x32_bf16 v[12:15], v[132:135], v[188:191], v[12:15]
	v_mfma_f32_16x16x32_bf16 v[8:11], v[140:143], v[188:191], v[8:11]
	s_barrier
; #define PG8_STAGE(bufoff, gbase, voff) do { _Pragma("unroll") for (int _i = 0; _i < 2; ++_i) \
;         __builtin_amdgcn_global_load_lds((const unsigned*)((const char*)(gbase) + (voff)[_i]), (LAS unsigned*)(lds + (bufoff) + ldsw + _i * 8192), 16, 0, 0); } while (0)
; #define PG8_LDA(dst, b, h) do { _Pragma("unroll") for (int m = 0; m < 4; ++m) _Pragma("unroll") for (int k = 0; k < 2; ++k) dst[m][k] = *(const LAS bf16x8*)(lds + PG8_SA(b, h) + aoff + m * 2048 + k * 1024); } while (0)
; #define PG8_LDB(dst, b, h) do { _Pragma("unroll") for (int n = 0; n < 2; ++n) _Pragma("unroll") for (int k = 0; k < 2; ++k) dst[n][k] = *(const LAS bf16x8*)(lds + PG8_SB(b, h) + boff + n * 2048 + k * 1024); } while (0)
; #define PG8_MMA(ai, bj, At, Bt) do { __builtin_amdgcn_s_setprio(1); _Pragma("unroll") for (int m = 0; m < 4; ++m) _Pragma("unroll") for (int n = 0; n < 2; ++n) _Pragma("unroll") for (int k = 0; k < 2; ++k) \
;         acc[ai][bj][m][n] = __builtin_amdgcn_mfma_f32_16x16x32_bf16(Bt[n][k], At[m][k], acc[ai][bj][m][n], 0, 0, 0); __builtin_amdgcn_s_setprio(0); } while (0)
; #define PG8_WAIT_V(n) asm volatile("s_waitcnt vmcnt(" #n ")" ::: "memory")
; #define PG8_WAIT_L(n) asm volatile("s_waitcnt lgkmcnt(" #n ")" ::: "memory")
; #define PG8_BAR __builtin_amdgcn_s_barrier()
; #define PG8_SCHED __builtin_amdgcn_sched_barrier(0)
; template <class Epi>
; DEVI void gemm_phase(LAS unsigned char* lds, const bf16_t* gA, const bf16_t* gBt, const int lda, const int ldb, const int K, const StaticOrder S_, const Epi E) {
;     ...
;             PG8_STAGE(PG8_SB(0, 1), b2 + hstepB, voffB);
;             PG8_WAIT_V(6); PG8_BAR; PG8_MMA(1, 1, At, B1); PG8_BAR;
;             PG8_LDB(B0, 1, 0); PG8_SCHED; PG8_LDA(At, 1, 0); PG8_STAGE(PG8_SA(0, 1), a2 + hstepA, voffA);
;             PG8_WAIT_L(8); PG8_BAR; PG8_WAIT_L(0); PG8_MMA(0, 0, At, B0); PG8_BAR; PG8_SCHED;
;             PG8_LDB(B1, 1, 1); PG8_STAGE(PG8_SB(1, 0), b3, voffB);
	s_add_u32 s40, s40, s2
	s_addc_u32 s41, s41, s3
	s_add_i32 s73, s50, s20
	v_lshl_add_u64 v[224:225], s[40:41], 0, v[168:169]
	s_mov_b32 m0, s73
	v_lshl_add_u64 v[226:227], s[40:41], 0, v[172:173]
	global_load_lds_dwordx4 v[224:225], off
	s_add_i32 m0, s73, 0x2000
	s_nop 0
	global_load_lds_dwordx4 v[226:227], off
	s_waitcnt vmcnt(6)
	s_barrier
	v_mfma_f32_16x16x32_bf16 v[52:55], v[192:195], v[144:147], v[52:55]
	v_mfma_f32_16x16x32_bf16 v[48:51], v[210:213], v[144:147], v[48:51]
	v_mfma_f32_16x16x32_bf16 v[36:39], v[192:195], v[152:155], v[36:39]
	v_mfma_f32_16x16x32_bf16 v[32:35], v[210:213], v[152:155], v[32:35]
	v_mfma_f32_16x16x32_bf16 v[20:23], v[192:195], v[160:163], v[20:23]
	v_mfma_f32_16x16x32_bf16 v[16:19], v[210:213], v[160:163], v[16:19]
	v_mfma_f32_16x16x32_bf16 v[4:7], v[192:195], v[184:187], v[4:7]
	v_mfma_f32_16x16x32_bf16 v[0:3], v[210:213], v[184:187], v[0:3]
	v_mfma_f32_16x16x32_bf16 v[52:55], v[206:209], v[148:151], v[52:55]
	v_mfma_f32_16x16x32_bf16 v[48:51], v[214:217], v[148:151], v[48:51]
	v_mfma_f32_16x16x32_bf16 v[36:39], v[206:209], v[156:159], v[36:39]
	v_mfma_f32_16x16x32_bf16 v[32:35], v[214:217], v[156:159], v[32:35]
	v_mfma_f32_16x16x32_bf16 v[20:23], v[206:209], v[180:183], v[20:23]
	v_mfma_f32_16x16x32_bf16 v[16:19], v[214:217], v[180:183], v[16:19]
	v_mfma_f32_16x16x32_bf16 v[4:7], v[206:209], v[188:191], v[4:7]
	v_mfma_f32_16x16x32_bf16 v[0:3], v[214:217], v[188:191], v[0:3]
	s_add_i32 s40, 0, 0x18000
	v_add_u32_e32 v140, s40, v199
	s_barrier
	ds_read_b128 v[128:131], v140
	ds_read_b128 v[132:135], v140 offset:1024
	ds_read_b128 v[136:139], v140 offset:2048
	ds_read_b128 v[140:143], v140 offset:3072
	s_add_u32 s16, s16, s0
	s_addc_u32 s17, s17, s1
	s_mov_b32 m0, s23
	v_lshl_add_u64 v[192:193], s[16:17], 0, v[166:167]
	ds_read_b128 v[144:147], v202 offset:32768
	ds_read_b128 v[148:151], v202 offset:33792
	ds_read_b128 v[152:155], v202 offset:34816
	ds_read_b128 v[156:159], v202 offset:35840
	ds_read_b128 v[160:163], v202 offset:36864
	ds_read_b128 v[180:183], v202 offset:37888
	ds_read_b128 v[184:187], v202 offset:38912
	ds_read_b128 v[188:191], v202 offset:39936
	global_load_lds_dwordx4 v[192:193], off
	v_lshl_add_u64 v[192:193], s[16:17], 0, v[170:171]
	s_mov_b32 m0, s24
	s_nop 0
	global_load_lds_dwordx4 v[192:193], off
	s_waitcnt lgkmcnt(8)
	s_barrier
	s_waitcnt lgkmcnt(0)
	s_waitcnt lgkmcnt(0)
	v_mfma_f32_16x16x32_bf16 v[124:127], v[128:131], v[144:147], v[124:127]
	v_mfma_f32_16x16x32_bf16 v[120:123], v[136:139], v[144:147], v[120:123]
	v_mfma_f32_16x16x32_bf16 v[108:111], v[128:131], v[152:155], v[108:111]
	v_mfma_f32_16x16x32_bf16 v[104:107], v[136:139], v[152:155], v[104:107]
	v_mfma_f32_16x16x32_bf16 v[92:95], v[128:131], v[160:163], v[92:95]
	v_mfma_f32_16x16x32_bf16 v[88:91], v[136:139], v[160:163], v[88:91]
	v_mfma_f32_16x16x32_bf16 v[76:79], v[128:131], v[184:187], v[76:79]
	v_mfma_f32_16x16x32_bf16 v[72:75], v[136:139], v[184:187], v[72:75]
	v_mfma_f32_16x16x32_bf16 v[124:127], v[132:135], v[148:151], v[124:127]
	v_mfma_f32_16x16x32_bf16 v[120:123], v[140:143], v[148:151], v[120:123]
	v_mfma_f32_16x16x32_bf16 v[108:111], v[132:135], v[156:159], v[108:111]
	v_mfma_f32_16x16x32_bf16 v[104:107], v[140:143], v[156:159], v[104:107]
	v_mfma_f32_16x16x32_bf16 v[92:95], v[132:135], v[180:183], v[92:95]
	v_mfma_f32_16x16x32_bf16 v[88:91], v[140:143], v[180:183], v[88:91]
	v_mfma_f32_16x16x32_bf16 v[76:79], v[132:135], v[188:191], v[76:79]
	v_mfma_f32_16x16x32_bf16 v[72:75], v[140:143], v[188:191], v[72:75]
	s_barrier
	s_add_i32 s16, 0, 0x1c000
	s_add_i32 s17, s40, s20
	v_add_u32_e32 v205, s16, v199
	v_lshl_add_u64 v[164:165], v[164:165], 0, s[8:9]
	s_mov_b32 m0, s17
	ds_read_b128 v[192:195], v205
	ds_read_b128 v[206:209], v205 offset:1024
	ds_read_b128 v[210:213], v205 offset:2048
	ds_read_b128 v[214:217], v205 offset:3072
	global_load_lds_dwordx4 v[164:165], off
	v_lshl_add_u64 v[164:165], v[218:219], 0, s[8:9]
	s_add_i32 m0, s17, 0x2000
	s_nop 0
	global_load_lds_dwordx4 v[164:165], off
	s_barrier
; #define PG8_STAGE(bufoff, gbase, voff) do { _Pragma("unroll") for (int _i = 0; _i < 2; ++_i) \
;         __builtin_amdgcn_global_load_lds((const unsigned*)((const char*)(gbase) + (voff)[_i]), (LAS unsigned*)(lds + (bufoff) + ldsw + _i * 8192), 16, 0, 0); } while (0)
; #define PG8_LDA(dst, b, h) do { _Pragma("unroll") for (int m = 0; m < 4; ++m) _Pragma("unroll") for (int k = 0; k < 2; ++k) dst[m][k] = *(const LAS bf16x8*)(lds + PG8_SA(b, h) + aoff + m * 2048 + k * 1024); } while (0)
; #define PG8_MMA(ai, bj, At, Bt) do { __builtin_amdgcn_s_setprio(1); _Pragma("unroll") for (int m = 0; m < 4; ++m) _Pragma("unroll") for (int n = 0; n < 2; ++n) _Pragma("unroll") for (int k = 0; k < 2; ++k) \
;         acc[ai][bj][m][n] = __builtin_amdgcn_mfma_f32_16x16x32_bf16(Bt[n][k], At[m][k], acc[ai][bj][m][n], 0, 0, 0); __builtin_amdgcn_s_setprio(0); } while (0)
; #define PG8_WAIT_V(n) asm volatile("s_waitcnt vmcnt(" #n ")" ::: "memory")
; #define PG8_WAIT_L(n) asm volatile("s_waitcnt lgkmcnt(" #n ")" ::: "memory")
; #define PG8_BAR __builtin_amdgcn_s_barrier()
; #define PG8_SCHED __builtin_amdgcn_sched_barrier(0)
; template <class Epi>
; DEVI void gemm_phase(LAS unsigned char* lds, const bf16_t* gA, const bf16_t* gBt, const int lda, const int ldb, const int K, const StaticOrder S_, const Epi E) {
;     ...
;             PG8_BAR; PG8_WAIT_L(0); PG8_MMA(0, 1, At, B1); PG8_BAR;
;             PG8_LDA(At, 1, 1); PG8_STAGE(PG8_SA(1, 0), a3, voffA);
;             PG8_BAR; PG8_WAIT_L(0); PG8_MMA(1, 0, At, B0); PG8_BAR; PG8_SCHED;
;             PG8_STAGE(PG8_SB(1, 1), b3 + hstepB, voffB);
;             PG8_WAIT_V(6); PG8_BAR; PG8_MMA(1, 1, At, B1); PG8_BAR;
;         }
	s_waitcnt lgkmcnt(0)
	s_waitcnt lgkmcnt(0)
	v_mfma_f32_16x16x32_bf16 v[116:119], v[192:195], v[144:147], v[116:119]
	v_mfma_f32_16x16x32_bf16 v[112:115], v[210:213], v[144:147], v[112:115]
	v_mfma_f32_16x16x32_bf16 v[100:103], v[192:195], v[152:155], v[100:103]
	v_mfma_f32_16x16x32_bf16 v[96:99], v[210:213], v[152:155], v[96:99]
	v_mfma_f32_16x16x32_bf16 v[84:87], v[192:195], v[160:163], v[84:87]
	v_mfma_f32_16x16x32_bf16 v[80:83], v[210:213], v[160:163], v[80:83]
	v_mfma_f32_16x16x32_bf16 v[68:71], v[192:195], v[184:187], v[68:71]
	v_mfma_f32_16x16x32_bf16 v[64:67], v[210:213], v[184:187], v[64:67]
	v_mfma_f32_16x16x32_bf16 v[116:119], v[206:209], v[148:151], v[116:119]
	v_mfma_f32_16x16x32_bf16 v[112:115], v[214:217], v[148:151], v[112:115]
	v_mfma_f32_16x16x32_bf16 v[100:103], v[206:209], v[156:159], v[100:103]
	v_mfma_f32_16x16x32_bf16 v[96:99], v[214:217], v[156:159], v[96:99]
	v_mfma_f32_16x16x32_bf16 v[84:87], v[206:209], v[180:183], v[84:87]
	v_mfma_f32_16x16x32_bf16 v[80:83], v[214:217], v[180:183], v[80:83]
	v_mfma_f32_16x16x32_bf16 v[68:71], v[206:209], v[188:191], v[68:71]
	v_mfma_f32_16x16x32_bf16 v[64:67], v[214:217], v[188:191], v[64:67]
	s_mov_b32 m0, s26
	v_lshl_add_u64 v[164:165], v[220:221], 0, s[8:9]
	s_barrier
	ds_read_b128 v[144:147], v202 offset:49152
	ds_read_b128 v[148:151], v202 offset:50176
	ds_read_b128 v[152:155], v202 offset:51200
	ds_read_b128 v[156:159], v202 offset:52224
	ds_read_b128 v[160:163], v202 offset:53248
	ds_read_b128 v[180:183], v202 offset:54272
	ds_read_b128 v[184:187], v202 offset:55296
	ds_read_b128 v[188:191], v202 offset:56320
	global_load_lds_dwordx4 v[164:165], off
	v_lshl_add_u64 v[164:165], v[222:223], 0, s[8:9]
	s_mov_b32 m0, s27
	s_nop 0
	global_load_lds_dwordx4 v[164:165], off
	s_barrier
	s_waitcnt lgkmcnt(0)
	s_waitcnt lgkmcnt(0)
	v_mfma_f32_16x16x32_bf16 v[60:63], v[128:131], v[144:147], v[60:63]
	v_mfma_f32_16x16x32_bf16 v[56:59], v[136:139], v[144:147], v[56:59]
	v_mfma_f32_16x16x32_bf16 v[44:47], v[128:131], v[152:155], v[44:47]
	v_mfma_f32_16x16x32_bf16 v[40:43], v[136:139], v[152:155], v[40:43]
	v_mfma_f32_16x16x32_bf16 v[28:31], v[128:131], v[160:163], v[28:31]
	v_mfma_f32_16x16x32_bf16 v[24:27], v[136:139], v[160:163], v[24:27]
	v_mfma_f32_16x16x32_bf16 v[12:15], v[128:131], v[184:187], v[12:15]
	v_mfma_f32_16x16x32_bf16 v[8:11], v[136:139], v[184:187], v[8:11]
	v_mfma_f32_16x16x32_bf16 v[60:63], v[132:135], v[148:151], v[60:63]
	v_mfma_f32_16x16x32_bf16 v[56:59], v[140:143], v[148:151], v[56:59]
	v_mfma_f32_16x16x32_bf16 v[44:47], v[132:135], v[156:159], v[44:47]
	v_mfma_f32_16x16x32_bf16 v[40:43], v[140:143], v[156:159], v[40:43]
	v_mfma_f32_16x16x32_bf16 v[28:31], v[132:135], v[180:183], v[28:31]
	v_mfma_f32_16x16x32_bf16 v[24:27], v[140:143], v[180:183], v[24:27]
	v_mfma_f32_16x16x32_bf16 v[12:15], v[132:135], v[188:191], v[12:15]
	v_mfma_f32_16x16x32_bf16 v[8:11], v[140:143], v[188:191], v[8:11]
	s_barrier
	s_add_i32 s16, s16, s20
	v_lshl_add_u64 v[128:129], v[224:225], 0, s[8:9]
	s_mov_b32 m0, s16
	s_nop 0
	global_load_lds_dwordx4 v[128:129], off
	v_lshl_add_u64 v[128:129], v[226:227], 0, s[8:9]
	s_add_i32 m0, s16, 0x2000
	s_nop 0
	global_load_lds_dwordx4 v[128:129], off
	s_waitcnt vmcnt(6)
	s_barrier
	v_mfma_f32_16x16x32_bf16 v[52:55], v[192:195], v[144:147], v[52:55]
	v_mfma_f32_16x16x32_bf16 v[48:51], v[210:213], v[144:147], v[48:51]
	v_mfma_f32_16x16x32_bf16 v[36:39], v[192:195], v[152:155], v[36:39]
	v_mfma_f32_16x16x32_bf16 v[32:35], v[210:213], v[152:155], v[32:35]
	v_mfma_f32_16x16x32_bf16 v[20:23], v[192:195], v[160:163], v[20:23]
	v_mfma_f32_16x16x32_bf16 v[16:19], v[210:213], v[160:163], v[16:19]
	v_mfma_f32_16x16x32_bf16 v[4:7], v[192:195], v[184:187], v[4:7]
	v_mfma_f32_16x16x32_bf16 v[0:3], v[210:213], v[184:187], v[0:3]
	v_mfma_f32_16x16x32_bf16 v[52:55], v[206:209], v[148:151], v[52:55]
	v_mfma_f32_16x16x32_bf16 v[48:51], v[214:217], v[148:151], v[48:51]
	v_mfma_f32_16x16x32_bf16 v[36:39], v[206:209], v[156:159], v[36:39]
	v_mfma_f32_16x16x32_bf16 v[32:35], v[214:217], v[156:159], v[32:35]
	v_mfma_f32_16x16x32_bf16 v[20:23], v[206:209], v[180:183], v[20:23]
	v_mfma_f32_16x16x32_bf16 v[16:19], v[214:217], v[180:183], v[16:19]
	v_mfma_f32_16x16x32_bf16 v[4:7], v[206:209], v[188:191], v[4:7]
	v_mfma_f32_16x16x32_bf16 v[0:3], v[214:217], v[188:191], v[0:3]
	s_add_u32 s14, s14, 0x100
	s_addc_u32 s15, s15, 0
	s_add_u32 s70, s70, 0x100
	s_addc_u32 s71, s71, 0
	s_cmp_ge_i32 s72, s25
	s_mov_b32 s16, s72
	s_barrier
	s_cbranch_scc0 .LBB0_1301

; #define PG8_STAGE(bufoff, gbase, voff) do { _Pragma("unroll") for (int _i = 0; _i < 2; ++_i) \
;         __builtin_amdgcn_global_load_lds((const unsigned*)((const char*)(gbase) + (voff)[_i]), (LAS unsigned*)(lds + (bufoff) + ldsw + _i * 8192), 16, 0, 0); } while (0)
; #define PG8_LDA(dst, b, h) do { _Pragma("unroll") for (int m = 0; m < 4; ++m) _Pragma("unroll") for (int k = 0; k < 2; ++k) dst[m][k] = *(const LAS bf16x8*)(lds + PG8_SA(b, h) + aoff + m * 2048 + k * 1024); } while (0)
; #define PG8_LDB(dst, b, h) do { _Pragma("unroll") for (int n = 0; n < 2; ++n) _Pragma("unroll") for (int k = 0; k < 2; ++k) dst[n][k] = *(const LAS bf16x8*)(lds + PG8_SB(b, h) + boff + n * 2048 + k * 1024); } while (0)
; #define PG8_MMA(ai, bj, At, Bt) do { __builtin_amdgcn_s_setprio(1); _Pragma("unroll") for (int m = 0; m < 4; ++m) _Pragma("unroll") for (int n = 0; n < 2; ++n) _Pragma("unroll") for (int k = 0; k < 2; ++k) \
;         acc[ai][bj][m][n] = __builtin_amdgcn_mfma_f32_16x16x32_bf16(Bt[n][k], At[m][k], acc[ai][bj][m][n], 0, 0, 0); __builtin_amdgcn_s_setprio(0); } while (0)
; #define PG8_WAIT_L(n) asm volatile("s_waitcnt lgkmcnt(" #n ")" ::: "memory")
; #define PG8_BAR __builtin_amdgcn_s_barrier()
; #define PG8_SCHED __builtin_amdgcn_sched_barrier(0)
; template <class Epi>
; DEVI void gemm_phase(LAS unsigned char* lds, const bf16_t* gA, const bf16_t* gBt, const int lda, const int ldb, const int K, const StaticOrder S_, const Epi E) {
;     ...
;             const bool last = (t == nt - 2);
;             const char* a1 = cA + (size_t)(t + 1) * kstep;
;             const char* a2 = last ? nA : cA + (size_t)(t + 2) * kstep; const char* b2 = last ? nB : cB + (size_t)(t + 2) * kstep;
;             const char* a3 = a2 + kstep; const char* b3 = b2 + kstep;
;             PG8_LDB(B0, 0, 0); PG8_SCHED; PG8_LDA(At, 0, 0); PG8_STAGE(PG8_SA(1, 1), a1 + hstepA, voffA);
;             PG8_WAIT_L(8); PG8_BAR; PG8_WAIT_L(0); PG8_MMA(0, 0, At, B0); PG8_BAR; PG8_SCHED;
;             PG8_LDB(B1, 0, 1); PG8_STAGE(PG8_SB(0, 0), b2, voffB);
;             PG8_BAR; PG8_WAIT_L(0); PG8_MMA(0, 1, At, B1); PG8_BAR;
;             PG8_LDA(At, 0, 1); PG8_STAGE(PG8_SA(0, 0), a2, voffA);
;             PG8_BAR; PG8_WAIT_L(0); PG8_MMA(1, 0, At, B0); PG8_BAR; PG8_SCHED;
.LBB0_1445:
	ds_read_b128 v[158:161], v151
	ds_read_b128 v[162:165], v151 offset:1024
	ds_read_b128 v[166:169], v151 offset:2048
	ds_read_b128 v[170:173], v151 offset:3072
	s_add_i32 s79, s16, 2
	s_add_u32 s70, s14, 0x80
	s_addc_u32 s17, s15, 0
	s_cmp_eq_u32 s26, s16
	s_cselect_b32 s16, s40, s70
	s_cselect_b32 s17, s41, s17
	s_cselect_b32 s71, s67, s78
	s_cselect_b32 s70, s66, s77
	v_lshl_add_u64 v[144:145], s[14:15], 0, v[138:139]
	s_add_i32 m0, s19, 0xc000
	ds_read_b128 v[174:177], v152
	ds_read_b128 v[178:181], v152 offset:1024
	ds_read_b128 v[182:185], v152 offset:2048
	ds_read_b128 v[186:189], v152 offset:3072
	ds_read_b128 v[190:193], v152 offset:4096
	ds_read_b128 v[198:201], v152 offset:5120
	ds_read_b128 v[202:205], v152 offset:6144
	ds_read_b128 v[206:209], v152 offset:7168
	global_load_lds_dwordx4 v[144:145], off
	v_lshl_add_u64 v[144:145], s[14:15], 0, v[140:141]
	s_add_i32 m0, s19, 0xe000
	s_nop 0
	global_load_lds_dwordx4 v[144:145], off
	s_waitcnt lgkmcnt(8)
	s_barrier
	s_waitcnt lgkmcnt(0)
	s_waitcnt lgkmcnt(0)
	v_mfma_f32_16x16x32_bf16 v[120:123], v[158:161], v[174:177], v[120:123]
	v_mfma_f32_16x16x32_bf16 v[116:119], v[166:169], v[174:177], v[116:119]
	v_mfma_f32_16x16x32_bf16 v[108:111], v[158:161], v[182:185], v[108:111]
	v_mfma_f32_16x16x32_bf16 v[100:103], v[166:169], v[182:185], v[100:103]
	v_mfma_f32_16x16x32_bf16 v[92:95], v[158:161], v[190:193], v[92:95]
	v_mfma_f32_16x16x32_bf16 v[84:87], v[166:169], v[190:193], v[84:87]
	v_mfma_f32_16x16x32_bf16 v[76:79], v[158:161], v[202:205], v[76:79]
	v_mfma_f32_16x16x32_bf16 v[68:71], v[166:169], v[202:205], v[68:71]
	v_mfma_f32_16x16x32_bf16 v[120:123], v[162:165], v[178:181], v[120:123]
	v_mfma_f32_16x16x32_bf16 v[116:119], v[170:173], v[178:181], v[116:119]
	v_mfma_f32_16x16x32_bf16 v[108:111], v[162:165], v[186:189], v[108:111]
	v_mfma_f32_16x16x32_bf16 v[100:103], v[170:173], v[186:189], v[100:103]
	v_mfma_f32_16x16x32_bf16 v[92:95], v[162:165], v[198:201], v[92:95]
	v_mfma_f32_16x16x32_bf16 v[84:87], v[170:173], v[198:201], v[84:87]
	v_mfma_f32_16x16x32_bf16 v[76:79], v[162:165], v[206:209], v[76:79]
	v_mfma_f32_16x16x32_bf16 v[68:71], v[170:173], v[206:209], v[68:71]
	s_barrier
	s_add_i32 s80, s34, s18
	v_lshl_add_u64 v[144:145], s[70:71], 0, v[130:131]
	s_mov_b32 m0, s80
	ds_read_b128 v[210:213], v153
	ds_read_b128 v[214:217], v153 offset:1024
	ds_read_b128 v[218:221], v153 offset:2048
	ds_read_b128 v[222:225], v153 offset:3072
	global_load_lds_dwordx4 v[144:145], off
	v_lshl_add_u64 v[194:195], s[70:71], 0, v[134:135]
	s_add_i32 m0, s80, 0x2000
	s_nop 0
	global_load_lds_dwordx4 v[194:195], off
	s_barrier
	s_waitcnt lgkmcnt(0)
	s_waitcnt lgkmcnt(0)
	v_mfma_f32_16x16x32_bf16 v[124:127], v[210:213], v[174:177], v[124:127]
	v_mfma_f32_16x16x32_bf16 v[112:115], v[218:221], v[174:177], v[112:115]
	v_mfma_f32_16x16x32_bf16 v[104:107], v[210:213], v[182:185], v[104:107]
	v_mfma_f32_16x16x32_bf16 v[96:99], v[218:221], v[182:185], v[96:99]
	v_mfma_f32_16x16x32_bf16 v[88:91], v[210:213], v[190:193], v[88:91]
	v_mfma_f32_16x16x32_bf16 v[80:83], v[218:221], v[190:193], v[80:83]
	v_mfma_f32_16x16x32_bf16 v[72:75], v[210:213], v[202:205], v[72:75]
	v_mfma_f32_16x16x32_bf16 v[64:67], v[218:221], v[202:205], v[64:67]
	v_mfma_f32_16x16x32_bf16 v[124:127], v[214:217], v[178:181], v[124:127]
	v_mfma_f32_16x16x32_bf16 v[112:115], v[222:225], v[178:181], v[112:115]
	v_mfma_f32_16x16x32_bf16 v[104:107], v[214:217], v[186:189], v[104:107]
	v_mfma_f32_16x16x32_bf16 v[96:99], v[222:225], v[186:189], v[96:99]
	v_mfma_f32_16x16x32_bf16 v[88:91], v[214:217], v[198:201], v[88:91]
	v_mfma_f32_16x16x32_bf16 v[80:83], v[222:225], v[198:201], v[80:83]
	v_mfma_f32_16x16x32_bf16 v[72:75], v[214:217], v[206:209], v[72:75]
	v_mfma_f32_16x16x32_bf16 v[64:67], v[222:225], v[206:209], v[64:67]
	s_mov_b32 m0, s19
	v_lshl_add_u64 v[226:227], s[16:17], 0, v[128:129]
	s_barrier
	ds_read_b128 v[174:177], v152 offset:16384
	ds_read_b128 v[178:181], v152 offset:17408
	ds_read_b128 v[182:185], v152 offset:18432
	ds_read_b128 v[186:189], v152 offset:19456
	ds_read_b128 v[190:193], v152 offset:20480
	ds_read_b128 v[198:201], v152 offset:21504
	ds_read_b128 v[202:205], v152 offset:22528
	ds_read_b128 v[206:209], v152 offset:23552
	global_load_lds_dwordx4 v[226:227], off
	v_lshl_add_u64 v[228:229], s[16:17], 0, v[132:133]
	s_mov_b32 m0, s20
	s_nop 0
	global_load_lds_dwordx4 v[228:229], off
	s_barrier
	s_waitcnt lgkmcnt(0)
	s_waitcnt lgkmcnt(0)
	v_mfma_f32_16x16x32_bf16 v[60:63], v[158:161], v[174:177], v[60:63]
	v_mfma_f32_16x16x32_bf16 v[56:59], v[166:169], v[174:177], v[56:59]
	v_mfma_f32_16x16x32_bf16 v[44:47], v[158:161], v[182:185], v[44:47]
	v_mfma_f32_16x16x32_bf16 v[40:43], v[166:169], v[182:185], v[40:43]
	v_mfma_f32_16x16x32_bf16 v[28:31], v[158:161], v[190:193], v[28:31]
	v_mfma_f32_16x16x32_bf16 v[24:27], v[166:169], v[190:193], v[24:27]
	v_mfma_f32_16x16x32_bf16 v[12:15], v[158:161], v[202:205], v[12:15]
	v_mfma_f32_16x16x32_bf16 v[8:11], v[166:169], v[202:205], v[8:11]
	v_mfma_f32_16x16x32_bf16 v[60:63], v[162:165], v[178:181], v[60:63]
	v_mfma_f32_16x16x32_bf16 v[56:59], v[170:173], v[178:181], v[56:59]
	v_mfma_f32_16x16x32_bf16 v[44:47], v[162:165], v[186:189], v[44:47]
	v_mfma_f32_16x16x32_bf16 v[40:43], v[170:173], v[186:189], v[40:43]
	v_mfma_f32_16x16x32_bf16 v[28:31], v[162:165], v[198:201], v[28:31]
	v_mfma_f32_16x16x32_bf16 v[24:27], v[170:173], v[198:201], v[24:27]
	v_mfma_f32_16x16x32_bf16 v[12:15], v[162:165], v[206:209], v[12:15]
	v_mfma_f32_16x16x32_bf16 v[8:11], v[170:173], v[206:209], v[8:11]
	s_barrier
; #define PG8_STAGE(bufoff, gbase, voff) do { _Pragma("unroll") for (int _i = 0; _i < 2; ++_i) \
;         __builtin_amdgcn_global_load_lds((const unsigned*)((const char*)(gbase) + (voff)[_i]), (LAS unsigned*)(lds + (bufoff) + ldsw + _i * 8192), 16, 0, 0); } while (0)
; #define PG8_LDA(dst, b, h) do { _Pragma("unroll") for (int m = 0; m < 4; ++m) _Pragma("unroll") for (int k = 0; k < 2; ++k) dst[m][k] = *(const LAS bf16x8*)(lds + PG8_SA(b, h) + aoff + m * 2048 + k * 1024); } while (0)
; #define PG8_LDB(dst, b, h) do { _Pragma("unroll") for (int n = 0; n < 2; ++n) _Pragma("unroll") for (int k = 0; k < 2; ++k) dst[n][k] = *(const LAS bf16x8*)(lds + PG8_SB(b, h) + boff + n * 2048 + k * 1024); } while (0)
; #define PG8_MMA(ai, bj, At, Bt) do { __builtin_amdgcn_s_setprio(1); _Pragma("unroll") for (int m = 0; m < 4; ++m) _Pragma("unroll") for (int n = 0; n < 2; ++n) _Pragma("unroll") for (int k = 0; k < 2; ++k) \
;         acc[ai][bj][m][n] = __builtin_amdgcn_mfma_f32_16x16x32_bf16(Bt[n][k], At[m][k], acc[ai][bj][m][n], 0, 0, 0); __builtin_amdgcn_s_setprio(0); } while (0)
; #define PG8_WAIT_V(n) asm volatile("s_waitcnt vmcnt(" #n ")" ::: "memory")
; #define PG8_WAIT_L(n) asm volatile("s_waitcnt lgkmcnt(" #n ")" ::: "memory")
; #define PG8_BAR __builtin_amdgcn_s_barrier()
; #define PG8_SCHED __builtin_amdgcn_sched_barrier(0)
; template <class Epi>
; DEVI void gemm_phase(LAS unsigned char* lds, const bf16_t* gA, const bf16_t* gBt, const int lda, const int ldb, const int K, const StaticOrder S_, const Epi E) {
;     ...
;             PG8_STAGE(PG8_SB(0, 1), b2 + hstepB, voffB);
;             PG8_WAIT_V(6); PG8_BAR; PG8_MMA(1, 1, At, B1); PG8_BAR;
;             PG8_LDB(B0, 1, 0); PG8_SCHED; PG8_LDA(At, 1, 0); PG8_STAGE(PG8_SA(0, 1), a2 + hstepA, voffA);
;             PG8_WAIT_L(8); PG8_BAR; PG8_WAIT_L(0); PG8_MMA(0, 0, At, B0); PG8_BAR; PG8_SCHED;
;             PG8_LDB(B1, 1, 1); PG8_STAGE(PG8_SB(1, 0), b3, voffB);
	s_add_u32 s70, s70, s2
	s_addc_u32 s71, s71, s3
	s_add_i32 s80, s35, s18
	v_lshl_add_u64 v[230:231], s[70:71], 0, v[130:131]
	s_mov_b32 m0, s80
	v_lshl_add_u64 v[232:233], s[70:71], 0, v[134:135]
	global_load_lds_dwordx4 v[230:231], off
	s_add_i32 m0, s80, 0x2000
	s_nop 0
	global_load_lds_dwordx4 v[232:233], off
	s_waitcnt vmcnt(6)
	s_barrier
	v_mfma_f32_16x16x32_bf16 v[52:55], v[210:213], v[174:177], v[52:55]
	v_mfma_f32_16x16x32_bf16 v[48:51], v[218:221], v[174:177], v[48:51]
	v_mfma_f32_16x16x32_bf16 v[36:39], v[210:213], v[182:185], v[36:39]
	v_mfma_f32_16x16x32_bf16 v[32:35], v[218:221], v[182:185], v[32:35]
	v_mfma_f32_16x16x32_bf16 v[20:23], v[210:213], v[190:193], v[20:23]
	v_mfma_f32_16x16x32_bf16 v[16:19], v[218:221], v[190:193], v[16:19]
	v_mfma_f32_16x16x32_bf16 v[4:7], v[210:213], v[202:205], v[4:7]
	v_mfma_f32_16x16x32_bf16 v[0:3], v[218:221], v[202:205], v[0:3]
	v_mfma_f32_16x16x32_bf16 v[52:55], v[214:217], v[178:181], v[52:55]
	v_mfma_f32_16x16x32_bf16 v[48:51], v[222:225], v[178:181], v[48:51]
	v_mfma_f32_16x16x32_bf16 v[36:39], v[214:217], v[186:189], v[36:39]
	v_mfma_f32_16x16x32_bf16 v[32:35], v[222:225], v[186:189], v[32:35]
	v_mfma_f32_16x16x32_bf16 v[20:23], v[214:217], v[198:201], v[20:23]
	v_mfma_f32_16x16x32_bf16 v[16:19], v[222:225], v[198:201], v[16:19]
	v_mfma_f32_16x16x32_bf16 v[4:7], v[214:217], v[206:209], v[4:7]
	v_mfma_f32_16x16x32_bf16 v[0:3], v[222:225], v[206:209], v[0:3]
	s_barrier
	ds_read_b128 v[158:161], v154
	ds_read_b128 v[162:165], v154 offset:1024
	ds_read_b128 v[166:169], v154 offset:2048
	ds_read_b128 v[170:173], v154 offset:3072
	s_add_u32 s16, s16, s0
	s_addc_u32 s17, s17, s1
	s_mov_b32 m0, s21
	v_lshl_add_u64 v[210:211], s[16:17], 0, v[128:129]
	ds_read_b128 v[174:177], v152 offset:32768
	ds_read_b128 v[178:181], v152 offset:33792
	ds_read_b128 v[182:185], v152 offset:34816
	ds_read_b128 v[186:189], v152 offset:35840
	ds_read_b128 v[190:193], v152 offset:36864
	ds_read_b128 v[198:201], v152 offset:37888
	ds_read_b128 v[202:205], v152 offset:38912
	ds_read_b128 v[206:209], v152 offset:39936
	global_load_lds_dwordx4 v[210:211], off
	v_lshl_add_u64 v[210:211], s[16:17], 0, v[132:133]
	s_mov_b32 m0, s22
	s_nop 0
	global_load_lds_dwordx4 v[210:211], off
	s_waitcnt lgkmcnt(8)
	s_barrier
	s_waitcnt lgkmcnt(0)
	s_waitcnt lgkmcnt(0)
	v_mfma_f32_16x16x32_bf16 v[120:123], v[158:161], v[174:177], v[120:123]
	v_mfma_f32_16x16x32_bf16 v[116:119], v[166:169], v[174:177], v[116:119]
	v_mfma_f32_16x16x32_bf16 v[108:111], v[158:161], v[182:185], v[108:111]
	v_mfma_f32_16x16x32_bf16 v[100:103], v[166:169], v[182:185], v[100:103]
	v_mfma_f32_16x16x32_bf16 v[92:95], v[158:161], v[190:193], v[92:95]
	v_mfma_f32_16x16x32_bf16 v[84:87], v[166:169], v[190:193], v[84:87]
	v_mfma_f32_16x16x32_bf16 v[76:79], v[158:161], v[202:205], v[76:79]
	v_mfma_f32_16x16x32_bf16 v[68:71], v[166:169], v[202:205], v[68:71]
	v_mfma_f32_16x16x32_bf16 v[120:123], v[162:165], v[178:181], v[120:123]
	v_mfma_f32_16x16x32_bf16 v[116:119], v[170:173], v[178:181], v[116:119]
	v_mfma_f32_16x16x32_bf16 v[108:111], v[162:165], v[186:189], v[108:111]
	v_mfma_f32_16x16x32_bf16 v[100:103], v[170:173], v[186:189], v[100:103]
	v_mfma_f32_16x16x32_bf16 v[92:95], v[162:165], v[198:201], v[92:95]
	v_mfma_f32_16x16x32_bf16 v[84:87], v[170:173], v[198:201], v[84:87]
	v_mfma_f32_16x16x32_bf16 v[76:79], v[162:165], v[206:209], v[76:79]
	v_mfma_f32_16x16x32_bf16 v[68:71], v[170:173], v[206:209], v[68:71]
	s_barrier
	s_add_i32 s16, s49, s18
	v_lshl_add_u64 v[144:145], v[144:145], 0, s[64:65]
	s_mov_b32 m0, s16
	ds_read_b128 v[210:213], v155
	ds_read_b128 v[214:217], v155 offset:1024
	ds_read_b128 v[218:221], v155 offset:2048
	ds_read_b128 v[222:225], v155 offset:3072
	global_load_lds_dwordx4 v[144:145], off
	v_lshl_add_u64 v[144:145], v[194:195], 0, s[64:65]
	s_add_i32 m0, s16, 0x2000
	s_nop 0
	global_load_lds_dwordx4 v[144:145], off
	s_barrier
; #define PG8_STAGE(bufoff, gbase, voff) do { _Pragma("unroll") for (int _i = 0; _i < 2; ++_i) \
;         __builtin_amdgcn_global_load_lds((const unsigned*)((const char*)(gbase) + (voff)[_i]), (LAS unsigned*)(lds + (bufoff) + ldsw + _i * 8192), 16, 0, 0); } while (0)
; #define PG8_LDA(dst, b, h) do { _Pragma("unroll") for (int m = 0; m < 4; ++m) _Pragma("unroll") for (int k = 0; k < 2; ++k) dst[m][k] = *(const LAS bf16x8*)(lds + PG8_SA(b, h) + aoff + m * 2048 + k * 1024); } while (0)
; #define PG8_MMA(ai, bj, At, Bt) do { __builtin_amdgcn_s_setprio(1); _Pragma("unroll") for (int m = 0; m < 4; ++m) _Pragma("unroll") for (int n = 0; n < 2; ++n) _Pragma("unroll") for (int k = 0; k < 2; ++k) \
;         acc[ai][bj][m][n] = __builtin_amdgcn_mfma_f32_16x16x32_bf16(Bt[n][k], At[m][k], acc[ai][bj][m][n], 0, 0, 0); __builtin_amdgcn_s_setprio(0); } while (0)
; #define PG8_WAIT_V(n) asm volatile("s_waitcnt vmcnt(" #n ")" ::: "memory")
; #define PG8_WAIT_L(n) asm volatile("s_waitcnt lgkmcnt(" #n ")" ::: "memory")
; #define PG8_BAR __builtin_amdgcn_s_barrier()
; #define PG8_SCHED __builtin_amdgcn_sched_barrier(0)
; template <class Epi>
; DEVI void gemm_phase(LAS unsigned char* lds, const bf16_t* gA, const bf16_t* gBt, const int lda, const int ldb, const int K, const StaticOrder S_, const Epi E) {
;     ...
;             PG8_BAR; PG8_WAIT_L(0); PG8_MMA(0, 1, At, B1); PG8_BAR;
;             PG8_LDA(At, 1, 1); PG8_STAGE(PG8_SA(1, 0), a3, voffA);
;             PG8_BAR; PG8_WAIT_L(0); PG8_MMA(1, 0, At, B0); PG8_BAR; PG8_SCHED;
;             PG8_STAGE(PG8_SB(1, 1), b3 + hstepB, voffB);
;             PG8_WAIT_V(6); PG8_BAR; PG8_MMA(1, 1, At, B1); PG8_BAR;
;         }
	s_waitcnt lgkmcnt(0)
	s_waitcnt lgkmcnt(0)
	v_mfma_f32_16x16x32_bf16 v[124:127], v[210:213], v[174:177], v[124:127]
	v_mfma_f32_16x16x32_bf16 v[112:115], v[218:221], v[174:177], v[112:115]
	v_mfma_f32_16x16x32_bf16 v[104:107], v[210:213], v[182:185], v[104:107]
	v_mfma_f32_16x16x32_bf16 v[96:99], v[218:221], v[182:185], v[96:99]
	v_mfma_f32_16x16x32_bf16 v[88:91], v[210:213], v[190:193], v[88:91]
	v_mfma_f32_16x16x32_bf16 v[80:83], v[218:221], v[190:193], v[80:83]
	v_mfma_f32_16x16x32_bf16 v[72:75], v[210:213], v[202:205], v[72:75]
	v_mfma_f32_16x16x32_bf16 v[64:67], v[218:221], v[202:205], v[64:67]
	v_mfma_f32_16x16x32_bf16 v[124:127], v[214:217], v[178:181], v[124:127]
	v_mfma_f32_16x16x32_bf16 v[112:115], v[222:225], v[178:181], v[112:115]
	v_mfma_f32_16x16x32_bf16 v[104:107], v[214:217], v[186:189], v[104:107]
	v_mfma_f32_16x16x32_bf16 v[96:99], v[222:225], v[186:189], v[96:99]
	v_mfma_f32_16x16x32_bf16 v[88:91], v[214:217], v[198:201], v[88:91]
	v_mfma_f32_16x16x32_bf16 v[80:83], v[222:225], v[198:201], v[80:83]
	v_mfma_f32_16x16x32_bf16 v[72:75], v[214:217], v[206:209], v[72:75]
	v_mfma_f32_16x16x32_bf16 v[64:67], v[222:225], v[206:209], v[64:67]
	s_mov_b32 m0, s23
	v_lshl_add_u64 v[144:145], v[226:227], 0, s[64:65]
	s_barrier
	ds_read_b128 v[174:177], v152 offset:49152
	ds_read_b128 v[178:181], v152 offset:50176
	ds_read_b128 v[182:185], v152 offset:51200
	ds_read_b128 v[186:189], v152 offset:52224
	ds_read_b128 v[190:193], v152 offset:53248
	ds_read_b128 v[198:201], v152 offset:54272
	ds_read_b128 v[202:205], v152 offset:55296
	ds_read_b128 v[206:209], v152 offset:56320
	global_load_lds_dwordx4 v[144:145], off
	v_lshl_add_u64 v[144:145], v[228:229], 0, s[64:65]
	s_mov_b32 m0, s24
	s_nop 0
	global_load_lds_dwordx4 v[144:145], off
	s_barrier
	s_waitcnt lgkmcnt(0)
	s_waitcnt lgkmcnt(0)
	v_mfma_f32_16x16x32_bf16 v[60:63], v[158:161], v[174:177], v[60:63]
	v_mfma_f32_16x16x32_bf16 v[56:59], v[166:169], v[174:177], v[56:59]
	v_mfma_f32_16x16x32_bf16 v[44:47], v[158:161], v[182:185], v[44:47]
	v_mfma_f32_16x16x32_bf16 v[40:43], v[166:169], v[182:185], v[40:43]
	v_mfma_f32_16x16x32_bf16 v[28:31], v[158:161], v[190:193], v[28:31]
	v_mfma_f32_16x16x32_bf16 v[24:27], v[166:169], v[190:193], v[24:27]
	v_mfma_f32_16x16x32_bf16 v[12:15], v[158:161], v[202:205], v[12:15]
	v_mfma_f32_16x16x32_bf16 v[8:11], v[166:169], v[202:205], v[8:11]
	v_mfma_f32_16x16x32_bf16 v[60:63], v[162:165], v[178:181], v[60:63]
	v_mfma_f32_16x16x32_bf16 v[56:59], v[170:173], v[178:181], v[56:59]
	v_mfma_f32_16x16x32_bf16 v[44:47], v[162:165], v[186:189], v[44:47]
	v_mfma_f32_16x16x32_bf16 v[40:43], v[170:173], v[186:189], v[40:43]
	v_mfma_f32_16x16x32_bf16 v[28:31], v[162:165], v[198:201], v[28:31]
	v_mfma_f32_16x16x32_bf16 v[24:27], v[170:173], v[198:201], v[24:27]
	v_mfma_f32_16x16x32_bf16 v[12:15], v[162:165], v[206:209], v[12:15]
	v_mfma_f32_16x16x32_bf16 v[8:11], v[170:173], v[206:209], v[8:11]
	s_barrier
	s_add_i32 s16, s31, s18
	v_lshl_add_u64 v[144:145], v[230:231], 0, s[64:65]
	s_mov_b32 m0, s16
	s_nop 0
	global_load_lds_dwordx4 v[144:145], off
	v_lshl_add_u64 v[144:145], v[232:233], 0, s[64:65]
	s_add_i32 m0, s16, 0x2000
	s_nop 0
	global_load_lds_dwordx4 v[144:145], off
	s_waitcnt vmcnt(6)
	s_barrier
	v_mfma_f32_16x16x32_bf16 v[52:55], v[210:213], v[174:177], v[52:55]
	v_mfma_f32_16x16x32_bf16 v[48:51], v[218:221], v[174:177], v[48:51]
	v_mfma_f32_16x16x32_bf16 v[36:39], v[210:213], v[182:185], v[36:39]
	v_mfma_f32_16x16x32_bf16 v[32:35], v[218:221], v[182:185], v[32:35]
	v_mfma_f32_16x16x32_bf16 v[20:23], v[210:213], v[190:193], v[20:23]
	v_mfma_f32_16x16x32_bf16 v[16:19], v[218:221], v[190:193], v[16:19]
	v_mfma_f32_16x16x32_bf16 v[4:7], v[210:213], v[202:205], v[4:7]
	v_mfma_f32_16x16x32_bf16 v[0:3], v[218:221], v[202:205], v[0:3]
	v_mfma_f32_16x16x32_bf16 v[52:55], v[214:217], v[178:181], v[52:55]
	v_mfma_f32_16x16x32_bf16 v[48:51], v[222:225], v[178:181], v[48:51]
	v_mfma_f32_16x16x32_bf16 v[36:39], v[214:217], v[186:189], v[36:39]
	v_mfma_f32_16x16x32_bf16 v[32:35], v[222:225], v[186:189], v[32:35]
	v_mfma_f32_16x16x32_bf16 v[20:23], v[214:217], v[198:201], v[20:23]
	v_mfma_f32_16x16x32_bf16 v[16:19], v[222:225], v[198:201], v[16:19]
	v_mfma_f32_16x16x32_bf16 v[4:7], v[214:217], v[206:209], v[4:7]
	v_mfma_f32_16x16x32_bf16 v[0:3], v[222:225], v[206:209], v[0:3]
	s_add_u32 s14, s14, 0x100
	s_addc_u32 s15, s15, 0
	s_add_u32 s77, s77, 0x100
	s_addc_u32 s78, s78, 0
	s_cmp_ge_i32 s79, s25
	s_mov_b32 s16, s79
	s_barrier
	s_cbranch_scc0 .LBB0_1445

; #define PG8_STAGE(bufoff, gbase, voff) do { _Pragma("unroll") for (int _i = 0; _i < 2; ++_i) \
;         __builtin_amdgcn_global_load_lds((const unsigned*)((const char*)(gbase) + (voff)[_i]), (LAS unsigned*)(lds + (bufoff) + ldsw + _i * 8192), 16, 0, 0); } while (0)
; #define PG8_LDA(dst, b, h) do { _Pragma("unroll") for (int m = 0; m < 4; ++m) _Pragma("unroll") for (int k = 0; k < 2; ++k) dst[m][k] = *(const LAS bf16x8*)(lds + PG8_SA(b, h) + aoff + m * 2048 + k * 1024); } while (0)
; #define PG8_LDB(dst, b, h) do { _Pragma("unroll") for (int n = 0; n < 2; ++n) _Pragma("unroll") for (int k = 0; k < 2; ++k) dst[n][k] = *(const LAS bf16x8*)(lds + PG8_SB(b, h) + boff + n * 2048 + k * 1024); } while (0)
; #define PG8_MMA(ai, bj, At, Bt) do { __builtin_amdgcn_s_setprio(1); _Pragma("unroll") for (int m = 0; m < 4; ++m) _Pragma("unroll") for (int n = 0; n < 2; ++n) _Pragma("unroll") for (int k = 0; k < 2; ++k) \
;         acc[ai][bj][m][n] = __builtin_amdgcn_mfma_f32_16x16x32_bf16(Bt[n][k], At[m][k], acc[ai][bj][m][n], 0, 0, 0); __builtin_amdgcn_s_setprio(0); } while (0)
; #define PG8_WAIT_L(n) asm volatile("s_waitcnt lgkmcnt(" #n ")" ::: "memory")
; #define PG8_BAR __builtin_amdgcn_s_barrier()
; #define PG8_SCHED __builtin_amdgcn_sched_barrier(0)
; template <class Epi>
; DEVI void gemm_phase(LAS unsigned char* lds, const bf16_t* gA, const bf16_t* gBt, const int lda, const int ldb, const int K, const StaticOrder S_, const Epi E) {
;     ...
;             const bool last = (t == nt - 2);
;             const char* a1 = cA + (size_t)(t + 1) * kstep;
;             const char* a2 = last ? nA : cA + (size_t)(t + 2) * kstep; const char* b2 = last ? nB : cB + (size_t)(t + 2) * kstep;
;             const char* a3 = a2 + kstep; const char* b3 = b2 + kstep;
;             PG8_LDB(B0, 0, 0); PG8_SCHED; PG8_LDA(At, 0, 0); PG8_STAGE(PG8_SA(1, 1), a1 + hstepA, voffA);
;             PG8_WAIT_L(8); PG8_BAR; PG8_WAIT_L(0); PG8_MMA(0, 0, At, B0); PG8_BAR; PG8_SCHED;
;             PG8_LDB(B1, 0, 1); PG8_STAGE(PG8_SB(0, 0), b2, voffB);
;             PG8_BAR; PG8_WAIT_L(0); PG8_MMA(0, 1, At, B1); PG8_BAR;
;             PG8_LDA(At, 0, 1); PG8_STAGE(PG8_SA(0, 0), a2, voffA);
;             PG8_BAR; PG8_WAIT_L(0); PG8_MMA(1, 0, At, B0); PG8_BAR; PG8_SCHED;
.LBB0_1574:
	ds_read_b128 v[128:131], v201
	ds_read_b128 v[132:135], v201 offset:1024
	ds_read_b128 v[136:139], v201 offset:2048
	ds_read_b128 v[140:143], v201 offset:3072
	s_add_i32 s75, s16, 2
	s_add_u32 s40, s14, 0x80
	s_addc_u32 s17, s15, 0
	s_cmp_eq_u32 s19, s16
	s_cselect_b32 s16, s12, s40
	s_cselect_b32 s17, s13, s17
	s_cselect_b32 s41, s43, s71
	s_cselect_b32 s40, s42, s70
	v_lshl_add_u64 v[164:165], s[14:15], 0, v[174:175]
	s_add_i32 m0, s74, 0xc000
	ds_read_b128 v[144:147], v202
	ds_read_b128 v[148:151], v202 offset:1024
	ds_read_b128 v[152:155], v202 offset:2048
	ds_read_b128 v[156:159], v202 offset:3072
	ds_read_b128 v[160:163], v202 offset:4096
	ds_read_b128 v[180:183], v202 offset:5120
	ds_read_b128 v[184:187], v202 offset:6144
	ds_read_b128 v[188:191], v202 offset:7168
	global_load_lds_dwordx4 v[164:165], off
	v_lshl_add_u64 v[164:165], s[14:15], 0, v[176:177]
	s_add_i32 m0, s74, 0xe000
	s_nop 0
	global_load_lds_dwordx4 v[164:165], off
	s_waitcnt lgkmcnt(8)
	s_barrier
	s_waitcnt lgkmcnt(0)
	s_waitcnt lgkmcnt(0)
	v_mfma_f32_16x16x32_bf16 v[124:127], v[128:131], v[144:147], v[124:127]
	v_mfma_f32_16x16x32_bf16 v[120:123], v[136:139], v[144:147], v[120:123]
	v_mfma_f32_16x16x32_bf16 v[108:111], v[128:131], v[152:155], v[108:111]
	v_mfma_f32_16x16x32_bf16 v[104:107], v[136:139], v[152:155], v[104:107]
	v_mfma_f32_16x16x32_bf16 v[92:95], v[128:131], v[160:163], v[92:95]
	v_mfma_f32_16x16x32_bf16 v[88:91], v[136:139], v[160:163], v[88:91]
	v_mfma_f32_16x16x32_bf16 v[76:79], v[128:131], v[184:187], v[76:79]
	v_mfma_f32_16x16x32_bf16 v[72:75], v[136:139], v[184:187], v[72:75]
	v_mfma_f32_16x16x32_bf16 v[124:127], v[132:135], v[148:151], v[124:127]
	v_mfma_f32_16x16x32_bf16 v[120:123], v[140:143], v[148:151], v[120:123]
	v_mfma_f32_16x16x32_bf16 v[108:111], v[132:135], v[156:159], v[108:111]
	v_mfma_f32_16x16x32_bf16 v[104:107], v[140:143], v[156:159], v[104:107]
	v_mfma_f32_16x16x32_bf16 v[92:95], v[132:135], v[180:183], v[92:95]
	v_mfma_f32_16x16x32_bf16 v[88:91], v[140:143], v[180:183], v[88:91]
	v_mfma_f32_16x16x32_bf16 v[76:79], v[132:135], v[188:191], v[76:79]
	v_mfma_f32_16x16x32_bf16 v[72:75], v[140:143], v[188:191], v[72:75]
	s_barrier
	s_add_i32 s76, s29, s20
	v_lshl_add_u64 v[164:165], s[40:41], 0, v[168:169]
	s_mov_b32 m0, s76
	ds_read_b128 v[192:195], v203
	ds_read_b128 v[206:209], v203 offset:1024
	ds_read_b128 v[210:213], v203 offset:2048
	ds_read_b128 v[214:217], v203 offset:3072
	global_load_lds_dwordx4 v[164:165], off
	v_lshl_add_u64 v[218:219], s[40:41], 0, v[172:173]
	s_add_i32 m0, s76, 0x2000
	s_nop 0
	global_load_lds_dwordx4 v[218:219], off
	s_barrier
	s_waitcnt lgkmcnt(0)
	s_waitcnt lgkmcnt(0)
	v_mfma_f32_16x16x32_bf16 v[116:119], v[192:195], v[144:147], v[116:119]
	v_mfma_f32_16x16x32_bf16 v[112:115], v[210:213], v[144:147], v[112:115]
	v_mfma_f32_16x16x32_bf16 v[100:103], v[192:195], v[152:155], v[100:103]
	v_mfma_f32_16x16x32_bf16 v[96:99], v[210:213], v[152:155], v[96:99]
	v_mfma_f32_16x16x32_bf16 v[84:87], v[192:195], v[160:163], v[84:87]
	v_mfma_f32_16x16x32_bf16 v[80:83], v[210:213], v[160:163], v[80:83]
	v_mfma_f32_16x16x32_bf16 v[68:71], v[192:195], v[184:187], v[68:71]
	v_mfma_f32_16x16x32_bf16 v[64:67], v[210:213], v[184:187], v[64:67]
	v_mfma_f32_16x16x32_bf16 v[116:119], v[206:209], v[148:151], v[116:119]
	v_mfma_f32_16x16x32_bf16 v[112:115], v[214:217], v[148:151], v[112:115]
	v_mfma_f32_16x16x32_bf16 v[100:103], v[206:209], v[156:159], v[100:103]
	v_mfma_f32_16x16x32_bf16 v[96:99], v[214:217], v[156:159], v[96:99]
	v_mfma_f32_16x16x32_bf16 v[84:87], v[206:209], v[180:183], v[84:87]
	v_mfma_f32_16x16x32_bf16 v[80:83], v[214:217], v[180:183], v[80:83]
	v_mfma_f32_16x16x32_bf16 v[68:71], v[206:209], v[188:191], v[68:71]
	v_mfma_f32_16x16x32_bf16 v[64:67], v[214:217], v[188:191], v[64:67]
	s_mov_b32 m0, s74
	v_lshl_add_u64 v[220:221], s[16:17], 0, v[166:167]
	s_barrier
	ds_read_b128 v[144:147], v202 offset:16384
	ds_read_b128 v[148:151], v202 offset:17408
	ds_read_b128 v[152:155], v202 offset:18432
	ds_read_b128 v[156:159], v202 offset:19456
	ds_read_b128 v[160:163], v202 offset:20480
	ds_read_b128 v[180:183], v202 offset:21504
	ds_read_b128 v[184:187], v202 offset:22528
	ds_read_b128 v[188:191], v202 offset:23552
	global_load_lds_dwordx4 v[220:221], off
	v_lshl_add_u64 v[222:223], s[16:17], 0, v[170:171]
	s_mov_b32 m0, s22
	s_nop 0
	global_load_lds_dwordx4 v[222:223], off
	s_barrier
	s_waitcnt lgkmcnt(0)
	s_waitcnt lgkmcnt(0)
	v_mfma_f32_16x16x32_bf16 v[60:63], v[128:131], v[144:147], v[60:63]
	v_mfma_f32_16x16x32_bf16 v[56:59], v[136:139], v[144:147], v[56:59]
	v_mfma_f32_16x16x32_bf16 v[44:47], v[128:131], v[152:155], v[44:47]
	v_mfma_f32_16x16x32_bf16 v[40:43], v[136:139], v[152:155], v[40:43]
	v_mfma_f32_16x16x32_bf16 v[28:31], v[128:131], v[160:163], v[28:31]
	v_mfma_f32_16x16x32_bf16 v[24:27], v[136:139], v[160:163], v[24:27]
	v_mfma_f32_16x16x32_bf16 v[12:15], v[128:131], v[184:187], v[12:15]
	v_mfma_f32_16x16x32_bf16 v[8:11], v[136:139], v[184:187], v[8:11]
	v_mfma_f32_16x16x32_bf16 v[60:63], v[132:135], v[148:151], v[60:63]
	v_mfma_f32_16x16x32_bf16 v[56:59], v[140:143], v[148:151], v[56:59]
	v_mfma_f32_16x16x32_bf16 v[44:47], v[132:135], v[156:159], v[44:47]
	v_mfma_f32_16x16x32_bf16 v[40:43], v[140:143], v[156:159], v[40:43]
	v_mfma_f32_16x16x32_bf16 v[28:31], v[132:135], v[180:183], v[28:31]
	v_mfma_f32_16x16x32_bf16 v[24:27], v[140:143], v[180:183], v[24:27]
	v_mfma_f32_16x16x32_bf16 v[12:15], v[132:135], v[188:191], v[12:15]
	v_mfma_f32_16x16x32_bf16 v[8:11], v[140:143], v[188:191], v[8:11]
	s_barrier
; #define PG8_STAGE(bufoff, gbase, voff) do { _Pragma("unroll") for (int _i = 0; _i < 2; ++_i) \
;         __builtin_amdgcn_global_load_lds((const unsigned*)((const char*)(gbase) + (voff)[_i]), (LAS unsigned*)(lds + (bufoff) + ldsw + _i * 8192), 16, 0, 0); } while (0)
; #define PG8_LDA(dst, b, h) do { _Pragma("unroll") for (int m = 0; m < 4; ++m) _Pragma("unroll") for (int k = 0; k < 2; ++k) dst[m][k] = *(const LAS bf16x8*)(lds + PG8_SA(b, h) + aoff + m * 2048 + k * 1024); } while (0)
; #define PG8_LDB(dst, b, h) do { _Pragma("unroll") for (int n = 0; n < 2; ++n) _Pragma("unroll") for (int k = 0; k < 2; ++k) dst[n][k] = *(const LAS bf16x8*)(lds + PG8_SB(b, h) + boff + n * 2048 + k * 1024); } while (0)
; #define PG8_MMA(ai, bj, At, Bt) do { __builtin_amdgcn_s_setprio(1); _Pragma("unroll") for (int m = 0; m < 4; ++m) _Pragma("unroll") for (int n = 0; n < 2; ++n) _Pragma("unroll") for (int k = 0; k < 2; ++k) \
;         acc[ai][bj][m][n] = __builtin_amdgcn_mfma_f32_16x16x32_bf16(Bt[n][k], At[m][k], acc[ai][bj][m][n], 0, 0, 0); __builtin_amdgcn_s_setprio(0); } while (0)
; #define PG8_WAIT_V(n) asm volatile("s_waitcnt vmcnt(" #n ")" ::: "memory")
; #define PG8_WAIT_L(n) asm volatile("s_waitcnt lgkmcnt(" #n ")" ::: "memory")
; #define PG8_BAR __builtin_amdgcn_s_barrier()
; #define PG8_SCHED __builtin_amdgcn_sched_barrier(0)
; template <class Epi>
; DEVI void gemm_phase(LAS unsigned char* lds, const bf16_t* gA, const bf16_t* gBt, const int lda, const int ldb, const int K, const StaticOrder S_, const Epi E) {
;     ...
;             PG8_STAGE(PG8_SB(0, 1), b2 + hstepB, voffB);
;             PG8_WAIT_V(6); PG8_BAR; PG8_MMA(1, 1, At, B1); PG8_BAR;
;             PG8_LDB(B0, 1, 0); PG8_SCHED; PG8_LDA(At, 1, 0); PG8_STAGE(PG8_SA(0, 1), a2 + hstepA, voffA);
;             PG8_WAIT_L(8); PG8_BAR; PG8_WAIT_L(0); PG8_MMA(0, 0, At, B0); PG8_BAR; PG8_SCHED;
;             PG8_LDB(B1, 1, 1); PG8_STAGE(PG8_SB(1, 0), b3, voffB);
	s_add_u32 s40, s40, s2
	s_addc_u32 s41, s41, s3
	s_add_i32 s76, s50, s20
	v_lshl_add_u64 v[224:225], s[40:41], 0, v[168:169]
	s_mov_b32 m0, s76
	v_lshl_add_u64 v[226:227], s[40:41], 0, v[172:173]
	global_load_lds_dwordx4 v[224:225], off
	s_add_i32 m0, s76, 0x2000
	s_nop 0
	global_load_lds_dwordx4 v[226:227], off
	s_waitcnt vmcnt(6)
	s_barrier
	v_mfma_f32_16x16x32_bf16 v[52:55], v[192:195], v[144:147], v[52:55]
	v_mfma_f32_16x16x32_bf16 v[48:51], v[210:213], v[144:147], v[48:51]
	v_mfma_f32_16x16x32_bf16 v[36:39], v[192:195], v[152:155], v[36:39]
	v_mfma_f32_16x16x32_bf16 v[32:35], v[210:213], v[152:155], v[32:35]
	v_mfma_f32_16x16x32_bf16 v[20:23], v[192:195], v[160:163], v[20:23]
	v_mfma_f32_16x16x32_bf16 v[16:19], v[210:213], v[160:163], v[16:19]
	v_mfma_f32_16x16x32_bf16 v[4:7], v[192:195], v[184:187], v[4:7]
	v_mfma_f32_16x16x32_bf16 v[0:3], v[210:213], v[184:187], v[0:3]
	v_mfma_f32_16x16x32_bf16 v[52:55], v[206:209], v[148:151], v[52:55]
	v_mfma_f32_16x16x32_bf16 v[48:51], v[214:217], v[148:151], v[48:51]
	v_mfma_f32_16x16x32_bf16 v[36:39], v[206:209], v[156:159], v[36:39]
	v_mfma_f32_16x16x32_bf16 v[32:35], v[214:217], v[156:159], v[32:35]
	v_mfma_f32_16x16x32_bf16 v[20:23], v[206:209], v[180:183], v[20:23]
	v_mfma_f32_16x16x32_bf16 v[16:19], v[214:217], v[180:183], v[16:19]
	v_mfma_f32_16x16x32_bf16 v[4:7], v[206:209], v[188:191], v[4:7]
	v_mfma_f32_16x16x32_bf16 v[0:3], v[214:217], v[188:191], v[0:3]
	s_add_i32 s40, 0, 0x18000
	v_add_u32_e32 v140, s40, v199
	s_barrier
	ds_read_b128 v[128:131], v140
	ds_read_b128 v[132:135], v140 offset:1024
	ds_read_b128 v[136:139], v140 offset:2048
	ds_read_b128 v[140:143], v140 offset:3072
	s_add_u32 s16, s16, s0
	s_addc_u32 s17, s17, s1
	s_mov_b32 m0, s23
	v_lshl_add_u64 v[192:193], s[16:17], 0, v[166:167]
	ds_read_b128 v[144:147], v202 offset:32768
	ds_read_b128 v[148:151], v202 offset:33792
	ds_read_b128 v[152:155], v202 offset:34816
	ds_read_b128 v[156:159], v202 offset:35840
	ds_read_b128 v[160:163], v202 offset:36864
	ds_read_b128 v[180:183], v202 offset:37888
	ds_read_b128 v[184:187], v202 offset:38912
	ds_read_b128 v[188:191], v202 offset:39936
	global_load_lds_dwordx4 v[192:193], off
	v_lshl_add_u64 v[192:193], s[16:17], 0, v[170:171]
	s_mov_b32 m0, s24
	s_nop 0
	global_load_lds_dwordx4 v[192:193], off
	s_waitcnt lgkmcnt(8)
	s_barrier
	s_waitcnt lgkmcnt(0)
	s_waitcnt lgkmcnt(0)
	v_mfma_f32_16x16x32_bf16 v[124:127], v[128:131], v[144:147], v[124:127]
	v_mfma_f32_16x16x32_bf16 v[120:123], v[136:139], v[144:147], v[120:123]
	v_mfma_f32_16x16x32_bf16 v[108:111], v[128:131], v[152:155], v[108:111]
	v_mfma_f32_16x16x32_bf16 v[104:107], v[136:139], v[152:155], v[104:107]
	v_mfma_f32_16x16x32_bf16 v[92:95], v[128:131], v[160:163], v[92:95]
	v_mfma_f32_16x16x32_bf16 v[88:91], v[136:139], v[160:163], v[88:91]
	v_mfma_f32_16x16x32_bf16 v[76:79], v[128:131], v[184:187], v[76:79]
	v_mfma_f32_16x16x32_bf16 v[72:75], v[136:139], v[184:187], v[72:75]
	v_mfma_f32_16x16x32_bf16 v[124:127], v[132:135], v[148:151], v[124:127]
	v_mfma_f32_16x16x32_bf16 v[120:123], v[140:143], v[148:151], v[120:123]
	v_mfma_f32_16x16x32_bf16 v[108:111], v[132:135], v[156:159], v[108:111]
	v_mfma_f32_16x16x32_bf16 v[104:107], v[140:143], v[156:159], v[104:107]
	v_mfma_f32_16x16x32_bf16 v[92:95], v[132:135], v[180:183], v[92:95]
	v_mfma_f32_16x16x32_bf16 v[88:91], v[140:143], v[180:183], v[88:91]
	v_mfma_f32_16x16x32_bf16 v[76:79], v[132:135], v[188:191], v[76:79]
	v_mfma_f32_16x16x32_bf16 v[72:75], v[140:143], v[188:191], v[72:75]
	s_barrier
	s_add_i32 s16, 0, 0x1c000
	s_add_i32 s17, s40, s20
	v_add_u32_e32 v205, s16, v199
	v_lshl_add_u64 v[164:165], v[164:165], 0, s[8:9]
	s_mov_b32 m0, s17
	ds_read_b128 v[192:195], v205
	ds_read_b128 v[206:209], v205 offset:1024
	ds_read_b128 v[210:213], v205 offset:2048
	ds_read_b128 v[214:217], v205 offset:3072
	global_load_lds_dwordx4 v[164:165], off
	v_lshl_add_u64 v[164:165], v[218:219], 0, s[8:9]
	s_add_i32 m0, s17, 0x2000
	s_nop 0
	global_load_lds_dwordx4 v[164:165], off
	s_barrier
; #define PG8_STAGE(bufoff, gbase, voff) do { _Pragma("unroll") for (int _i = 0; _i < 2; ++_i) \
;         __builtin_amdgcn_global_load_lds((const unsigned*)((const char*)(gbase) + (voff)[_i]), (LAS unsigned*)(lds + (bufoff) + ldsw + _i * 8192), 16, 0, 0); } while (0)
; #define PG8_LDA(dst, b, h) do { _Pragma("unroll") for (int m = 0; m < 4; ++m) _Pragma("unroll") for (int k = 0; k < 2; ++k) dst[m][k] = *(const LAS bf16x8*)(lds + PG8_SA(b, h) + aoff + m * 2048 + k * 1024); } while (0)
; #define PG8_MMA(ai, bj, At, Bt) do { __builtin_amdgcn_s_setprio(1); _Pragma("unroll") for (int m = 0; m < 4; ++m) _Pragma("unroll") for (int n = 0; n < 2; ++n) _Pragma("unroll") for (int k = 0; k < 2; ++k) \
;         acc[ai][bj][m][n] = __builtin_amdgcn_mfma_f32_16x16x32_bf16(Bt[n][k], At[m][k], acc[ai][bj][m][n], 0, 0, 0); __builtin_amdgcn_s_setprio(0); } while (0)
; #define PG8_WAIT_V(n) asm volatile("s_waitcnt vmcnt(" #n ")" ::: "memory")
; #define PG8_WAIT_L(n) asm volatile("s_waitcnt lgkmcnt(" #n ")" ::: "memory")
; #define PG8_BAR __builtin_amdgcn_s_barrier()
; #define PG8_SCHED __builtin_amdgcn_sched_barrier(0)
; template <class Epi>
; DEVI void gemm_phase(LAS unsigned char* lds, const bf16_t* gA, const bf16_t* gBt, const int lda, const int ldb, const int K, const StaticOrder S_, const Epi E) {
;     ...
;             PG8_BAR; PG8_WAIT_L(0); PG8_MMA(0, 1, At, B1); PG8_BAR;
;             PG8_LDA(At, 1, 1); PG8_STAGE(PG8_SA(1, 0), a3, voffA);
;             PG8_BAR; PG8_WAIT_L(0); PG8_MMA(1, 0, At, B0); PG8_BAR; PG8_SCHED;
;             PG8_STAGE(PG8_SB(1, 1), b3 + hstepB, voffB);
;             PG8_WAIT_V(6); PG8_BAR; PG8_MMA(1, 1, At, B1); PG8_BAR;
;         }
	s_waitcnt lgkmcnt(0)
	s_waitcnt lgkmcnt(0)
	v_mfma_f32_16x16x32_bf16 v[116:119], v[192:195], v[144:147], v[116:119]
	v_mfma_f32_16x16x32_bf16 v[112:115], v[210:213], v[144:147], v[112:115]
	v_mfma_f32_16x16x32_bf16 v[100:103], v[192:195], v[152:155], v[100:103]
	v_mfma_f32_16x16x32_bf16 v[96:99], v[210:213], v[152:155], v[96:99]
	v_mfma_f32_16x16x32_bf16 v[84:87], v[192:195], v[160:163], v[84:87]
	v_mfma_f32_16x16x32_bf16 v[80:83], v[210:213], v[160:163], v[80:83]
	v_mfma_f32_16x16x32_bf16 v[68:71], v[192:195], v[184:187], v[68:71]
	v_mfma_f32_16x16x32_bf16 v[64:67], v[210:213], v[184:187], v[64:67]
	v_mfma_f32_16x16x32_bf16 v[116:119], v[206:209], v[148:151], v[116:119]
	v_mfma_f32_16x16x32_bf16 v[112:115], v[214:217], v[148:151], v[112:115]
	v_mfma_f32_16x16x32_bf16 v[100:103], v[206:209], v[156:159], v[100:103]
	v_mfma_f32_16x16x32_bf16 v[96:99], v[214:217], v[156:159], v[96:99]
	v_mfma_f32_16x16x32_bf16 v[84:87], v[206:209], v[180:183], v[84:87]
	v_mfma_f32_16x16x32_bf16 v[80:83], v[214:217], v[180:183], v[80:83]
	v_mfma_f32_16x16x32_bf16 v[68:71], v[206:209], v[188:191], v[68:71]
	v_mfma_f32_16x16x32_bf16 v[64:67], v[214:217], v[188:191], v[64:67]
	s_mov_b32 m0, s26
	v_lshl_add_u64 v[164:165], v[220:221], 0, s[8:9]
	s_barrier
	ds_read_b128 v[144:147], v202 offset:49152
	ds_read_b128 v[148:151], v202 offset:50176
	ds_read_b128 v[152:155], v202 offset:51200
	ds_read_b128 v[156:159], v202 offset:52224
	ds_read_b128 v[160:163], v202 offset:53248
	ds_read_b128 v[180:183], v202 offset:54272
	ds_read_b128 v[184:187], v202 offset:55296
	ds_read_b128 v[188:191], v202 offset:56320
	global_load_lds_dwordx4 v[164:165], off
	v_lshl_add_u64 v[164:165], v[222:223], 0, s[8:9]
	s_mov_b32 m0, s27
	s_nop 0
	global_load_lds_dwordx4 v[164:165], off
	s_barrier
	s_waitcnt lgkmcnt(0)
	s_waitcnt lgkmcnt(0)
	v_mfma_f32_16x16x32_bf16 v[60:63], v[128:131], v[144:147], v[60:63]
	v_mfma_f32_16x16x32_bf16 v[56:59], v[136:139], v[144:147], v[56:59]
	v_mfma_f32_16x16x32_bf16 v[44:47], v[128:131], v[152:155], v[44:47]
	v_mfma_f32_16x16x32_bf16 v[40:43], v[136:139], v[152:155], v[40:43]
	v_mfma_f32_16x16x32_bf16 v[28:31], v[128:131], v[160:163], v[28:31]
	v_mfma_f32_16x16x32_bf16 v[24:27], v[136:139], v[160:163], v[24:27]
	v_mfma_f32_16x16x32_bf16 v[12:15], v[128:131], v[184:187], v[12:15]
	v_mfma_f32_16x16x32_bf16 v[8:11], v[136:139], v[184:187], v[8:11]
	v_mfma_f32_16x16x32_bf16 v[60:63], v[132:135], v[148:151], v[60:63]
	v_mfma_f32_16x16x32_bf16 v[56:59], v[140:143], v[148:151], v[56:59]
	v_mfma_f32_16x16x32_bf16 v[44:47], v[132:135], v[156:159], v[44:47]
	v_mfma_f32_16x16x32_bf16 v[40:43], v[140:143], v[156:159], v[40:43]
	v_mfma_f32_16x16x32_bf16 v[28:31], v[132:135], v[180:183], v[28:31]
	v_mfma_f32_16x16x32_bf16 v[24:27], v[140:143], v[180:183], v[24:27]
	v_mfma_f32_16x16x32_bf16 v[12:15], v[132:135], v[188:191], v[12:15]
	v_mfma_f32_16x16x32_bf16 v[8:11], v[140:143], v[188:191], v[8:11]
	s_barrier
	s_add_i32 s16, s16, s20
	v_lshl_add_u64 v[128:129], v[224:225], 0, s[8:9]
	s_mov_b32 m0, s16
	s_nop 0
	global_load_lds_dwordx4 v[128:129], off
	v_lshl_add_u64 v[128:129], v[226:227], 0, s[8:9]
	s_add_i32 m0, s16, 0x2000
	s_nop 0
	global_load_lds_dwordx4 v[128:129], off
	s_waitcnt vmcnt(6)
	s_barrier
	v_mfma_f32_16x16x32_bf16 v[52:55], v[192:195], v[144:147], v[52:55]
	v_mfma_f32_16x16x32_bf16 v[48:51], v[210:213], v[144:147], v[48:51]
	v_mfma_f32_16x16x32_bf16 v[36:39], v[192:195], v[152:155], v[36:39]
	v_mfma_f32_16x16x32_bf16 v[32:35], v[210:213], v[152:155], v[32:35]
	v_mfma_f32_16x16x32_bf16 v[20:23], v[192:195], v[160:163], v[20:23]
	v_mfma_f32_16x16x32_bf16 v[16:19], v[210:213], v[160:163], v[16:19]
	v_mfma_f32_16x16x32_bf16 v[4:7], v[192:195], v[184:187], v[4:7]
	v_mfma_f32_16x16x32_bf16 v[0:3], v[210:213], v[184:187], v[0:3]
	v_mfma_f32_16x16x32_bf16 v[52:55], v[206:209], v[148:151], v[52:55]
	v_mfma_f32_16x16x32_bf16 v[48:51], v[214:217], v[148:151], v[48:51]
	v_mfma_f32_16x16x32_bf16 v[36:39], v[206:209], v[156:159], v[36:39]
	v_mfma_f32_16x16x32_bf16 v[32:35], v[214:217], v[156:159], v[32:35]
	v_mfma_f32_16x16x32_bf16 v[20:23], v[206:209], v[180:183], v[20:23]
	v_mfma_f32_16x16x32_bf16 v[16:19], v[214:217], v[180:183], v[16:19]
	v_mfma_f32_16x16x32_bf16 v[4:7], v[206:209], v[188:191], v[4:7]
	v_mfma_f32_16x16x32_bf16 v[0:3], v[214:217], v[188:191], v[0:3]
	s_add_u32 s14, s14, 0x100
	s_addc_u32 s15, s15, 0
	s_add_u32 s70, s70, 0x100
	s_addc_u32 s71, s71, 0
	s_cmp_ge_i32 s75, s25
	s_mov_b32 s16, s75
	s_barrier
	s_cbranch_scc0 .LBB0_1574
	v_readlane_b32 s76, v238, 50
	v_readlane_b32 s77, v238, 51
	v_readlane_b32 s78, v238, 52
	v_readlane_b32 s79, v238, 53
	v_readlane_b32 s80, v238, 54
	v_readlane_b32 s81, v238, 55
	v_readlane_b32 s82, v238, 56
	v_readlane_b32 s83, v238, 57

; #define PG8_STAGE(bufoff, gbase, voff) do { _Pragma("unroll") for (int _i = 0; _i < 2; ++_i) \
;         __builtin_amdgcn_global_load_lds((const unsigned*)((const char*)(gbase) + (voff)[_i]), (LAS unsigned*)(lds + (bufoff) + ldsw + _i * 8192), 16, 0, 0); } while (0)
; #define PG8_LDA(dst, b, h) do { _Pragma("unroll") for (int m = 0; m < 4; ++m) _Pragma("unroll") for (int k = 0; k < 2; ++k) dst[m][k] = *(const LAS bf16x8*)(lds + PG8_SA(b, h) + aoff + m * 2048 + k * 1024); } while (0)
; #define PG8_LDB(dst, b, h) do { _Pragma("unroll") for (int n = 0; n < 2; ++n) _Pragma("unroll") for (int k = 0; k < 2; ++k) dst[n][k] = *(const LAS bf16x8*)(lds + PG8_SB(b, h) + boff + n * 2048 + k * 1024); } while (0)
; #define PG8_MMA(ai, bj, At, Bt) do { __builtin_amdgcn_s_setprio(1); _Pragma("unroll") for (int m = 0; m < 4; ++m) _Pragma("unroll") for (int n = 0; n < 2; ++n) _Pragma("unroll") for (int k = 0; k < 2; ++k) \
;         acc[ai][bj][m][n] = __builtin_amdgcn_mfma_f32_16x16x32_bf16(Bt[n][k], At[m][k], acc[ai][bj][m][n], 0, 0, 0); __builtin_amdgcn_s_setprio(0); } while (0)
; #define PG8_WAIT_L(n) asm volatile("s_waitcnt lgkmcnt(" #n ")" ::: "memory")
; #define PG8_BAR __builtin_amdgcn_s_barrier()
; #define PG8_SCHED __builtin_amdgcn_sched_barrier(0)
; template <class Epi>
; DEVI void gemm_phase(LAS unsigned char* lds, const bf16_t* gA, const bf16_t* gBt, const int lda, const int ldb, const int K, const StaticOrder S_, const Epi E) {
;     ...
;             const bool last = (t == nt - 2);
;             const char* a1 = cA + (size_t)(t + 1) * kstep;
;             const char* a2 = last ? nA : cA + (size_t)(t + 2) * kstep; const char* b2 = last ? nB : cB + (size_t)(t + 2) * kstep;
;             const char* a3 = a2 + kstep; const char* b3 = b2 + kstep;
;             PG8_LDB(B0, 0, 0); PG8_SCHED; PG8_LDA(At, 0, 0); PG8_STAGE(PG8_SA(1, 1), a1 + hstepA, voffA);
;             PG8_WAIT_L(8); PG8_BAR; PG8_WAIT_L(0); PG8_MMA(0, 0, At, B0); PG8_BAR; PG8_SCHED;
;             PG8_LDB(B1, 0, 1); PG8_STAGE(PG8_SB(0, 0), b2, voffB);
;             PG8_BAR; PG8_WAIT_L(0); PG8_MMA(0, 1, At, B1); PG8_BAR;
;             PG8_LDA(At, 0, 1); PG8_STAGE(PG8_SA(0, 0), a2, voffA);
;             PG8_BAR; PG8_WAIT_L(0); PG8_MMA(1, 0, At, B0); PG8_BAR; PG8_SCHED;
.LBB0_1848:
	ds_read_b128 v[128:131], v201
	ds_read_b128 v[132:135], v201 offset:1024
	ds_read_b128 v[136:139], v201 offset:2048
	ds_read_b128 v[140:143], v201 offset:3072
	s_add_i32 s64, s16, 2
	s_add_u32 s38, s14, 0x80
	s_addc_u32 s17, s15, 0
	s_cmp_eq_u32 s19, s16
	s_cselect_b32 s16, s12, s38
	s_cselect_b32 s17, s13, s17
	s_cselect_b32 s39, s41, s57
	s_cselect_b32 s38, s40, s56
	v_lshl_add_u64 v[164:165], s[14:15], 0, v[174:175]
	s_add_i32 m0, s61, 0xc000
	ds_read_b128 v[144:147], v202
	ds_read_b128 v[148:151], v202 offset:1024
	ds_read_b128 v[152:155], v202 offset:2048
	ds_read_b128 v[156:159], v202 offset:3072
	ds_read_b128 v[160:163], v202 offset:4096
	ds_read_b128 v[180:183], v202 offset:5120
	ds_read_b128 v[184:187], v202 offset:6144
	ds_read_b128 v[188:191], v202 offset:7168
	global_load_lds_dwordx4 v[164:165], off
	v_lshl_add_u64 v[164:165], s[14:15], 0, v[176:177]
	s_add_i32 m0, s61, 0xe000
	s_nop 0
	global_load_lds_dwordx4 v[164:165], off
	s_waitcnt lgkmcnt(8)
	s_barrier
	s_waitcnt lgkmcnt(0)
	s_waitcnt lgkmcnt(0)
	v_mfma_f32_16x16x32_bf16 v[124:127], v[128:131], v[144:147], v[124:127]
	v_mfma_f32_16x16x32_bf16 v[120:123], v[136:139], v[144:147], v[120:123]
	v_mfma_f32_16x16x32_bf16 v[108:111], v[128:131], v[152:155], v[108:111]
	v_mfma_f32_16x16x32_bf16 v[104:107], v[136:139], v[152:155], v[104:107]
	v_mfma_f32_16x16x32_bf16 v[92:95], v[128:131], v[160:163], v[92:95]
	v_mfma_f32_16x16x32_bf16 v[88:91], v[136:139], v[160:163], v[88:91]
	v_mfma_f32_16x16x32_bf16 v[76:79], v[128:131], v[184:187], v[76:79]
	v_mfma_f32_16x16x32_bf16 v[72:75], v[136:139], v[184:187], v[72:75]
	v_mfma_f32_16x16x32_bf16 v[124:127], v[132:135], v[148:151], v[124:127]
	v_mfma_f32_16x16x32_bf16 v[120:123], v[140:143], v[148:151], v[120:123]
	v_mfma_f32_16x16x32_bf16 v[108:111], v[132:135], v[156:159], v[108:111]
	v_mfma_f32_16x16x32_bf16 v[104:107], v[140:143], v[156:159], v[104:107]
	v_mfma_f32_16x16x32_bf16 v[92:95], v[132:135], v[180:183], v[92:95]
	v_mfma_f32_16x16x32_bf16 v[88:91], v[140:143], v[180:183], v[88:91]
	v_mfma_f32_16x16x32_bf16 v[76:79], v[132:135], v[188:191], v[76:79]
	v_mfma_f32_16x16x32_bf16 v[72:75], v[140:143], v[188:191], v[72:75]
	s_barrier
	s_add_i32 s65, s29, s20
	v_lshl_add_u64 v[164:165], s[38:39], 0, v[168:169]
	s_mov_b32 m0, s65
	ds_read_b128 v[192:195], v203
	ds_read_b128 v[206:209], v203 offset:1024
	ds_read_b128 v[210:213], v203 offset:2048
	ds_read_b128 v[214:217], v203 offset:3072
	global_load_lds_dwordx4 v[164:165], off
	v_lshl_add_u64 v[218:219], s[38:39], 0, v[172:173]
	s_add_i32 m0, s65, 0x2000
	s_nop 0
	global_load_lds_dwordx4 v[218:219], off
	s_barrier
	s_waitcnt lgkmcnt(0)
	s_waitcnt lgkmcnt(0)
	v_mfma_f32_16x16x32_bf16 v[116:119], v[192:195], v[144:147], v[116:119]
	v_mfma_f32_16x16x32_bf16 v[112:115], v[210:213], v[144:147], v[112:115]
	v_mfma_f32_16x16x32_bf16 v[100:103], v[192:195], v[152:155], v[100:103]
	v_mfma_f32_16x16x32_bf16 v[96:99], v[210:213], v[152:155], v[96:99]
	v_mfma_f32_16x16x32_bf16 v[84:87], v[192:195], v[160:163], v[84:87]
	v_mfma_f32_16x16x32_bf16 v[80:83], v[210:213], v[160:163], v[80:83]
	v_mfma_f32_16x16x32_bf16 v[68:71], v[192:195], v[184:187], v[68:71]
	v_mfma_f32_16x16x32_bf16 v[64:67], v[210:213], v[184:187], v[64:67]
	v_mfma_f32_16x16x32_bf16 v[116:119], v[206:209], v[148:151], v[116:119]
	v_mfma_f32_16x16x32_bf16 v[112:115], v[214:217], v[148:151], v[112:115]
	v_mfma_f32_16x16x32_bf16 v[100:103], v[206:209], v[156:159], v[100:103]
	v_mfma_f32_16x16x32_bf16 v[96:99], v[214:217], v[156:159], v[96:99]
	v_mfma_f32_16x16x32_bf16 v[84:87], v[206:209], v[180:183], v[84:87]
	v_mfma_f32_16x16x32_bf16 v[80:83], v[214:217], v[180:183], v[80:83]
	v_mfma_f32_16x16x32_bf16 v[68:71], v[206:209], v[188:191], v[68:71]
	v_mfma_f32_16x16x32_bf16 v[64:67], v[214:217], v[188:191], v[64:67]
	s_mov_b32 m0, s61
	v_lshl_add_u64 v[220:221], s[16:17], 0, v[166:167]
	s_barrier
	ds_read_b128 v[144:147], v202 offset:16384
	ds_read_b128 v[148:151], v202 offset:17408
	ds_read_b128 v[152:155], v202 offset:18432
	ds_read_b128 v[156:159], v202 offset:19456
	ds_read_b128 v[160:163], v202 offset:20480
	ds_read_b128 v[180:183], v202 offset:21504
	ds_read_b128 v[184:187], v202 offset:22528
	ds_read_b128 v[188:191], v202 offset:23552
	global_load_lds_dwordx4 v[220:221], off
	v_lshl_add_u64 v[222:223], s[16:17], 0, v[170:171]
	s_mov_b32 m0, s22
	s_nop 0
	global_load_lds_dwordx4 v[222:223], off
	s_barrier
	s_waitcnt lgkmcnt(0)
	s_waitcnt lgkmcnt(0)
	v_mfma_f32_16x16x32_bf16 v[60:63], v[128:131], v[144:147], v[60:63]
	v_mfma_f32_16x16x32_bf16 v[56:59], v[136:139], v[144:147], v[56:59]
	v_mfma_f32_16x16x32_bf16 v[44:47], v[128:131], v[152:155], v[44:47]
	v_mfma_f32_16x16x32_bf16 v[40:43], v[136:139], v[152:155], v[40:43]
	v_mfma_f32_16x16x32_bf16 v[28:31], v[128:131], v[160:163], v[28:31]
	v_mfma_f32_16x16x32_bf16 v[24:27], v[136:139], v[160:163], v[24:27]
	v_mfma_f32_16x16x32_bf16 v[12:15], v[128:131], v[184:187], v[12:15]
	v_mfma_f32_16x16x32_bf16 v[8:11], v[136:139], v[184:187], v[8:11]
	v_mfma_f32_16x16x32_bf16 v[60:63], v[132:135], v[148:151], v[60:63]
	v_mfma_f32_16x16x32_bf16 v[56:59], v[140:143], v[148:151], v[56:59]
	v_mfma_f32_16x16x32_bf16 v[44:47], v[132:135], v[156:159], v[44:47]
	v_mfma_f32_16x16x32_bf16 v[40:43], v[140:143], v[156:159], v[40:43]
	v_mfma_f32_16x16x32_bf16 v[28:31], v[132:135], v[180:183], v[28:31]
	v_mfma_f32_16x16x32_bf16 v[24:27], v[140:143], v[180:183], v[24:27]
	v_mfma_f32_16x16x32_bf16 v[12:15], v[132:135], v[188:191], v[12:15]
	v_mfma_f32_16x16x32_bf16 v[8:11], v[140:143], v[188:191], v[8:11]
	s_barrier
; #define PG8_STAGE(bufoff, gbase, voff) do { _Pragma("unroll") for (int _i = 0; _i < 2; ++_i) \
;         __builtin_amdgcn_global_load_lds((const unsigned*)((const char*)(gbase) + (voff)[_i]), (LAS unsigned*)(lds + (bufoff) + ldsw + _i * 8192), 16, 0, 0); } while (0)
; #define PG8_LDA(dst, b, h) do { _Pragma("unroll") for (int m = 0; m < 4; ++m) _Pragma("unroll") for (int k = 0; k < 2; ++k) dst[m][k] = *(const LAS bf16x8*)(lds + PG8_SA(b, h) + aoff + m * 2048 + k * 1024); } while (0)
; #define PG8_LDB(dst, b, h) do { _Pragma("unroll") for (int n = 0; n < 2; ++n) _Pragma("unroll") for (int k = 0; k < 2; ++k) dst[n][k] = *(const LAS bf16x8*)(lds + PG8_SB(b, h) + boff + n * 2048 + k * 1024); } while (0)
; #define PG8_MMA(ai, bj, At, Bt) do { __builtin_amdgcn_s_setprio(1); _Pragma("unroll") for (int m = 0; m < 4; ++m) _Pragma("unroll") for (int n = 0; n < 2; ++n) _Pragma("unroll") for (int k = 0; k < 2; ++k) \
;         acc[ai][bj][m][n] = __builtin_amdgcn_mfma_f32_16x16x32_bf16(Bt[n][k], At[m][k], acc[ai][bj][m][n], 0, 0, 0); __builtin_amdgcn_s_setprio(0); } while (0)
; #define PG8_WAIT_V(n) asm volatile("s_waitcnt vmcnt(" #n ")" ::: "memory")
; #define PG8_WAIT_L(n) asm volatile("s_waitcnt lgkmcnt(" #n ")" ::: "memory")
; #define PG8_BAR __builtin_amdgcn_s_barrier()
; #define PG8_SCHED __builtin_amdgcn_sched_barrier(0)
; template <class Epi>
; DEVI void gemm_phase(LAS unsigned char* lds, const bf16_t* gA, const bf16_t* gBt, const int lda, const int ldb, const int K, const StaticOrder S_, const Epi E) {
;     ...
;             PG8_STAGE(PG8_SB(0, 1), b2 + hstepB, voffB);
;             PG8_WAIT_V(6); PG8_BAR; PG8_MMA(1, 1, At, B1); PG8_BAR;
;             PG8_LDB(B0, 1, 0); PG8_SCHED; PG8_LDA(At, 1, 0); PG8_STAGE(PG8_SA(0, 1), a2 + hstepA, voffA);
;             PG8_WAIT_L(8); PG8_BAR; PG8_WAIT_L(0); PG8_MMA(0, 0, At, B0); PG8_BAR; PG8_SCHED;
;             PG8_LDB(B1, 1, 1); PG8_STAGE(PG8_SB(1, 0), b3, voffB);
	s_add_u32 s38, s38, s2
	s_addc_u32 s39, s39, s3
	s_add_i32 s65, s50, s20
	v_lshl_add_u64 v[224:225], s[38:39], 0, v[168:169]
	s_mov_b32 m0, s65
	v_lshl_add_u64 v[226:227], s[38:39], 0, v[172:173]
	global_load_lds_dwordx4 v[224:225], off
	s_add_i32 m0, s65, 0x2000
	s_nop 0
	global_load_lds_dwordx4 v[226:227], off
	s_waitcnt vmcnt(6)
	s_barrier
	v_mfma_f32_16x16x32_bf16 v[52:55], v[192:195], v[144:147], v[52:55]
	v_mfma_f32_16x16x32_bf16 v[48:51], v[210:213], v[144:147], v[48:51]
	v_mfma_f32_16x16x32_bf16 v[36:39], v[192:195], v[152:155], v[36:39]
	v_mfma_f32_16x16x32_bf16 v[32:35], v[210:213], v[152:155], v[32:35]
	v_mfma_f32_16x16x32_bf16 v[20:23], v[192:195], v[160:163], v[20:23]
	v_mfma_f32_16x16x32_bf16 v[16:19], v[210:213], v[160:163], v[16:19]
	v_mfma_f32_16x16x32_bf16 v[4:7], v[192:195], v[184:187], v[4:7]
	v_mfma_f32_16x16x32_bf16 v[0:3], v[210:213], v[184:187], v[0:3]
	v_mfma_f32_16x16x32_bf16 v[52:55], v[206:209], v[148:151], v[52:55]
	v_mfma_f32_16x16x32_bf16 v[48:51], v[214:217], v[148:151], v[48:51]
	v_mfma_f32_16x16x32_bf16 v[36:39], v[206:209], v[156:159], v[36:39]
	v_mfma_f32_16x16x32_bf16 v[32:35], v[214:217], v[156:159], v[32:35]
	v_mfma_f32_16x16x32_bf16 v[20:23], v[206:209], v[180:183], v[20:23]
	v_mfma_f32_16x16x32_bf16 v[16:19], v[214:217], v[180:183], v[16:19]
	v_mfma_f32_16x16x32_bf16 v[4:7], v[206:209], v[188:191], v[4:7]
	v_mfma_f32_16x16x32_bf16 v[0:3], v[214:217], v[188:191], v[0:3]
	s_add_i32 s38, 0, 0x18000
	v_add_u32_e32 v140, s38, v199
	s_barrier
	ds_read_b128 v[128:131], v140
	ds_read_b128 v[132:135], v140 offset:1024
	ds_read_b128 v[136:139], v140 offset:2048
	ds_read_b128 v[140:143], v140 offset:3072
	s_add_u32 s16, s16, s0
	s_addc_u32 s17, s17, s1
	s_mov_b32 m0, s23
	v_lshl_add_u64 v[192:193], s[16:17], 0, v[166:167]
	ds_read_b128 v[144:147], v202 offset:32768
	ds_read_b128 v[148:151], v202 offset:33792
	ds_read_b128 v[152:155], v202 offset:34816
	ds_read_b128 v[156:159], v202 offset:35840
	ds_read_b128 v[160:163], v202 offset:36864
	ds_read_b128 v[180:183], v202 offset:37888
	ds_read_b128 v[184:187], v202 offset:38912
	ds_read_b128 v[188:191], v202 offset:39936
	global_load_lds_dwordx4 v[192:193], off
	v_lshl_add_u64 v[192:193], s[16:17], 0, v[170:171]
	s_mov_b32 m0, s24
	s_nop 0
	global_load_lds_dwordx4 v[192:193], off
	s_waitcnt lgkmcnt(8)
	s_barrier
	s_waitcnt lgkmcnt(0)
	s_waitcnt lgkmcnt(0)
	v_mfma_f32_16x16x32_bf16 v[124:127], v[128:131], v[144:147], v[124:127]
	v_mfma_f32_16x16x32_bf16 v[120:123], v[136:139], v[144:147], v[120:123]
	v_mfma_f32_16x16x32_bf16 v[108:111], v[128:131], v[152:155], v[108:111]
	v_mfma_f32_16x16x32_bf16 v[104:107], v[136:139], v[152:155], v[104:107]
	v_mfma_f32_16x16x32_bf16 v[92:95], v[128:131], v[160:163], v[92:95]
	v_mfma_f32_16x16x32_bf16 v[88:91], v[136:139], v[160:163], v[88:91]
	v_mfma_f32_16x16x32_bf16 v[76:79], v[128:131], v[184:187], v[76:79]
	v_mfma_f32_16x16x32_bf16 v[72:75], v[136:139], v[184:187], v[72:75]
	v_mfma_f32_16x16x32_bf16 v[124:127], v[132:135], v[148:151], v[124:127]
	v_mfma_f32_16x16x32_bf16 v[120:123], v[140:143], v[148:151], v[120:123]
	v_mfma_f32_16x16x32_bf16 v[108:111], v[132:135], v[156:159], v[108:111]
	v_mfma_f32_16x16x32_bf16 v[104:107], v[140:143], v[156:159], v[104:107]
	v_mfma_f32_16x16x32_bf16 v[92:95], v[132:135], v[180:183], v[92:95]
	v_mfma_f32_16x16x32_bf16 v[88:91], v[140:143], v[180:183], v[88:91]
	v_mfma_f32_16x16x32_bf16 v[76:79], v[132:135], v[188:191], v[76:79]
	v_mfma_f32_16x16x32_bf16 v[72:75], v[140:143], v[188:191], v[72:75]
	s_barrier
	s_add_i32 s16, 0, 0x1c000
	s_add_i32 s17, s38, s20
	v_add_u32_e32 v205, s16, v199
	v_lshl_add_u64 v[164:165], v[164:165], 0, s[8:9]
	s_mov_b32 m0, s17
	ds_read_b128 v[192:195], v205
	ds_read_b128 v[206:209], v205 offset:1024
	ds_read_b128 v[210:213], v205 offset:2048
	ds_read_b128 v[214:217], v205 offset:3072
	global_load_lds_dwordx4 v[164:165], off
	v_lshl_add_u64 v[164:165], v[218:219], 0, s[8:9]
	s_add_i32 m0, s17, 0x2000
	s_nop 0
	global_load_lds_dwordx4 v[164:165], off
	s_barrier
; #define PG8_STAGE(bufoff, gbase, voff) do { _Pragma("unroll") for (int _i = 0; _i < 2; ++_i) \
;         __builtin_amdgcn_global_load_lds((const unsigned*)((const char*)(gbase) + (voff)[_i]), (LAS unsigned*)(lds + (bufoff) + ldsw + _i * 8192), 16, 0, 0); } while (0)
; #define PG8_LDA(dst, b, h) do { _Pragma("unroll") for (int m = 0; m < 4; ++m) _Pragma("unroll") for (int k = 0; k < 2; ++k) dst[m][k] = *(const LAS bf16x8*)(lds + PG8_SA(b, h) + aoff + m * 2048 + k * 1024); } while (0)
; #define PG8_MMA(ai, bj, At, Bt) do { __builtin_amdgcn_s_setprio(1); _Pragma("unroll") for (int m = 0; m < 4; ++m) _Pragma("unroll") for (int n = 0; n < 2; ++n) _Pragma("unroll") for (int k = 0; k < 2; ++k) \
;         acc[ai][bj][m][n] = __builtin_amdgcn_mfma_f32_16x16x32_bf16(Bt[n][k], At[m][k], acc[ai][bj][m][n], 0, 0, 0); __builtin_amdgcn_s_setprio(0); } while (0)
; #define PG8_WAIT_V(n) asm volatile("s_waitcnt vmcnt(" #n ")" ::: "memory")
; #define PG8_WAIT_L(n) asm volatile("s_waitcnt lgkmcnt(" #n ")" ::: "memory")
; #define PG8_BAR __builtin_amdgcn_s_barrier()
; #define PG8_SCHED __builtin_amdgcn_sched_barrier(0)
; template <class Epi>
; DEVI void gemm_phase(LAS unsigned char* lds, const bf16_t* gA, const bf16_t* gBt, const int lda, const int ldb, const int K, const StaticOrder S_, const Epi E) {
;     ...
;             PG8_BAR; PG8_WAIT_L(0); PG8_MMA(0, 1, At, B1); PG8_BAR;
;             PG8_LDA(At, 1, 1); PG8_STAGE(PG8_SA(1, 0), a3, voffA);
;             PG8_BAR; PG8_WAIT_L(0); PG8_MMA(1, 0, At, B0); PG8_BAR; PG8_SCHED;
;             PG8_STAGE(PG8_SB(1, 1), b3 + hstepB, voffB);
;             PG8_WAIT_V(6); PG8_BAR; PG8_MMA(1, 1, At, B1); PG8_BAR;
;         }
	s_waitcnt lgkmcnt(0)
	s_waitcnt lgkmcnt(0)
	v_mfma_f32_16x16x32_bf16 v[116:119], v[192:195], v[144:147], v[116:119]
	v_mfma_f32_16x16x32_bf16 v[112:115], v[210:213], v[144:147], v[112:115]
	v_mfma_f32_16x16x32_bf16 v[100:103], v[192:195], v[152:155], v[100:103]
	v_mfma_f32_16x16x32_bf16 v[96:99], v[210:213], v[152:155], v[96:99]
	v_mfma_f32_16x16x32_bf16 v[84:87], v[192:195], v[160:163], v[84:87]
	v_mfma_f32_16x16x32_bf16 v[80:83], v[210:213], v[160:163], v[80:83]
	v_mfma_f32_16x16x32_bf16 v[68:71], v[192:195], v[184:187], v[68:71]
	v_mfma_f32_16x16x32_bf16 v[64:67], v[210:213], v[184:187], v[64:67]
	v_mfma_f32_16x16x32_bf16 v[116:119], v[206:209], v[148:151], v[116:119]
	v_mfma_f32_16x16x32_bf16 v[112:115], v[214:217], v[148:151], v[112:115]
	v_mfma_f32_16x16x32_bf16 v[100:103], v[206:209], v[156:159], v[100:103]
	v_mfma_f32_16x16x32_bf16 v[96:99], v[214:217], v[156:159], v[96:99]
	v_mfma_f32_16x16x32_bf16 v[84:87], v[206:209], v[180:183], v[84:87]
	v_mfma_f32_16x16x32_bf16 v[80:83], v[214:217], v[180:183], v[80:83]
	v_mfma_f32_16x16x32_bf16 v[68:71], v[206:209], v[188:191], v[68:71]
	v_mfma_f32_16x16x32_bf16 v[64:67], v[214:217], v[188:191], v[64:67]
	s_mov_b32 m0, s26
	v_lshl_add_u64 v[164:165], v[220:221], 0, s[8:9]
	s_barrier
	ds_read_b128 v[144:147], v202 offset:49152
	ds_read_b128 v[148:151], v202 offset:50176
	ds_read_b128 v[152:155], v202 offset:51200
	ds_read_b128 v[156:159], v202 offset:52224
	ds_read_b128 v[160:163], v202 offset:53248
	ds_read_b128 v[180:183], v202 offset:54272
	ds_read_b128 v[184:187], v202 offset:55296
	ds_read_b128 v[188:191], v202 offset:56320
	global_load_lds_dwordx4 v[164:165], off
	v_lshl_add_u64 v[164:165], v[222:223], 0, s[8:9]
	s_mov_b32 m0, s27
	s_nop 0
	global_load_lds_dwordx4 v[164:165], off
	s_barrier
	s_waitcnt lgkmcnt(0)
	s_waitcnt lgkmcnt(0)
	v_mfma_f32_16x16x32_bf16 v[60:63], v[128:131], v[144:147], v[60:63]
	v_mfma_f32_16x16x32_bf16 v[56:59], v[136:139], v[144:147], v[56:59]
	v_mfma_f32_16x16x32_bf16 v[44:47], v[128:131], v[152:155], v[44:47]
	v_mfma_f32_16x16x32_bf16 v[40:43], v[136:139], v[152:155], v[40:43]
	v_mfma_f32_16x16x32_bf16 v[28:31], v[128:131], v[160:163], v[28:31]
	v_mfma_f32_16x16x32_bf16 v[24:27], v[136:139], v[160:163], v[24:27]
	v_mfma_f32_16x16x32_bf16 v[12:15], v[128:131], v[184:187], v[12:15]
	v_mfma_f32_16x16x32_bf16 v[8:11], v[136:139], v[184:187], v[8:11]
	v_mfma_f32_16x16x32_bf16 v[60:63], v[132:135], v[148:151], v[60:63]
	v_mfma_f32_16x16x32_bf16 v[56:59], v[140:143], v[148:151], v[56:59]
	v_mfma_f32_16x16x32_bf16 v[44:47], v[132:135], v[156:159], v[44:47]
	v_mfma_f32_16x16x32_bf16 v[40:43], v[140:143], v[156:159], v[40:43]
	v_mfma_f32_16x16x32_bf16 v[28:31], v[132:135], v[180:183], v[28:31]
	v_mfma_f32_16x16x32_bf16 v[24:27], v[140:143], v[180:183], v[24:27]
	v_mfma_f32_16x16x32_bf16 v[12:15], v[132:135], v[188:191], v[12:15]
	v_mfma_f32_16x16x32_bf16 v[8:11], v[140:143], v[188:191], v[8:11]
	s_barrier
	s_add_i32 s16, s16, s20
	v_lshl_add_u64 v[128:129], v[224:225], 0, s[8:9]
	s_mov_b32 m0, s16
	s_nop 0
	global_load_lds_dwordx4 v[128:129], off
	v_lshl_add_u64 v[128:129], v[226:227], 0, s[8:9]
	s_add_i32 m0, s16, 0x2000
	s_nop 0
	global_load_lds_dwordx4 v[128:129], off
	s_waitcnt vmcnt(6)
	s_barrier
	v_mfma_f32_16x16x32_bf16 v[52:55], v[192:195], v[144:147], v[52:55]
	v_mfma_f32_16x16x32_bf16 v[48:51], v[210:213], v[144:147], v[48:51]
	v_mfma_f32_16x16x32_bf16 v[36:39], v[192:195], v[152:155], v[36:39]
	v_mfma_f32_16x16x32_bf16 v[32:35], v[210:213], v[152:155], v[32:35]
	v_mfma_f32_16x16x32_bf16 v[20:23], v[192:195], v[160:163], v[20:23]
	v_mfma_f32_16x16x32_bf16 v[16:19], v[210:213], v[160:163], v[16:19]
	v_mfma_f32_16x16x32_bf16 v[4:7], v[192:195], v[184:187], v[4:7]
	v_mfma_f32_16x16x32_bf16 v[0:3], v[210:213], v[184:187], v[0:3]
	v_mfma_f32_16x16x32_bf16 v[52:55], v[206:209], v[148:151], v[52:55]
	v_mfma_f32_16x16x32_bf16 v[48:51], v[214:217], v[148:151], v[48:51]
	v_mfma_f32_16x16x32_bf16 v[36:39], v[206:209], v[156:159], v[36:39]
	v_mfma_f32_16x16x32_bf16 v[32:35], v[214:217], v[156:159], v[32:35]
	v_mfma_f32_16x16x32_bf16 v[20:23], v[206:209], v[180:183], v[20:23]
	v_mfma_f32_16x16x32_bf16 v[16:19], v[214:217], v[180:183], v[16:19]
	v_mfma_f32_16x16x32_bf16 v[4:7], v[206:209], v[188:191], v[4:7]
	v_mfma_f32_16x16x32_bf16 v[0:3], v[214:217], v[188:191], v[0:3]
	s_add_u32 s14, s14, 0x100
	s_addc_u32 s15, s15, 0
	s_add_u32 s56, s56, 0x100
	s_addc_u32 s57, s57, 0
	s_cmp_ge_i32 s64, s25
	s_mov_b32 s16, s64
	s_barrier
	s_cbranch_scc0 .LBB0_1848
	v_readlane_b32 s64, v241, 0
	v_readlane_b32 s66, v241, 2
	v_readlane_b32 s65, v241, 1
	v_readlane_b32 s67, v241, 3

; #define PG8_STAGE(bufoff, gbase, voff) do { _Pragma("unroll") for (int _i = 0; _i < 2; ++_i) \
;         __builtin_amdgcn_global_load_lds((const unsigned*)((const char*)(gbase) + (voff)[_i]), (LAS unsigned*)(lds + (bufoff) + ldsw + _i * 8192), 16, 0, 0); } while (0)
; #define PG8_LDA(dst, b, h) do { _Pragma("unroll") for (int m = 0; m < 4; ++m) _Pragma("unroll") for (int k = 0; k < 2; ++k) dst[m][k] = *(const LAS bf16x8*)(lds + PG8_SA(b, h) + aoff + m * 2048 + k * 1024); } while (0)
; #define PG8_LDB(dst, b, h) do { _Pragma("unroll") for (int n = 0; n < 2; ++n) _Pragma("unroll") for (int k = 0; k < 2; ++k) dst[n][k] = *(const LAS bf16x8*)(lds + PG8_SB(b, h) + boff + n * 2048 + k * 1024); } while (0)
; #define PG8_MMA(ai, bj, At, Bt) do { __builtin_amdgcn_s_setprio(1); _Pragma("unroll") for (int m = 0; m < 4; ++m) _Pragma("unroll") for (int n = 0; n < 2; ++n) _Pragma("unroll") for (int k = 0; k < 2; ++k) \
;         acc[ai][bj][m][n] = __builtin_amdgcn_mfma_f32_16x16x32_bf16(Bt[n][k], At[m][k], acc[ai][bj][m][n], 0, 0, 0); __builtin_amdgcn_s_setprio(0); } while (0)
; #define PG8_WAIT_L(n) asm volatile("s_waitcnt lgkmcnt(" #n ")" ::: "memory")
; #define PG8_BAR __builtin_amdgcn_s_barrier()
; #define PG8_SCHED __builtin_amdgcn_sched_barrier(0)
; template <class Epi>
; DEVI void gemm_phase(LAS unsigned char* lds, const bf16_t* gA, const bf16_t* gBt, const int lda, const int ldb, const int K, const StaticOrder S_, const Epi E) {
;     ...
;             const bool last = (t == nt - 2);
;             const char* a1 = cA + (size_t)(t + 1) * kstep;
;             const char* a2 = last ? nA : cA + (size_t)(t + 2) * kstep; const char* b2 = last ? nB : cB + (size_t)(t + 2) * kstep;
;             const char* a3 = a2 + kstep; const char* b3 = b2 + kstep;
;             PG8_LDB(B0, 0, 0); PG8_SCHED; PG8_LDA(At, 0, 0); PG8_STAGE(PG8_SA(1, 1), a1 + hstepA, voffA);
;             PG8_WAIT_L(8); PG8_BAR; PG8_WAIT_L(0); PG8_MMA(0, 0, At, B0); PG8_BAR; PG8_SCHED;
;             PG8_LDB(B1, 0, 1); PG8_STAGE(PG8_SB(0, 0), b2, voffB);
;             PG8_BAR; PG8_WAIT_L(0); PG8_MMA(0, 1, At, B1); PG8_BAR;
;             PG8_LDA(At, 0, 1); PG8_STAGE(PG8_SA(0, 0), a2, voffA);
;             PG8_BAR; PG8_WAIT_L(0); PG8_MMA(1, 0, At, B0); PG8_BAR; PG8_SCHED;
.LBB0_1980:
	ds_read_b128 v[160:163], v153
	ds_read_b128 v[164:167], v153 offset:1024
	ds_read_b128 v[168:171], v153 offset:2048
	ds_read_b128 v[172:175], v153 offset:3072
	s_add_i32 s70, s16, 2
	s_add_u32 s38, s14, 0x80
	s_addc_u32 s17, s15, 0
	s_cmp_eq_u32 s26, s16
	s_cselect_b32 s16, s54, s38
	s_cselect_b32 s17, s55, s17
	s_cselect_b32 s39, s57, s61
	s_cselect_b32 s38, s56, s60
	v_lshl_add_u64 v[144:145], s[14:15], 0, v[138:139]
	s_add_i32 m0, s19, 0xc000
	ds_read_b128 v[176:179], v154
	ds_read_b128 v[180:183], v154 offset:1024
	ds_read_b128 v[184:187], v154 offset:2048
	ds_read_b128 v[188:191], v154 offset:3072
	ds_read_b128 v[192:195], v154 offset:4096
	ds_read_b128 v[198:201], v154 offset:5120
	ds_read_b128 v[202:205], v154 offset:6144
	ds_read_b128 v[206:209], v154 offset:7168
	global_load_lds_dwordx4 v[144:145], off
	v_lshl_add_u64 v[144:145], s[14:15], 0, v[140:141]
	s_add_i32 m0, s19, 0xe000
	s_nop 0
	global_load_lds_dwordx4 v[144:145], off
	s_waitcnt lgkmcnt(8)
	s_barrier
	s_waitcnt lgkmcnt(0)
	s_waitcnt lgkmcnt(0)
	v_mfma_f32_16x16x32_bf16 v[124:127], v[160:163], v[176:179], v[124:127]
	v_mfma_f32_16x16x32_bf16 v[120:123], v[168:171], v[176:179], v[120:123]
	v_mfma_f32_16x16x32_bf16 v[108:111], v[160:163], v[184:187], v[108:111]
	v_mfma_f32_16x16x32_bf16 v[104:107], v[168:171], v[184:187], v[104:107]
	v_mfma_f32_16x16x32_bf16 v[92:95], v[160:163], v[192:195], v[92:95]
	v_mfma_f32_16x16x32_bf16 v[88:91], v[168:171], v[192:195], v[88:91]
	v_mfma_f32_16x16x32_bf16 v[76:79], v[160:163], v[202:205], v[76:79]
	v_mfma_f32_16x16x32_bf16 v[72:75], v[168:171], v[202:205], v[72:75]
	v_mfma_f32_16x16x32_bf16 v[124:127], v[164:167], v[180:183], v[124:127]
	v_mfma_f32_16x16x32_bf16 v[120:123], v[172:175], v[180:183], v[120:123]
	v_mfma_f32_16x16x32_bf16 v[108:111], v[164:167], v[188:191], v[108:111]
	v_mfma_f32_16x16x32_bf16 v[104:107], v[172:175], v[188:191], v[104:107]
	v_mfma_f32_16x16x32_bf16 v[92:95], v[164:167], v[198:201], v[92:95]
	v_mfma_f32_16x16x32_bf16 v[88:91], v[172:175], v[198:201], v[88:91]
	v_mfma_f32_16x16x32_bf16 v[76:79], v[164:167], v[206:209], v[76:79]
	v_mfma_f32_16x16x32_bf16 v[72:75], v[172:175], v[206:209], v[72:75]
	s_barrier
	s_add_i32 s71, s31, s18
	v_lshl_add_u64 v[144:145], s[38:39], 0, v[130:131]
	s_mov_b32 m0, s71
	ds_read_b128 v[210:213], v155
	ds_read_b128 v[214:217], v155 offset:1024
	ds_read_b128 v[218:221], v155 offset:2048
	ds_read_b128 v[222:225], v155 offset:3072
	global_load_lds_dwordx4 v[144:145], off
	v_lshl_add_u64 v[226:227], s[38:39], 0, v[134:135]
	s_add_i32 m0, s71, 0x2000
	s_nop 0
	global_load_lds_dwordx4 v[226:227], off
	s_barrier
	s_waitcnt lgkmcnt(0)
	s_waitcnt lgkmcnt(0)
	v_mfma_f32_16x16x32_bf16 v[116:119], v[210:213], v[176:179], v[116:119]
	v_mfma_f32_16x16x32_bf16 v[112:115], v[218:221], v[176:179], v[112:115]
	v_mfma_f32_16x16x32_bf16 v[100:103], v[210:213], v[184:187], v[100:103]
	v_mfma_f32_16x16x32_bf16 v[96:99], v[218:221], v[184:187], v[96:99]
	v_mfma_f32_16x16x32_bf16 v[84:87], v[210:213], v[192:195], v[84:87]
	v_mfma_f32_16x16x32_bf16 v[80:83], v[218:221], v[192:195], v[80:83]
	v_mfma_f32_16x16x32_bf16 v[68:71], v[210:213], v[202:205], v[68:71]
	v_mfma_f32_16x16x32_bf16 v[64:67], v[218:221], v[202:205], v[64:67]
	v_mfma_f32_16x16x32_bf16 v[116:119], v[214:217], v[180:183], v[116:119]
	v_mfma_f32_16x16x32_bf16 v[112:115], v[222:225], v[180:183], v[112:115]
	v_mfma_f32_16x16x32_bf16 v[100:103], v[214:217], v[188:191], v[100:103]
	v_mfma_f32_16x16x32_bf16 v[96:99], v[222:225], v[188:191], v[96:99]
	v_mfma_f32_16x16x32_bf16 v[84:87], v[214:217], v[198:201], v[84:87]
	v_mfma_f32_16x16x32_bf16 v[80:83], v[222:225], v[198:201], v[80:83]
	v_mfma_f32_16x16x32_bf16 v[68:71], v[214:217], v[206:209], v[68:71]
	v_mfma_f32_16x16x32_bf16 v[64:67], v[222:225], v[206:209], v[64:67]
	s_mov_b32 m0, s19
	v_lshl_add_u64 v[228:229], s[16:17], 0, v[128:129]
	s_barrier
	ds_read_b128 v[176:179], v154 offset:16384
	ds_read_b128 v[180:183], v154 offset:17408
	ds_read_b128 v[184:187], v154 offset:18432
	ds_read_b128 v[188:191], v154 offset:19456
	ds_read_b128 v[192:195], v154 offset:20480
	ds_read_b128 v[198:201], v154 offset:21504
	ds_read_b128 v[202:205], v154 offset:22528
	ds_read_b128 v[206:209], v154 offset:23552
	global_load_lds_dwordx4 v[228:229], off
	v_lshl_add_u64 v[230:231], s[16:17], 0, v[132:133]
	s_mov_b32 m0, s20
	s_nop 0
	global_load_lds_dwordx4 v[230:231], off
	s_barrier
	s_waitcnt lgkmcnt(0)
	s_waitcnt lgkmcnt(0)
	v_mfma_f32_16x16x32_bf16 v[60:63], v[160:163], v[176:179], v[60:63]
	v_mfma_f32_16x16x32_bf16 v[56:59], v[168:171], v[176:179], v[56:59]
	v_mfma_f32_16x16x32_bf16 v[44:47], v[160:163], v[184:187], v[44:47]
	v_mfma_f32_16x16x32_bf16 v[40:43], v[168:171], v[184:187], v[40:43]
	v_mfma_f32_16x16x32_bf16 v[28:31], v[160:163], v[192:195], v[28:31]
	v_mfma_f32_16x16x32_bf16 v[24:27], v[168:171], v[192:195], v[24:27]
	v_mfma_f32_16x16x32_bf16 v[12:15], v[160:163], v[202:205], v[12:15]
	v_mfma_f32_16x16x32_bf16 v[8:11], v[168:171], v[202:205], v[8:11]
	v_mfma_f32_16x16x32_bf16 v[60:63], v[164:167], v[180:183], v[60:63]
	v_mfma_f32_16x16x32_bf16 v[56:59], v[172:175], v[180:183], v[56:59]
	v_mfma_f32_16x16x32_bf16 v[44:47], v[164:167], v[188:191], v[44:47]
	v_mfma_f32_16x16x32_bf16 v[40:43], v[172:175], v[188:191], v[40:43]
	v_mfma_f32_16x16x32_bf16 v[28:31], v[164:167], v[198:201], v[28:31]
	v_mfma_f32_16x16x32_bf16 v[24:27], v[172:175], v[198:201], v[24:27]
	v_mfma_f32_16x16x32_bf16 v[12:15], v[164:167], v[206:209], v[12:15]
	v_mfma_f32_16x16x32_bf16 v[8:11], v[172:175], v[206:209], v[8:11]
	s_barrier
; #define PG8_STAGE(bufoff, gbase, voff) do { _Pragma("unroll") for (int _i = 0; _i < 2; ++_i) \
;         __builtin_amdgcn_global_load_lds((const unsigned*)((const char*)(gbase) + (voff)[_i]), (LAS unsigned*)(lds + (bufoff) + ldsw + _i * 8192), 16, 0, 0); } while (0)
; #define PG8_LDA(dst, b, h) do { _Pragma("unroll") for (int m = 0; m < 4; ++m) _Pragma("unroll") for (int k = 0; k < 2; ++k) dst[m][k] = *(const LAS bf16x8*)(lds + PG8_SA(b, h) + aoff + m * 2048 + k * 1024); } while (0)
; #define PG8_LDB(dst, b, h) do { _Pragma("unroll") for (int n = 0; n < 2; ++n) _Pragma("unroll") for (int k = 0; k < 2; ++k) dst[n][k] = *(const LAS bf16x8*)(lds + PG8_SB(b, h) + boff + n * 2048 + k * 1024); } while (0)
; #define PG8_MMA(ai, bj, At, Bt) do { __builtin_amdgcn_s_setprio(1); _Pragma("unroll") for (int m = 0; m < 4; ++m) _Pragma("unroll") for (int n = 0; n < 2; ++n) _Pragma("unroll") for (int k = 0; k < 2; ++k) \
;         acc[ai][bj][m][n] = __builtin_amdgcn_mfma_f32_16x16x32_bf16(Bt[n][k], At[m][k], acc[ai][bj][m][n], 0, 0, 0); __builtin_amdgcn_s_setprio(0); } while (0)
; #define PG8_WAIT_V(n) asm volatile("s_waitcnt vmcnt(" #n ")" ::: "memory")
; #define PG8_WAIT_L(n) asm volatile("s_waitcnt lgkmcnt(" #n ")" ::: "memory")
; #define PG8_BAR __builtin_amdgcn_s_barrier()
; #define PG8_SCHED __builtin_amdgcn_sched_barrier(0)
; template <class Epi>
; DEVI void gemm_phase(LAS unsigned char* lds, const bf16_t* gA, const bf16_t* gBt, const int lda, const int ldb, const int K, const StaticOrder S_, const Epi E) {
;     ...
;             PG8_STAGE(PG8_SB(0, 1), b2 + hstepB, voffB);
;             PG8_WAIT_V(6); PG8_BAR; PG8_MMA(1, 1, At, B1); PG8_BAR;
;             PG8_LDB(B0, 1, 0); PG8_SCHED; PG8_LDA(At, 1, 0); PG8_STAGE(PG8_SA(0, 1), a2 + hstepA, voffA);
;             PG8_WAIT_L(8); PG8_BAR; PG8_WAIT_L(0); PG8_MMA(0, 0, At, B0); PG8_BAR; PG8_SCHED;
;             PG8_LDB(B1, 1, 1); PG8_STAGE(PG8_SB(1, 0), b3, voffB);
	s_add_u32 s38, s38, s2
	s_addc_u32 s39, s39, s3
	s_add_i32 s71, s48, s18
	v_lshl_add_u64 v[232:233], s[38:39], 0, v[130:131]
	s_mov_b32 m0, s71
	v_lshl_add_u64 v[234:235], s[38:39], 0, v[134:135]
	global_load_lds_dwordx4 v[232:233], off
	s_add_i32 m0, s71, 0x2000
	s_nop 0
	global_load_lds_dwordx4 v[234:235], off
	s_waitcnt vmcnt(6)
	s_barrier
	v_mfma_f32_16x16x32_bf16 v[52:55], v[210:213], v[176:179], v[52:55]
	v_mfma_f32_16x16x32_bf16 v[48:51], v[218:221], v[176:179], v[48:51]
	v_mfma_f32_16x16x32_bf16 v[36:39], v[210:213], v[184:187], v[36:39]
	v_mfma_f32_16x16x32_bf16 v[32:35], v[218:221], v[184:187], v[32:35]
	v_mfma_f32_16x16x32_bf16 v[20:23], v[210:213], v[192:195], v[20:23]
	v_mfma_f32_16x16x32_bf16 v[16:19], v[218:221], v[192:195], v[16:19]
	v_mfma_f32_16x16x32_bf16 v[4:7], v[210:213], v[202:205], v[4:7]
	v_mfma_f32_16x16x32_bf16 v[0:3], v[218:221], v[202:205], v[0:3]
	v_mfma_f32_16x16x32_bf16 v[52:55], v[214:217], v[180:183], v[52:55]
	v_mfma_f32_16x16x32_bf16 v[48:51], v[222:225], v[180:183], v[48:51]
	v_mfma_f32_16x16x32_bf16 v[36:39], v[214:217], v[188:191], v[36:39]
	v_mfma_f32_16x16x32_bf16 v[32:35], v[222:225], v[188:191], v[32:35]
	v_mfma_f32_16x16x32_bf16 v[20:23], v[214:217], v[198:201], v[20:23]
	v_mfma_f32_16x16x32_bf16 v[16:19], v[222:225], v[198:201], v[16:19]
	v_mfma_f32_16x16x32_bf16 v[4:7], v[214:217], v[206:209], v[4:7]
	v_mfma_f32_16x16x32_bf16 v[0:3], v[222:225], v[206:209], v[0:3]
	s_barrier
	ds_read_b128 v[160:163], v156
	ds_read_b128 v[164:167], v156 offset:1024
	ds_read_b128 v[168:171], v156 offset:2048
	ds_read_b128 v[172:175], v156 offset:3072
	s_add_u32 s16, s16, s0
	s_addc_u32 s17, s17, s1
	s_mov_b32 m0, s21
	v_lshl_add_u64 v[210:211], s[16:17], 0, v[128:129]
	ds_read_b128 v[176:179], v154 offset:32768
	ds_read_b128 v[180:183], v154 offset:33792
	ds_read_b128 v[184:187], v154 offset:34816
	ds_read_b128 v[188:191], v154 offset:35840
	ds_read_b128 v[192:195], v154 offset:36864
	ds_read_b128 v[198:201], v154 offset:37888
	ds_read_b128 v[202:205], v154 offset:38912
	ds_read_b128 v[206:209], v154 offset:39936
	global_load_lds_dwordx4 v[210:211], off
	v_lshl_add_u64 v[210:211], s[16:17], 0, v[132:133]
	s_mov_b32 m0, s22
	s_nop 0
	global_load_lds_dwordx4 v[210:211], off
	s_waitcnt lgkmcnt(8)
	s_barrier
	s_waitcnt lgkmcnt(0)
	s_waitcnt lgkmcnt(0)
	v_mfma_f32_16x16x32_bf16 v[124:127], v[160:163], v[176:179], v[124:127]
	v_mfma_f32_16x16x32_bf16 v[120:123], v[168:171], v[176:179], v[120:123]
	v_mfma_f32_16x16x32_bf16 v[108:111], v[160:163], v[184:187], v[108:111]
	v_mfma_f32_16x16x32_bf16 v[104:107], v[168:171], v[184:187], v[104:107]
	v_mfma_f32_16x16x32_bf16 v[92:95], v[160:163], v[192:195], v[92:95]
	v_mfma_f32_16x16x32_bf16 v[88:91], v[168:171], v[192:195], v[88:91]
	v_mfma_f32_16x16x32_bf16 v[76:79], v[160:163], v[202:205], v[76:79]
	v_mfma_f32_16x16x32_bf16 v[72:75], v[168:171], v[202:205], v[72:75]
	v_mfma_f32_16x16x32_bf16 v[124:127], v[164:167], v[180:183], v[124:127]
	v_mfma_f32_16x16x32_bf16 v[120:123], v[172:175], v[180:183], v[120:123]
	v_mfma_f32_16x16x32_bf16 v[108:111], v[164:167], v[188:191], v[108:111]
	v_mfma_f32_16x16x32_bf16 v[104:107], v[172:175], v[188:191], v[104:107]
	v_mfma_f32_16x16x32_bf16 v[92:95], v[164:167], v[198:201], v[92:95]
	v_mfma_f32_16x16x32_bf16 v[88:91], v[172:175], v[198:201], v[88:91]
	v_mfma_f32_16x16x32_bf16 v[76:79], v[164:167], v[206:209], v[76:79]
	v_mfma_f32_16x16x32_bf16 v[72:75], v[172:175], v[206:209], v[72:75]
	s_barrier
	s_add_i32 s16, s49, s18
	v_lshl_add_u64 v[144:145], v[144:145], 0, s[52:53]
	s_mov_b32 m0, s16
	ds_read_b128 v[210:213], v157
	ds_read_b128 v[214:217], v157 offset:1024
	ds_read_b128 v[218:221], v157 offset:2048
	ds_read_b128 v[222:225], v157 offset:3072
	global_load_lds_dwordx4 v[144:145], off
	v_lshl_add_u64 v[144:145], v[226:227], 0, s[52:53]
	s_add_i32 m0, s16, 0x2000
	s_nop 0
	global_load_lds_dwordx4 v[144:145], off
	s_barrier
; #define PG8_STAGE(bufoff, gbase, voff) do { _Pragma("unroll") for (int _i = 0; _i < 2; ++_i) \
;         __builtin_amdgcn_global_load_lds((const unsigned*)((const char*)(gbase) + (voff)[_i]), (LAS unsigned*)(lds + (bufoff) + ldsw + _i * 8192), 16, 0, 0); } while (0)
; #define PG8_LDA(dst, b, h) do { _Pragma("unroll") for (int m = 0; m < 4; ++m) _Pragma("unroll") for (int k = 0; k < 2; ++k) dst[m][k] = *(const LAS bf16x8*)(lds + PG8_SA(b, h) + aoff + m * 2048 + k * 1024); } while (0)
; #define PG8_MMA(ai, bj, At, Bt) do { __builtin_amdgcn_s_setprio(1); _Pragma("unroll") for (int m = 0; m < 4; ++m) _Pragma("unroll") for (int n = 0; n < 2; ++n) _Pragma("unroll") for (int k = 0; k < 2; ++k) \
;         acc[ai][bj][m][n] = __builtin_amdgcn_mfma_f32_16x16x32_bf16(Bt[n][k], At[m][k], acc[ai][bj][m][n], 0, 0, 0); __builtin_amdgcn_s_setprio(0); } while (0)
; #define PG8_WAIT_V(n) asm volatile("s_waitcnt vmcnt(" #n ")" ::: "memory")
; #define PG8_WAIT_L(n) asm volatile("s_waitcnt lgkmcnt(" #n ")" ::: "memory")
; #define PG8_BAR __builtin_amdgcn_s_barrier()
; #define PG8_SCHED __builtin_amdgcn_sched_barrier(0)
; template <class Epi>
; DEVI void gemm_phase(LAS unsigned char* lds, const bf16_t* gA, const bf16_t* gBt, const int lda, const int ldb, const int K, const StaticOrder S_, const Epi E) {
;     ...
;             PG8_BAR; PG8_WAIT_L(0); PG8_MMA(0, 1, At, B1); PG8_BAR;
;             PG8_LDA(At, 1, 1); PG8_STAGE(PG8_SA(1, 0), a3, voffA);
;             PG8_BAR; PG8_WAIT_L(0); PG8_MMA(1, 0, At, B0); PG8_BAR; PG8_SCHED;
;             PG8_STAGE(PG8_SB(1, 1), b3 + hstepB, voffB);
;             PG8_WAIT_V(6); PG8_BAR; PG8_MMA(1, 1, At, B1); PG8_BAR;
;         }
	s_waitcnt lgkmcnt(0)
	s_waitcnt lgkmcnt(0)
	v_mfma_f32_16x16x32_bf16 v[116:119], v[210:213], v[176:179], v[116:119]
	v_mfma_f32_16x16x32_bf16 v[112:115], v[218:221], v[176:179], v[112:115]
	v_mfma_f32_16x16x32_bf16 v[100:103], v[210:213], v[184:187], v[100:103]
	v_mfma_f32_16x16x32_bf16 v[96:99], v[218:221], v[184:187], v[96:99]
	v_mfma_f32_16x16x32_bf16 v[84:87], v[210:213], v[192:195], v[84:87]
	v_mfma_f32_16x16x32_bf16 v[80:83], v[218:221], v[192:195], v[80:83]
	v_mfma_f32_16x16x32_bf16 v[68:71], v[210:213], v[202:205], v[68:71]
	v_mfma_f32_16x16x32_bf16 v[64:67], v[218:221], v[202:205], v[64:67]
	v_mfma_f32_16x16x32_bf16 v[116:119], v[214:217], v[180:183], v[116:119]
	v_mfma_f32_16x16x32_bf16 v[112:115], v[222:225], v[180:183], v[112:115]
	v_mfma_f32_16x16x32_bf16 v[100:103], v[214:217], v[188:191], v[100:103]
	v_mfma_f32_16x16x32_bf16 v[96:99], v[222:225], v[188:191], v[96:99]
	v_mfma_f32_16x16x32_bf16 v[84:87], v[214:217], v[198:201], v[84:87]
	v_mfma_f32_16x16x32_bf16 v[80:83], v[222:225], v[198:201], v[80:83]
	v_mfma_f32_16x16x32_bf16 v[68:71], v[214:217], v[206:209], v[68:71]
	v_mfma_f32_16x16x32_bf16 v[64:67], v[222:225], v[206:209], v[64:67]
	s_mov_b32 m0, s23
	v_lshl_add_u64 v[144:145], v[228:229], 0, s[52:53]
	s_barrier
	ds_read_b128 v[176:179], v154 offset:49152
	ds_read_b128 v[180:183], v154 offset:50176
	ds_read_b128 v[184:187], v154 offset:51200
	ds_read_b128 v[188:191], v154 offset:52224
	ds_read_b128 v[192:195], v154 offset:53248
	ds_read_b128 v[198:201], v154 offset:54272
	ds_read_b128 v[202:205], v154 offset:55296
	ds_read_b128 v[206:209], v154 offset:56320
	global_load_lds_dwordx4 v[144:145], off
	v_lshl_add_u64 v[144:145], v[230:231], 0, s[52:53]
	s_mov_b32 m0, s24
	s_nop 0
	global_load_lds_dwordx4 v[144:145], off
	s_barrier
	s_waitcnt lgkmcnt(0)
	s_waitcnt lgkmcnt(0)
	v_mfma_f32_16x16x32_bf16 v[60:63], v[160:163], v[176:179], v[60:63]
	v_mfma_f32_16x16x32_bf16 v[56:59], v[168:171], v[176:179], v[56:59]
	v_mfma_f32_16x16x32_bf16 v[44:47], v[160:163], v[184:187], v[44:47]
	v_mfma_f32_16x16x32_bf16 v[40:43], v[168:171], v[184:187], v[40:43]
	v_mfma_f32_16x16x32_bf16 v[28:31], v[160:163], v[192:195], v[28:31]
	v_mfma_f32_16x16x32_bf16 v[24:27], v[168:171], v[192:195], v[24:27]
	v_mfma_f32_16x16x32_bf16 v[12:15], v[160:163], v[202:205], v[12:15]
	v_mfma_f32_16x16x32_bf16 v[8:11], v[168:171], v[202:205], v[8:11]
	v_mfma_f32_16x16x32_bf16 v[60:63], v[164:167], v[180:183], v[60:63]
	v_mfma_f32_16x16x32_bf16 v[56:59], v[172:175], v[180:183], v[56:59]
	v_mfma_f32_16x16x32_bf16 v[44:47], v[164:167], v[188:191], v[44:47]
	v_mfma_f32_16x16x32_bf16 v[40:43], v[172:175], v[188:191], v[40:43]
	v_mfma_f32_16x16x32_bf16 v[28:31], v[164:167], v[198:201], v[28:31]
	v_mfma_f32_16x16x32_bf16 v[24:27], v[172:175], v[198:201], v[24:27]
	v_mfma_f32_16x16x32_bf16 v[12:15], v[164:167], v[206:209], v[12:15]
	v_mfma_f32_16x16x32_bf16 v[8:11], v[172:175], v[206:209], v[8:11]
	s_barrier
	s_add_i32 s16, s50, s18
	v_lshl_add_u64 v[144:145], v[232:233], 0, s[52:53]
	s_mov_b32 m0, s16
	s_nop 0
	global_load_lds_dwordx4 v[144:145], off
	v_lshl_add_u64 v[144:145], v[234:235], 0, s[52:53]
	s_add_i32 m0, s16, 0x2000
	s_nop 0
	global_load_lds_dwordx4 v[144:145], off
	s_waitcnt vmcnt(6)
	s_barrier
	v_mfma_f32_16x16x32_bf16 v[52:55], v[210:213], v[176:179], v[52:55]
	v_mfma_f32_16x16x32_bf16 v[48:51], v[218:221], v[176:179], v[48:51]
	v_mfma_f32_16x16x32_bf16 v[36:39], v[210:213], v[184:187], v[36:39]
	v_mfma_f32_16x16x32_bf16 v[32:35], v[218:221], v[184:187], v[32:35]
	v_mfma_f32_16x16x32_bf16 v[20:23], v[210:213], v[192:195], v[20:23]
	v_mfma_f32_16x16x32_bf16 v[16:19], v[218:221], v[192:195], v[16:19]
	v_mfma_f32_16x16x32_bf16 v[4:7], v[210:213], v[202:205], v[4:7]
	v_mfma_f32_16x16x32_bf16 v[0:3], v[218:221], v[202:205], v[0:3]
	v_mfma_f32_16x16x32_bf16 v[52:55], v[214:217], v[180:183], v[52:55]
	v_mfma_f32_16x16x32_bf16 v[48:51], v[222:225], v[180:183], v[48:51]
	v_mfma_f32_16x16x32_bf16 v[36:39], v[214:217], v[188:191], v[36:39]
	v_mfma_f32_16x16x32_bf16 v[32:35], v[222:225], v[188:191], v[32:35]
	v_mfma_f32_16x16x32_bf16 v[20:23], v[214:217], v[198:201], v[20:23]
	v_mfma_f32_16x16x32_bf16 v[16:19], v[222:225], v[198:201], v[16:19]
	v_mfma_f32_16x16x32_bf16 v[4:7], v[214:217], v[206:209], v[4:7]
	v_mfma_f32_16x16x32_bf16 v[0:3], v[222:225], v[206:209], v[0:3]
	s_add_u32 s14, s14, 0x100
	s_addc_u32 s15, s15, 0
	s_add_u32 s60, s60, 0x100
	s_addc_u32 s61, s61, 0
	s_cmp_ge_i32 s70, s25
	s_mov_b32 s16, s70
	s_barrier
	s_cbranch_scc0 .LBB0_1980

; #define PG8_STAGE(bufoff, gbase, voff) do { _Pragma("unroll") for (int _i = 0; _i < 2; ++_i) \
;         __builtin_amdgcn_global_load_lds((const unsigned*)((const char*)(gbase) + (voff)[_i]), (LAS unsigned*)(lds + (bufoff) + ldsw + _i * 8192), 16, 0, 0); } while (0)
; #define PG8_LDA(dst, b, h) do { _Pragma("unroll") for (int m = 0; m < 4; ++m) _Pragma("unroll") for (int k = 0; k < 2; ++k) dst[m][k] = *(const LAS bf16x8*)(lds + PG8_SA(b, h) + aoff + m * 2048 + k * 1024); } while (0)
; #define PG8_LDB(dst, b, h) do { _Pragma("unroll") for (int n = 0; n < 2; ++n) _Pragma("unroll") for (int k = 0; k < 2; ++k) dst[n][k] = *(const LAS bf16x8*)(lds + PG8_SB(b, h) + boff + n * 2048 + k * 1024); } while (0)
; #define PG8_MMA(ai, bj, At, Bt) do { __builtin_amdgcn_s_setprio(1); _Pragma("unroll") for (int m = 0; m < 4; ++m) _Pragma("unroll") for (int n = 0; n < 2; ++n) _Pragma("unroll") for (int k = 0; k < 2; ++k) \
;         acc[ai][bj][m][n] = __builtin_amdgcn_mfma_f32_16x16x32_bf16(Bt[n][k], At[m][k], acc[ai][bj][m][n], 0, 0, 0); __builtin_amdgcn_s_setprio(0); } while (0)
; #define PG8_WAIT_L(n) asm volatile("s_waitcnt lgkmcnt(" #n ")" ::: "memory")
; #define PG8_BAR __builtin_amdgcn_s_barrier()
; #define PG8_SCHED __builtin_amdgcn_sched_barrier(0)
; template <class Epi>
; DEVI void gemm_phase(LAS unsigned char* lds, const bf16_t* gA, const bf16_t* gBt, const int lda, const int ldb, const int K, const StaticOrder S_, const Epi E) {
;     ...
;             const bool last = (t == nt - 2);
;             const char* a1 = cA + (size_t)(t + 1) * kstep;
;             const char* a2 = last ? nA : cA + (size_t)(t + 2) * kstep; const char* b2 = last ? nB : cB + (size_t)(t + 2) * kstep;
;             const char* a3 = a2 + kstep; const char* b3 = b2 + kstep;
;             PG8_LDB(B0, 0, 0); PG8_SCHED; PG8_LDA(At, 0, 0); PG8_STAGE(PG8_SA(1, 1), a1 + hstepA, voffA);
;             PG8_WAIT_L(8); PG8_BAR; PG8_WAIT_L(0); PG8_MMA(0, 0, At, B0); PG8_BAR; PG8_SCHED;
;             PG8_LDB(B1, 0, 1); PG8_STAGE(PG8_SB(0, 0), b2, voffB);
;             PG8_BAR; PG8_WAIT_L(0); PG8_MMA(0, 1, At, B1); PG8_BAR;
;             PG8_LDA(At, 0, 1); PG8_STAGE(PG8_SA(0, 0), a2, voffA);
;             PG8_BAR; PG8_WAIT_L(0); PG8_MMA(1, 0, At, B0); PG8_BAR; PG8_SCHED;
.LBB0_2366:
	ds_read_b128 v[128:131], v201
	ds_read_b128 v[132:135], v201 offset:1024
	ds_read_b128 v[136:139], v201 offset:2048
	ds_read_b128 v[140:143], v201 offset:3072
	s_add_i32 s60, s16, 2
	s_add_u32 s38, s14, 0x80
	s_addc_u32 s17, s15, 0
	s_cmp_eq_u32 s19, s16
	s_cselect_b32 s16, s12, s38
	s_cselect_b32 s17, s13, s17
	s_cselect_b32 s39, s41, s49
	s_cselect_b32 s38, s40, s48
	v_lshl_add_u64 v[164:165], s[14:15], 0, v[174:175]
	s_add_i32 m0, s55, 0xc000
	ds_read_b128 v[144:147], v202
	ds_read_b128 v[148:151], v202 offset:1024
	ds_read_b128 v[152:155], v202 offset:2048
	ds_read_b128 v[156:159], v202 offset:3072
	ds_read_b128 v[160:163], v202 offset:4096
	ds_read_b128 v[180:183], v202 offset:5120
	ds_read_b128 v[184:187], v202 offset:6144
	ds_read_b128 v[188:191], v202 offset:7168
	global_load_lds_dwordx4 v[164:165], off
	v_lshl_add_u64 v[164:165], s[14:15], 0, v[176:177]
	s_add_i32 m0, s55, 0xe000
	s_nop 0
	global_load_lds_dwordx4 v[164:165], off
	s_waitcnt lgkmcnt(8)
	s_barrier
	s_waitcnt lgkmcnt(0)
	s_waitcnt lgkmcnt(0)
	v_mfma_f32_16x16x32_bf16 v[124:127], v[128:131], v[144:147], v[124:127]
	v_mfma_f32_16x16x32_bf16 v[120:123], v[136:139], v[144:147], v[120:123]
	v_mfma_f32_16x16x32_bf16 v[108:111], v[128:131], v[152:155], v[108:111]
	v_mfma_f32_16x16x32_bf16 v[104:107], v[136:139], v[152:155], v[104:107]
	v_mfma_f32_16x16x32_bf16 v[92:95], v[128:131], v[160:163], v[92:95]
	v_mfma_f32_16x16x32_bf16 v[88:91], v[136:139], v[160:163], v[88:91]
	v_mfma_f32_16x16x32_bf16 v[76:79], v[128:131], v[184:187], v[76:79]
	v_mfma_f32_16x16x32_bf16 v[72:75], v[136:139], v[184:187], v[72:75]
	v_mfma_f32_16x16x32_bf16 v[124:127], v[132:135], v[148:151], v[124:127]
	v_mfma_f32_16x16x32_bf16 v[120:123], v[140:143], v[148:151], v[120:123]
	v_mfma_f32_16x16x32_bf16 v[108:111], v[132:135], v[156:159], v[108:111]
	v_mfma_f32_16x16x32_bf16 v[104:107], v[140:143], v[156:159], v[104:107]
	v_mfma_f32_16x16x32_bf16 v[92:95], v[132:135], v[180:183], v[92:95]
	v_mfma_f32_16x16x32_bf16 v[88:91], v[140:143], v[180:183], v[88:91]
	v_mfma_f32_16x16x32_bf16 v[76:79], v[132:135], v[188:191], v[76:79]
	v_mfma_f32_16x16x32_bf16 v[72:75], v[140:143], v[188:191], v[72:75]
	s_barrier
	s_add_i32 s61, s29, s20
	v_lshl_add_u64 v[164:165], s[38:39], 0, v[168:169]
	s_mov_b32 m0, s61
	ds_read_b128 v[192:195], v203
	ds_read_b128 v[206:209], v203 offset:1024
	ds_read_b128 v[210:213], v203 offset:2048
	ds_read_b128 v[214:217], v203 offset:3072
	global_load_lds_dwordx4 v[164:165], off
	v_lshl_add_u64 v[218:219], s[38:39], 0, v[172:173]
	s_add_i32 m0, s61, 0x2000
	s_nop 0
	global_load_lds_dwordx4 v[218:219], off
	s_barrier
	s_waitcnt lgkmcnt(0)
	s_waitcnt lgkmcnt(0)
	v_mfma_f32_16x16x32_bf16 v[116:119], v[192:195], v[144:147], v[116:119]
	v_mfma_f32_16x16x32_bf16 v[112:115], v[210:213], v[144:147], v[112:115]
	v_mfma_f32_16x16x32_bf16 v[100:103], v[192:195], v[152:155], v[100:103]
	v_mfma_f32_16x16x32_bf16 v[96:99], v[210:213], v[152:155], v[96:99]
	v_mfma_f32_16x16x32_bf16 v[84:87], v[192:195], v[160:163], v[84:87]
	v_mfma_f32_16x16x32_bf16 v[80:83], v[210:213], v[160:163], v[80:83]
	v_mfma_f32_16x16x32_bf16 v[68:71], v[192:195], v[184:187], v[68:71]
	v_mfma_f32_16x16x32_bf16 v[64:67], v[210:213], v[184:187], v[64:67]
	v_mfma_f32_16x16x32_bf16 v[116:119], v[206:209], v[148:151], v[116:119]
	v_mfma_f32_16x16x32_bf16 v[112:115], v[214:217], v[148:151], v[112:115]
	v_mfma_f32_16x16x32_bf16 v[100:103], v[206:209], v[156:159], v[100:103]
	v_mfma_f32_16x16x32_bf16 v[96:99], v[214:217], v[156:159], v[96:99]
	v_mfma_f32_16x16x32_bf16 v[84:87], v[206:209], v[180:183], v[84:87]
	v_mfma_f32_16x16x32_bf16 v[80:83], v[214:217], v[180:183], v[80:83]
	v_mfma_f32_16x16x32_bf16 v[68:71], v[206:209], v[188:191], v[68:71]
	v_mfma_f32_16x16x32_bf16 v[64:67], v[214:217], v[188:191], v[64:67]
	s_mov_b32 m0, s55
	v_lshl_add_u64 v[220:221], s[16:17], 0, v[166:167]
	s_barrier
	ds_read_b128 v[144:147], v202 offset:16384
	ds_read_b128 v[148:151], v202 offset:17408
	ds_read_b128 v[152:155], v202 offset:18432
	ds_read_b128 v[156:159], v202 offset:19456
	ds_read_b128 v[160:163], v202 offset:20480
	ds_read_b128 v[180:183], v202 offset:21504
	ds_read_b128 v[184:187], v202 offset:22528
	ds_read_b128 v[188:191], v202 offset:23552
	global_load_lds_dwordx4 v[220:221], off
	v_lshl_add_u64 v[222:223], s[16:17], 0, v[170:171]
	s_mov_b32 m0, s22
	s_nop 0
	global_load_lds_dwordx4 v[222:223], off
	s_barrier
	s_waitcnt lgkmcnt(0)
	s_waitcnt lgkmcnt(0)
	v_mfma_f32_16x16x32_bf16 v[60:63], v[128:131], v[144:147], v[60:63]
	v_mfma_f32_16x16x32_bf16 v[56:59], v[136:139], v[144:147], v[56:59]
	v_mfma_f32_16x16x32_bf16 v[44:47], v[128:131], v[152:155], v[44:47]
	v_mfma_f32_16x16x32_bf16 v[40:43], v[136:139], v[152:155], v[40:43]
	v_mfma_f32_16x16x32_bf16 v[28:31], v[128:131], v[160:163], v[28:31]
	v_mfma_f32_16x16x32_bf16 v[24:27], v[136:139], v[160:163], v[24:27]
	v_mfma_f32_16x16x32_bf16 v[12:15], v[128:131], v[184:187], v[12:15]
	v_mfma_f32_16x16x32_bf16 v[8:11], v[136:139], v[184:187], v[8:11]
	v_mfma_f32_16x16x32_bf16 v[60:63], v[132:135], v[148:151], v[60:63]
	v_mfma_f32_16x16x32_bf16 v[56:59], v[140:143], v[148:151], v[56:59]
	v_mfma_f32_16x16x32_bf16 v[44:47], v[132:135], v[156:159], v[44:47]
	v_mfma_f32_16x16x32_bf16 v[40:43], v[140:143], v[156:159], v[40:43]
	v_mfma_f32_16x16x32_bf16 v[28:31], v[132:135], v[180:183], v[28:31]
	v_mfma_f32_16x16x32_bf16 v[24:27], v[140:143], v[180:183], v[24:27]
	v_mfma_f32_16x16x32_bf16 v[12:15], v[132:135], v[188:191], v[12:15]
	v_mfma_f32_16x16x32_bf16 v[8:11], v[140:143], v[188:191], v[8:11]
	s_barrier
; #define PG8_STAGE(bufoff, gbase, voff) do { _Pragma("unroll") for (int _i = 0; _i < 2; ++_i) \
;         __builtin_amdgcn_global_load_lds((const unsigned*)((const char*)(gbase) + (voff)[_i]), (LAS unsigned*)(lds + (bufoff) + ldsw + _i * 8192), 16, 0, 0); } while (0)
; #define PG8_LDA(dst, b, h) do { _Pragma("unroll") for (int m = 0; m < 4; ++m) _Pragma("unroll") for (int k = 0; k < 2; ++k) dst[m][k] = *(const LAS bf16x8*)(lds + PG8_SA(b, h) + aoff + m * 2048 + k * 1024); } while (0)
; #define PG8_LDB(dst, b, h) do { _Pragma("unroll") for (int n = 0; n < 2; ++n) _Pragma("unroll") for (int k = 0; k < 2; ++k) dst[n][k] = *(const LAS bf16x8*)(lds + PG8_SB(b, h) + boff + n * 2048 + k * 1024); } while (0)
; #define PG8_MMA(ai, bj, At, Bt) do { __builtin_amdgcn_s_setprio(1); _Pragma("unroll") for (int m = 0; m < 4; ++m) _Pragma("unroll") for (int n = 0; n < 2; ++n) _Pragma("unroll") for (int k = 0; k < 2; ++k) \
;         acc[ai][bj][m][n] = __builtin_amdgcn_mfma_f32_16x16x32_bf16(Bt[n][k], At[m][k], acc[ai][bj][m][n], 0, 0, 0); __builtin_amdgcn_s_setprio(0); } while (0)
; #define PG8_WAIT_V(n) asm volatile("s_waitcnt vmcnt(" #n ")" ::: "memory")
; #define PG8_WAIT_L(n) asm volatile("s_waitcnt lgkmcnt(" #n ")" ::: "memory")
; #define PG8_BAR __builtin_amdgcn_s_barrier()
; #define PG8_SCHED __builtin_amdgcn_sched_barrier(0)
; template <class Epi>
; DEVI void gemm_phase(LAS unsigned char* lds, const bf16_t* gA, const bf16_t* gBt, const int lda, const int ldb, const int K, const StaticOrder S_, const Epi E) {
;     ...
;             PG8_STAGE(PG8_SB(0, 1), b2 + hstepB, voffB);
;             PG8_WAIT_V(6); PG8_BAR; PG8_MMA(1, 1, At, B1); PG8_BAR;
;             PG8_LDB(B0, 1, 0); PG8_SCHED; PG8_LDA(At, 1, 0); PG8_STAGE(PG8_SA(0, 1), a2 + hstepA, voffA);
;             PG8_WAIT_L(8); PG8_BAR; PG8_WAIT_L(0); PG8_MMA(0, 0, At, B0); PG8_BAR; PG8_SCHED;
;             PG8_LDB(B1, 1, 1); PG8_STAGE(PG8_SB(1, 0), b3, voffB);
	s_add_u32 s38, s38, s2
	s_addc_u32 s39, s39, s3
	s_add_i32 s61, s50, s20
	v_lshl_add_u64 v[224:225], s[38:39], 0, v[168:169]
	s_mov_b32 m0, s61
	v_lshl_add_u64 v[226:227], s[38:39], 0, v[172:173]
	global_load_lds_dwordx4 v[224:225], off
	s_add_i32 m0, s61, 0x2000
	s_nop 0
	global_load_lds_dwordx4 v[226:227], off
	s_waitcnt vmcnt(6)
	s_barrier
	v_mfma_f32_16x16x32_bf16 v[52:55], v[192:195], v[144:147], v[52:55]
	v_mfma_f32_16x16x32_bf16 v[48:51], v[210:213], v[144:147], v[48:51]
	v_mfma_f32_16x16x32_bf16 v[36:39], v[192:195], v[152:155], v[36:39]
	v_mfma_f32_16x16x32_bf16 v[32:35], v[210:213], v[152:155], v[32:35]
	v_mfma_f32_16x16x32_bf16 v[20:23], v[192:195], v[160:163], v[20:23]
	v_mfma_f32_16x16x32_bf16 v[16:19], v[210:213], v[160:163], v[16:19]
	v_mfma_f32_16x16x32_bf16 v[4:7], v[192:195], v[184:187], v[4:7]
	v_mfma_f32_16x16x32_bf16 v[0:3], v[210:213], v[184:187], v[0:3]
	v_mfma_f32_16x16x32_bf16 v[52:55], v[206:209], v[148:151], v[52:55]
	v_mfma_f32_16x16x32_bf16 v[48:51], v[214:217], v[148:151], v[48:51]
	v_mfma_f32_16x16x32_bf16 v[36:39], v[206:209], v[156:159], v[36:39]
	v_mfma_f32_16x16x32_bf16 v[32:35], v[214:217], v[156:159], v[32:35]
	v_mfma_f32_16x16x32_bf16 v[20:23], v[206:209], v[180:183], v[20:23]
	v_mfma_f32_16x16x32_bf16 v[16:19], v[214:217], v[180:183], v[16:19]
	v_mfma_f32_16x16x32_bf16 v[4:7], v[206:209], v[188:191], v[4:7]
	v_mfma_f32_16x16x32_bf16 v[0:3], v[214:217], v[188:191], v[0:3]
	s_add_i32 s38, 0, 0x18000
	v_add_u32_e32 v140, s38, v199
	s_barrier
	ds_read_b128 v[128:131], v140
	ds_read_b128 v[132:135], v140 offset:1024
	ds_read_b128 v[136:139], v140 offset:2048
	ds_read_b128 v[140:143], v140 offset:3072
	s_add_u32 s16, s16, s0
	s_addc_u32 s17, s17, s1
	s_mov_b32 m0, s23
	v_lshl_add_u64 v[192:193], s[16:17], 0, v[166:167]
	ds_read_b128 v[144:147], v202 offset:32768
	ds_read_b128 v[148:151], v202 offset:33792
	ds_read_b128 v[152:155], v202 offset:34816
	ds_read_b128 v[156:159], v202 offset:35840
	ds_read_b128 v[160:163], v202 offset:36864
	ds_read_b128 v[180:183], v202 offset:37888
	ds_read_b128 v[184:187], v202 offset:38912
	ds_read_b128 v[188:191], v202 offset:39936
	global_load_lds_dwordx4 v[192:193], off
	v_lshl_add_u64 v[192:193], s[16:17], 0, v[170:171]
	s_mov_b32 m0, s24
	s_nop 0
	global_load_lds_dwordx4 v[192:193], off
	s_waitcnt lgkmcnt(8)
	s_barrier
	s_waitcnt lgkmcnt(0)
	s_waitcnt lgkmcnt(0)
	v_mfma_f32_16x16x32_bf16 v[124:127], v[128:131], v[144:147], v[124:127]
	v_mfma_f32_16x16x32_bf16 v[120:123], v[136:139], v[144:147], v[120:123]
	v_mfma_f32_16x16x32_bf16 v[108:111], v[128:131], v[152:155], v[108:111]
	v_mfma_f32_16x16x32_bf16 v[104:107], v[136:139], v[152:155], v[104:107]
	v_mfma_f32_16x16x32_bf16 v[92:95], v[128:131], v[160:163], v[92:95]
	v_mfma_f32_16x16x32_bf16 v[88:91], v[136:139], v[160:163], v[88:91]
	v_mfma_f32_16x16x32_bf16 v[76:79], v[128:131], v[184:187], v[76:79]
	v_mfma_f32_16x16x32_bf16 v[72:75], v[136:139], v[184:187], v[72:75]
	v_mfma_f32_16x16x32_bf16 v[124:127], v[132:135], v[148:151], v[124:127]
	v_mfma_f32_16x16x32_bf16 v[120:123], v[140:143], v[148:151], v[120:123]
	v_mfma_f32_16x16x32_bf16 v[108:111], v[132:135], v[156:159], v[108:111]
	v_mfma_f32_16x16x32_bf16 v[104:107], v[140:143], v[156:159], v[104:107]
	v_mfma_f32_16x16x32_bf16 v[92:95], v[132:135], v[180:183], v[92:95]
	v_mfma_f32_16x16x32_bf16 v[88:91], v[140:143], v[180:183], v[88:91]
	v_mfma_f32_16x16x32_bf16 v[76:79], v[132:135], v[188:191], v[76:79]
	v_mfma_f32_16x16x32_bf16 v[72:75], v[140:143], v[188:191], v[72:75]
	s_barrier
	s_add_i32 s16, 0, 0x1c000
	s_add_i32 s17, s38, s20
	v_add_u32_e32 v205, s16, v199
	v_lshl_add_u64 v[164:165], v[164:165], 0, s[8:9]
	s_mov_b32 m0, s17
	ds_read_b128 v[192:195], v205
	ds_read_b128 v[206:209], v205 offset:1024
	ds_read_b128 v[210:213], v205 offset:2048
	ds_read_b128 v[214:217], v205 offset:3072
	global_load_lds_dwordx4 v[164:165], off
	v_lshl_add_u64 v[164:165], v[218:219], 0, s[8:9]
	s_add_i32 m0, s17, 0x2000
	s_nop 0
	global_load_lds_dwordx4 v[164:165], off
	s_barrier
; #define PG8_STAGE(bufoff, gbase, voff) do { _Pragma("unroll") for (int _i = 0; _i < 2; ++_i) \
;         __builtin_amdgcn_global_load_lds((const unsigned*)((const char*)(gbase) + (voff)[_i]), (LAS unsigned*)(lds + (bufoff) + ldsw + _i * 8192), 16, 0, 0); } while (0)
; #define PG8_LDA(dst, b, h) do { _Pragma("unroll") for (int m = 0; m < 4; ++m) _Pragma("unroll") for (int k = 0; k < 2; ++k) dst[m][k] = *(const LAS bf16x8*)(lds + PG8_SA(b, h) + aoff + m * 2048 + k * 1024); } while (0)
; #define PG8_MMA(ai, bj, At, Bt) do { __builtin_amdgcn_s_setprio(1); _Pragma("unroll") for (int m = 0; m < 4; ++m) _Pragma("unroll") for (int n = 0; n < 2; ++n) _Pragma("unroll") for (int k = 0; k < 2; ++k) \
;         acc[ai][bj][m][n] = __builtin_amdgcn_mfma_f32_16x16x32_bf16(Bt[n][k], At[m][k], acc[ai][bj][m][n], 0, 0, 0); __builtin_amdgcn_s_setprio(0); } while (0)
; #define PG8_WAIT_V(n) asm volatile("s_waitcnt vmcnt(" #n ")" ::: "memory")
; #define PG8_WAIT_L(n) asm volatile("s_waitcnt lgkmcnt(" #n ")" ::: "memory")
; #define PG8_BAR __builtin_amdgcn_s_barrier()
; #define PG8_SCHED __builtin_amdgcn_sched_barrier(0)
; template <class Epi>
; DEVI void gemm_phase(LAS unsigned char* lds, const bf16_t* gA, const bf16_t* gBt, const int lda, const int ldb, const int K, const StaticOrder S_, const Epi E) {
;     ...
;             PG8_BAR; PG8_WAIT_L(0); PG8_MMA(0, 1, At, B1); PG8_BAR;
;             PG8_LDA(At, 1, 1); PG8_STAGE(PG8_SA(1, 0), a3, voffA);
;             PG8_BAR; PG8_WAIT_L(0); PG8_MMA(1, 0, At, B0); PG8_BAR; PG8_SCHED;
;             PG8_STAGE(PG8_SB(1, 1), b3 + hstepB, voffB);
;             PG8_WAIT_V(6); PG8_BAR; PG8_MMA(1, 1, At, B1); PG8_BAR;
;         }
	s_waitcnt lgkmcnt(0)
	s_waitcnt lgkmcnt(0)
	v_mfma_f32_16x16x32_bf16 v[116:119], v[192:195], v[144:147], v[116:119]
	v_mfma_f32_16x16x32_bf16 v[112:115], v[210:213], v[144:147], v[112:115]
	v_mfma_f32_16x16x32_bf16 v[100:103], v[192:195], v[152:155], v[100:103]
	v_mfma_f32_16x16x32_bf16 v[96:99], v[210:213], v[152:155], v[96:99]
	v_mfma_f32_16x16x32_bf16 v[84:87], v[192:195], v[160:163], v[84:87]
	v_mfma_f32_16x16x32_bf16 v[80:83], v[210:213], v[160:163], v[80:83]
	v_mfma_f32_16x16x32_bf16 v[68:71], v[192:195], v[184:187], v[68:71]
	v_mfma_f32_16x16x32_bf16 v[64:67], v[210:213], v[184:187], v[64:67]
	v_mfma_f32_16x16x32_bf16 v[116:119], v[206:209], v[148:151], v[116:119]
	v_mfma_f32_16x16x32_bf16 v[112:115], v[214:217], v[148:151], v[112:115]
	v_mfma_f32_16x16x32_bf16 v[100:103], v[206:209], v[156:159], v[100:103]
	v_mfma_f32_16x16x32_bf16 v[96:99], v[214:217], v[156:159], v[96:99]
	v_mfma_f32_16x16x32_bf16 v[84:87], v[206:209], v[180:183], v[84:87]
	v_mfma_f32_16x16x32_bf16 v[80:83], v[214:217], v[180:183], v[80:83]
	v_mfma_f32_16x16x32_bf16 v[68:71], v[206:209], v[188:191], v[68:71]
	v_mfma_f32_16x16x32_bf16 v[64:67], v[214:217], v[188:191], v[64:67]
	s_mov_b32 m0, s26
	v_lshl_add_u64 v[164:165], v[220:221], 0, s[8:9]
	s_barrier
	ds_read_b128 v[144:147], v202 offset:49152
	ds_read_b128 v[148:151], v202 offset:50176
	ds_read_b128 v[152:155], v202 offset:51200
	ds_read_b128 v[156:159], v202 offset:52224
	ds_read_b128 v[160:163], v202 offset:53248
	ds_read_b128 v[180:183], v202 offset:54272
	ds_read_b128 v[184:187], v202 offset:55296
	ds_read_b128 v[188:191], v202 offset:56320
	global_load_lds_dwordx4 v[164:165], off
	v_lshl_add_u64 v[164:165], v[222:223], 0, s[8:9]
	s_mov_b32 m0, s27
	s_nop 0
	global_load_lds_dwordx4 v[164:165], off
	s_barrier
	s_waitcnt lgkmcnt(0)
	s_waitcnt lgkmcnt(0)
	v_mfma_f32_16x16x32_bf16 v[60:63], v[128:131], v[144:147], v[60:63]
	v_mfma_f32_16x16x32_bf16 v[56:59], v[136:139], v[144:147], v[56:59]
	v_mfma_f32_16x16x32_bf16 v[44:47], v[128:131], v[152:155], v[44:47]
	v_mfma_f32_16x16x32_bf16 v[40:43], v[136:139], v[152:155], v[40:43]
	v_mfma_f32_16x16x32_bf16 v[28:31], v[128:131], v[160:163], v[28:31]
	v_mfma_f32_16x16x32_bf16 v[24:27], v[136:139], v[160:163], v[24:27]
	v_mfma_f32_16x16x32_bf16 v[12:15], v[128:131], v[184:187], v[12:15]
	v_mfma_f32_16x16x32_bf16 v[8:11], v[136:139], v[184:187], v[8:11]
	v_mfma_f32_16x16x32_bf16 v[60:63], v[132:135], v[148:151], v[60:63]
	v_mfma_f32_16x16x32_bf16 v[56:59], v[140:143], v[148:151], v[56:59]
	v_mfma_f32_16x16x32_bf16 v[44:47], v[132:135], v[156:159], v[44:47]
	v_mfma_f32_16x16x32_bf16 v[40:43], v[140:143], v[156:159], v[40:43]
	v_mfma_f32_16x16x32_bf16 v[28:31], v[132:135], v[180:183], v[28:31]
	v_mfma_f32_16x16x32_bf16 v[24:27], v[140:143], v[180:183], v[24:27]
	v_mfma_f32_16x16x32_bf16 v[12:15], v[132:135], v[188:191], v[12:15]
	v_mfma_f32_16x16x32_bf16 v[8:11], v[140:143], v[188:191], v[8:11]
	s_barrier
	s_add_i32 s16, s16, s20
	v_lshl_add_u64 v[128:129], v[224:225], 0, s[8:9]
	s_mov_b32 m0, s16
	s_nop 0
	global_load_lds_dwordx4 v[128:129], off
	v_lshl_add_u64 v[128:129], v[226:227], 0, s[8:9]
	s_add_i32 m0, s16, 0x2000
	s_nop 0
	global_load_lds_dwordx4 v[128:129], off
	s_waitcnt vmcnt(6)
	s_barrier
	v_mfma_f32_16x16x32_bf16 v[52:55], v[192:195], v[144:147], v[52:55]
	v_mfma_f32_16x16x32_bf16 v[48:51], v[210:213], v[144:147], v[48:51]
	v_mfma_f32_16x16x32_bf16 v[36:39], v[192:195], v[152:155], v[36:39]
	v_mfma_f32_16x16x32_bf16 v[32:35], v[210:213], v[152:155], v[32:35]
	v_mfma_f32_16x16x32_bf16 v[20:23], v[192:195], v[160:163], v[20:23]
	v_mfma_f32_16x16x32_bf16 v[16:19], v[210:213], v[160:163], v[16:19]
	v_mfma_f32_16x16x32_bf16 v[4:7], v[192:195], v[184:187], v[4:7]
	v_mfma_f32_16x16x32_bf16 v[0:3], v[210:213], v[184:187], v[0:3]
	v_mfma_f32_16x16x32_bf16 v[52:55], v[206:209], v[148:151], v[52:55]
	v_mfma_f32_16x16x32_bf16 v[48:51], v[214:217], v[148:151], v[48:51]
	v_mfma_f32_16x16x32_bf16 v[36:39], v[206:209], v[156:159], v[36:39]
	v_mfma_f32_16x16x32_bf16 v[32:35], v[214:217], v[156:159], v[32:35]
	v_mfma_f32_16x16x32_bf16 v[20:23], v[206:209], v[180:183], v[20:23]
	v_mfma_f32_16x16x32_bf16 v[16:19], v[214:217], v[180:183], v[16:19]
	v_mfma_f32_16x16x32_bf16 v[4:7], v[206:209], v[188:191], v[4:7]
	v_mfma_f32_16x16x32_bf16 v[0:3], v[214:217], v[188:191], v[0:3]
	s_add_u32 s14, s14, 0x100
	s_addc_u32 s15, s15, 0
	s_add_u32 s48, s48, 0x100
	s_addc_u32 s49, s49, 0
	s_cmp_ge_i32 s60, s25
	s_mov_b32 s16, s60
	s_barrier
	s_cbranch_scc0 .LBB0_2366

; #define PG8_STAGE(bufoff, gbase, voff) do { _Pragma("unroll") for (int _i = 0; _i < 2; ++_i) \
;         __builtin_amdgcn_global_load_lds((const unsigned*)((const char*)(gbase) + (voff)[_i]), (LAS unsigned*)(lds + (bufoff) + ldsw + _i * 8192), 16, 0, 0); } while (0)
; #define PG8_LDA(dst, b, h) do { _Pragma("unroll") for (int m = 0; m < 4; ++m) _Pragma("unroll") for (int k = 0; k < 2; ++k) dst[m][k] = *(const LAS bf16x8*)(lds + PG8_SA(b, h) + aoff + m * 2048 + k * 1024); } while (0)
; #define PG8_LDB(dst, b, h) do { _Pragma("unroll") for (int n = 0; n < 2; ++n) _Pragma("unroll") for (int k = 0; k < 2; ++k) dst[n][k] = *(const LAS bf16x8*)(lds + PG8_SB(b, h) + boff + n * 2048 + k * 1024); } while (0)
; #define PG8_MMA(ai, bj, At, Bt) do { __builtin_amdgcn_s_setprio(1); _Pragma("unroll") for (int m = 0; m < 4; ++m) _Pragma("unroll") for (int n = 0; n < 2; ++n) _Pragma("unroll") for (int k = 0; k < 2; ++k) \
;         acc[ai][bj][m][n] = __builtin_amdgcn_mfma_f32_16x16x32_bf16(Bt[n][k], At[m][k], acc[ai][bj][m][n], 0, 0, 0); __builtin_amdgcn_s_setprio(0); } while (0)
; #define PG8_WAIT_L(n) asm volatile("s_waitcnt lgkmcnt(" #n ")" ::: "memory")
; #define PG8_BAR __builtin_amdgcn_s_barrier()
; #define PG8_SCHED __builtin_amdgcn_sched_barrier(0)
; template <class Epi>
; DEVI void gemm_phase(LAS unsigned char* lds, const bf16_t* gA, const bf16_t* gBt, const int lda, const int ldb, const int K, const StaticOrder S_, const Epi E) {
;     ...
;             const bool last = (t == nt - 2);
;             const char* a1 = cA + (size_t)(t + 1) * kstep;
;             const char* a2 = last ? nA : cA + (size_t)(t + 2) * kstep; const char* b2 = last ? nB : cB + (size_t)(t + 2) * kstep;
;             const char* a3 = a2 + kstep; const char* b3 = b2 + kstep;
;             PG8_LDB(B0, 0, 0); PG8_SCHED; PG8_LDA(At, 0, 0); PG8_STAGE(PG8_SA(1, 1), a1 + hstepA, voffA);
;             PG8_WAIT_L(8); PG8_BAR; PG8_WAIT_L(0); PG8_MMA(0, 0, At, B0); PG8_BAR; PG8_SCHED;
;             PG8_LDB(B1, 0, 1); PG8_STAGE(PG8_SB(0, 0), b2, voffB);
;             PG8_BAR; PG8_WAIT_L(0); PG8_MMA(0, 1, At, B1); PG8_BAR;
;             PG8_LDA(At, 0, 1); PG8_STAGE(PG8_SA(0, 0), a2, voffA);
;             PG8_BAR; PG8_WAIT_L(0); PG8_MMA(1, 0, At, B0); PG8_BAR; PG8_SCHED;
.LBB0_2510:
	ds_read_b128 v[158:161], v151
	ds_read_b128 v[162:165], v151 offset:1024
	ds_read_b128 v[166:169], v151 offset:2048
	ds_read_b128 v[170:173], v151 offset:3072
	s_add_i32 s61, s16, 2
	s_add_u32 s48, s14, 0x80
	s_addc_u32 s17, s15, 0
	s_cmp_eq_u32 s26, s16
	s_cselect_b32 s16, s38, s48
	s_cselect_b32 s17, s39, s17
	s_cselect_b32 s49, s47, s60
	s_cselect_b32 s48, s46, s59
	v_lshl_add_u64 v[144:145], s[14:15], 0, v[138:139]
	s_add_i32 m0, s19, 0xc000
	ds_read_b128 v[174:177], v152
	ds_read_b128 v[178:181], v152 offset:1024
	ds_read_b128 v[182:185], v152 offset:2048
	ds_read_b128 v[186:189], v152 offset:3072
	ds_read_b128 v[190:193], v152 offset:4096
	ds_read_b128 v[198:201], v152 offset:5120
	ds_read_b128 v[202:205], v152 offset:6144
	ds_read_b128 v[206:209], v152 offset:7168
	global_load_lds_dwordx4 v[144:145], off
	v_lshl_add_u64 v[144:145], s[14:15], 0, v[140:141]
	s_add_i32 m0, s19, 0xe000
	s_nop 0
	global_load_lds_dwordx4 v[144:145], off
	s_waitcnt lgkmcnt(8)
	s_barrier
	s_waitcnt lgkmcnt(0)
	s_waitcnt lgkmcnt(0)
	v_mfma_f32_16x16x32_bf16 v[120:123], v[158:161], v[174:177], v[120:123]
	v_mfma_f32_16x16x32_bf16 v[116:119], v[166:169], v[174:177], v[116:119]
	v_mfma_f32_16x16x32_bf16 v[108:111], v[158:161], v[182:185], v[108:111]
	v_mfma_f32_16x16x32_bf16 v[100:103], v[166:169], v[182:185], v[100:103]
	v_mfma_f32_16x16x32_bf16 v[92:95], v[158:161], v[190:193], v[92:95]
	v_mfma_f32_16x16x32_bf16 v[84:87], v[166:169], v[190:193], v[84:87]
	v_mfma_f32_16x16x32_bf16 v[76:79], v[158:161], v[202:205], v[76:79]
	v_mfma_f32_16x16x32_bf16 v[68:71], v[166:169], v[202:205], v[68:71]
	v_mfma_f32_16x16x32_bf16 v[120:123], v[162:165], v[178:181], v[120:123]
	v_mfma_f32_16x16x32_bf16 v[116:119], v[170:173], v[178:181], v[116:119]
	v_mfma_f32_16x16x32_bf16 v[108:111], v[162:165], v[186:189], v[108:111]
	v_mfma_f32_16x16x32_bf16 v[100:103], v[170:173], v[186:189], v[100:103]
	v_mfma_f32_16x16x32_bf16 v[92:95], v[162:165], v[198:201], v[92:95]
	v_mfma_f32_16x16x32_bf16 v[84:87], v[170:173], v[198:201], v[84:87]
	v_mfma_f32_16x16x32_bf16 v[76:79], v[162:165], v[206:209], v[76:79]
	v_mfma_f32_16x16x32_bf16 v[68:71], v[170:173], v[206:209], v[68:71]
	s_barrier
	s_add_i32 s62, s30, s18
	v_lshl_add_u64 v[144:145], s[48:49], 0, v[130:131]
	s_mov_b32 m0, s62
	ds_read_b128 v[210:213], v153
	ds_read_b128 v[214:217], v153 offset:1024
	ds_read_b128 v[218:221], v153 offset:2048
	ds_read_b128 v[222:225], v153 offset:3072
	global_load_lds_dwordx4 v[144:145], off
	v_lshl_add_u64 v[194:195], s[48:49], 0, v[134:135]
	s_add_i32 m0, s62, 0x2000
	s_nop 0
	global_load_lds_dwordx4 v[194:195], off
	s_barrier
	s_waitcnt lgkmcnt(0)
	s_waitcnt lgkmcnt(0)
	v_mfma_f32_16x16x32_bf16 v[124:127], v[210:213], v[174:177], v[124:127]
	v_mfma_f32_16x16x32_bf16 v[112:115], v[218:221], v[174:177], v[112:115]
	v_mfma_f32_16x16x32_bf16 v[104:107], v[210:213], v[182:185], v[104:107]
	v_mfma_f32_16x16x32_bf16 v[96:99], v[218:221], v[182:185], v[96:99]
	v_mfma_f32_16x16x32_bf16 v[88:91], v[210:213], v[190:193], v[88:91]
	v_mfma_f32_16x16x32_bf16 v[80:83], v[218:221], v[190:193], v[80:83]
	v_mfma_f32_16x16x32_bf16 v[72:75], v[210:213], v[202:205], v[72:75]
	v_mfma_f32_16x16x32_bf16 v[64:67], v[218:221], v[202:205], v[64:67]
	v_mfma_f32_16x16x32_bf16 v[124:127], v[214:217], v[178:181], v[124:127]
	v_mfma_f32_16x16x32_bf16 v[112:115], v[222:225], v[178:181], v[112:115]
	v_mfma_f32_16x16x32_bf16 v[104:107], v[214:217], v[186:189], v[104:107]
	v_mfma_f32_16x16x32_bf16 v[96:99], v[222:225], v[186:189], v[96:99]
	v_mfma_f32_16x16x32_bf16 v[88:91], v[214:217], v[198:201], v[88:91]
	v_mfma_f32_16x16x32_bf16 v[80:83], v[222:225], v[198:201], v[80:83]
	v_mfma_f32_16x16x32_bf16 v[72:75], v[214:217], v[206:209], v[72:75]
	v_mfma_f32_16x16x32_bf16 v[64:67], v[222:225], v[206:209], v[64:67]
	s_mov_b32 m0, s19
	v_lshl_add_u64 v[226:227], s[16:17], 0, v[128:129]
	s_barrier
	ds_read_b128 v[174:177], v152 offset:16384
	ds_read_b128 v[178:181], v152 offset:17408
	ds_read_b128 v[182:185], v152 offset:18432
	ds_read_b128 v[186:189], v152 offset:19456
	ds_read_b128 v[190:193], v152 offset:20480
	ds_read_b128 v[198:201], v152 offset:21504
	ds_read_b128 v[202:205], v152 offset:22528
	ds_read_b128 v[206:209], v152 offset:23552
	global_load_lds_dwordx4 v[226:227], off
	v_lshl_add_u64 v[228:229], s[16:17], 0, v[132:133]
	s_mov_b32 m0, s20
	s_nop 0
	global_load_lds_dwordx4 v[228:229], off
	s_barrier
	s_waitcnt lgkmcnt(0)
	s_waitcnt lgkmcnt(0)
	v_mfma_f32_16x16x32_bf16 v[60:63], v[158:161], v[174:177], v[60:63]
	v_mfma_f32_16x16x32_bf16 v[56:59], v[166:169], v[174:177], v[56:59]
	v_mfma_f32_16x16x32_bf16 v[44:47], v[158:161], v[182:185], v[44:47]
	v_mfma_f32_16x16x32_bf16 v[40:43], v[166:169], v[182:185], v[40:43]
	v_mfma_f32_16x16x32_bf16 v[28:31], v[158:161], v[190:193], v[28:31]
	v_mfma_f32_16x16x32_bf16 v[24:27], v[166:169], v[190:193], v[24:27]
	v_mfma_f32_16x16x32_bf16 v[12:15], v[158:161], v[202:205], v[12:15]
	v_mfma_f32_16x16x32_bf16 v[8:11], v[166:169], v[202:205], v[8:11]
	v_mfma_f32_16x16x32_bf16 v[60:63], v[162:165], v[178:181], v[60:63]
	v_mfma_f32_16x16x32_bf16 v[56:59], v[170:173], v[178:181], v[56:59]
	v_mfma_f32_16x16x32_bf16 v[44:47], v[162:165], v[186:189], v[44:47]
	v_mfma_f32_16x16x32_bf16 v[40:43], v[170:173], v[186:189], v[40:43]
	v_mfma_f32_16x16x32_bf16 v[28:31], v[162:165], v[198:201], v[28:31]
	v_mfma_f32_16x16x32_bf16 v[24:27], v[170:173], v[198:201], v[24:27]
	v_mfma_f32_16x16x32_bf16 v[12:15], v[162:165], v[206:209], v[12:15]
	v_mfma_f32_16x16x32_bf16 v[8:11], v[170:173], v[206:209], v[8:11]
	s_barrier
; #define PG8_STAGE(bufoff, gbase, voff) do { _Pragma("unroll") for (int _i = 0; _i < 2; ++_i) \
;         __builtin_amdgcn_global_load_lds((const unsigned*)((const char*)(gbase) + (voff)[_i]), (LAS unsigned*)(lds + (bufoff) + ldsw + _i * 8192), 16, 0, 0); } while (0)
; #define PG8_LDA(dst, b, h) do { _Pragma("unroll") for (int m = 0; m < 4; ++m) _Pragma("unroll") for (int k = 0; k < 2; ++k) dst[m][k] = *(const LAS bf16x8*)(lds + PG8_SA(b, h) + aoff + m * 2048 + k * 1024); } while (0)
; #define PG8_LDB(dst, b, h) do { _Pragma("unroll") for (int n = 0; n < 2; ++n) _Pragma("unroll") for (int k = 0; k < 2; ++k) dst[n][k] = *(const LAS bf16x8*)(lds + PG8_SB(b, h) + boff + n * 2048 + k * 1024); } while (0)
; #define PG8_MMA(ai, bj, At, Bt) do { __builtin_amdgcn_s_setprio(1); _Pragma("unroll") for (int m = 0; m < 4; ++m) _Pragma("unroll") for (int n = 0; n < 2; ++n) _Pragma("unroll") for (int k = 0; k < 2; ++k) \
;         acc[ai][bj][m][n] = __builtin_amdgcn_mfma_f32_16x16x32_bf16(Bt[n][k], At[m][k], acc[ai][bj][m][n], 0, 0, 0); __builtin_amdgcn_s_setprio(0); } while (0)
; #define PG8_WAIT_V(n) asm volatile("s_waitcnt vmcnt(" #n ")" ::: "memory")
; #define PG8_WAIT_L(n) asm volatile("s_waitcnt lgkmcnt(" #n ")" ::: "memory")
; #define PG8_BAR __builtin_amdgcn_s_barrier()
; #define PG8_SCHED __builtin_amdgcn_sched_barrier(0)
; template <class Epi>
; DEVI void gemm_phase(LAS unsigned char* lds, const bf16_t* gA, const bf16_t* gBt, const int lda, const int ldb, const int K, const StaticOrder S_, const Epi E) {
;     ...
;             PG8_STAGE(PG8_SB(0, 1), b2 + hstepB, voffB);
;             PG8_WAIT_V(6); PG8_BAR; PG8_MMA(1, 1, At, B1); PG8_BAR;
;             PG8_LDB(B0, 1, 0); PG8_SCHED; PG8_LDA(At, 1, 0); PG8_STAGE(PG8_SA(0, 1), a2 + hstepA, voffA);
;             PG8_WAIT_L(8); PG8_BAR; PG8_WAIT_L(0); PG8_MMA(0, 0, At, B0); PG8_BAR; PG8_SCHED;
;             PG8_LDB(B1, 1, 1); PG8_STAGE(PG8_SB(1, 0), b3, voffB);
	s_add_u32 s48, s48, s2
	s_addc_u32 s49, s49, s3
	s_add_i32 s62, s50, s18
	v_lshl_add_u64 v[230:231], s[48:49], 0, v[130:131]
	s_mov_b32 m0, s62
	v_lshl_add_u64 v[232:233], s[48:49], 0, v[134:135]
	global_load_lds_dwordx4 v[230:231], off
	s_add_i32 m0, s62, 0x2000
	s_nop 0
	global_load_lds_dwordx4 v[232:233], off
	s_waitcnt vmcnt(6)
	s_barrier
	v_mfma_f32_16x16x32_bf16 v[52:55], v[210:213], v[174:177], v[52:55]
	v_mfma_f32_16x16x32_bf16 v[48:51], v[218:221], v[174:177], v[48:51]
	v_mfma_f32_16x16x32_bf16 v[36:39], v[210:213], v[182:185], v[36:39]
	v_mfma_f32_16x16x32_bf16 v[32:35], v[218:221], v[182:185], v[32:35]
	v_mfma_f32_16x16x32_bf16 v[20:23], v[210:213], v[190:193], v[20:23]
	v_mfma_f32_16x16x32_bf16 v[16:19], v[218:221], v[190:193], v[16:19]
	v_mfma_f32_16x16x32_bf16 v[4:7], v[210:213], v[202:205], v[4:7]
	v_mfma_f32_16x16x32_bf16 v[0:3], v[218:221], v[202:205], v[0:3]
	v_mfma_f32_16x16x32_bf16 v[52:55], v[214:217], v[178:181], v[52:55]
	v_mfma_f32_16x16x32_bf16 v[48:51], v[222:225], v[178:181], v[48:51]
	v_mfma_f32_16x16x32_bf16 v[36:39], v[214:217], v[186:189], v[36:39]
	v_mfma_f32_16x16x32_bf16 v[32:35], v[222:225], v[186:189], v[32:35]
	v_mfma_f32_16x16x32_bf16 v[20:23], v[214:217], v[198:201], v[20:23]
	v_mfma_f32_16x16x32_bf16 v[16:19], v[222:225], v[198:201], v[16:19]
	v_mfma_f32_16x16x32_bf16 v[4:7], v[214:217], v[206:209], v[4:7]
	v_mfma_f32_16x16x32_bf16 v[0:3], v[222:225], v[206:209], v[0:3]
	s_barrier
	ds_read_b128 v[158:161], v154
	ds_read_b128 v[162:165], v154 offset:1024
	ds_read_b128 v[166:169], v154 offset:2048
	ds_read_b128 v[170:173], v154 offset:3072
	s_add_u32 s16, s16, s0
	s_addc_u32 s17, s17, s1
	s_mov_b32 m0, s21
	v_lshl_add_u64 v[210:211], s[16:17], 0, v[128:129]
	ds_read_b128 v[174:177], v152 offset:32768
	ds_read_b128 v[178:181], v152 offset:33792
	ds_read_b128 v[182:185], v152 offset:34816
	ds_read_b128 v[186:189], v152 offset:35840
	ds_read_b128 v[190:193], v152 offset:36864
	ds_read_b128 v[198:201], v152 offset:37888
	ds_read_b128 v[202:205], v152 offset:38912
	ds_read_b128 v[206:209], v152 offset:39936
	global_load_lds_dwordx4 v[210:211], off
	v_lshl_add_u64 v[210:211], s[16:17], 0, v[132:133]
	s_mov_b32 m0, s22
	s_nop 0
	global_load_lds_dwordx4 v[210:211], off
	s_waitcnt lgkmcnt(8)
	s_barrier
	s_waitcnt lgkmcnt(0)
	s_waitcnt lgkmcnt(0)
	v_mfma_f32_16x16x32_bf16 v[120:123], v[158:161], v[174:177], v[120:123]
	v_mfma_f32_16x16x32_bf16 v[116:119], v[166:169], v[174:177], v[116:119]
	v_mfma_f32_16x16x32_bf16 v[108:111], v[158:161], v[182:185], v[108:111]
	v_mfma_f32_16x16x32_bf16 v[100:103], v[166:169], v[182:185], v[100:103]
	v_mfma_f32_16x16x32_bf16 v[92:95], v[158:161], v[190:193], v[92:95]
	v_mfma_f32_16x16x32_bf16 v[84:87], v[166:169], v[190:193], v[84:87]
	v_mfma_f32_16x16x32_bf16 v[76:79], v[158:161], v[202:205], v[76:79]
	v_mfma_f32_16x16x32_bf16 v[68:71], v[166:169], v[202:205], v[68:71]
	v_mfma_f32_16x16x32_bf16 v[120:123], v[162:165], v[178:181], v[120:123]
	v_mfma_f32_16x16x32_bf16 v[116:119], v[170:173], v[178:181], v[116:119]
	v_mfma_f32_16x16x32_bf16 v[108:111], v[162:165], v[186:189], v[108:111]
	v_mfma_f32_16x16x32_bf16 v[100:103], v[170:173], v[186:189], v[100:103]
	v_mfma_f32_16x16x32_bf16 v[92:95], v[162:165], v[198:201], v[92:95]
	v_mfma_f32_16x16x32_bf16 v[84:87], v[170:173], v[198:201], v[84:87]
	v_mfma_f32_16x16x32_bf16 v[76:79], v[162:165], v[206:209], v[76:79]
	v_mfma_f32_16x16x32_bf16 v[68:71], v[170:173], v[206:209], v[68:71]
	s_barrier
	s_add_i32 s16, s51, s18
	v_lshl_add_u64 v[144:145], v[144:145], 0, s[44:45]
	s_mov_b32 m0, s16
	ds_read_b128 v[210:213], v155
	ds_read_b128 v[214:217], v155 offset:1024
	ds_read_b128 v[218:221], v155 offset:2048
	ds_read_b128 v[222:225], v155 offset:3072
	global_load_lds_dwordx4 v[144:145], off
	v_lshl_add_u64 v[144:145], v[194:195], 0, s[44:45]
	s_add_i32 m0, s16, 0x2000
	s_nop 0
	global_load_lds_dwordx4 v[144:145], off
	s_barrier
; #define PG8_STAGE(bufoff, gbase, voff) do { _Pragma("unroll") for (int _i = 0; _i < 2; ++_i) \
;         __builtin_amdgcn_global_load_lds((const unsigned*)((const char*)(gbase) + (voff)[_i]), (LAS unsigned*)(lds + (bufoff) + ldsw + _i * 8192), 16, 0, 0); } while (0)
; #define PG8_LDA(dst, b, h) do { _Pragma("unroll") for (int m = 0; m < 4; ++m) _Pragma("unroll") for (int k = 0; k < 2; ++k) dst[m][k] = *(const LAS bf16x8*)(lds + PG8_SA(b, h) + aoff + m * 2048 + k * 1024); } while (0)
; #define PG8_MMA(ai, bj, At, Bt) do { __builtin_amdgcn_s_setprio(1); _Pragma("unroll") for (int m = 0; m < 4; ++m) _Pragma("unroll") for (int n = 0; n < 2; ++n) _Pragma("unroll") for (int k = 0; k < 2; ++k) \
;         acc[ai][bj][m][n] = __builtin_amdgcn_mfma_f32_16x16x32_bf16(Bt[n][k], At[m][k], acc[ai][bj][m][n], 0, 0, 0); __builtin_amdgcn_s_setprio(0); } while (0)
; #define PG8_WAIT_V(n) asm volatile("s_waitcnt vmcnt(" #n ")" ::: "memory")
; #define PG8_WAIT_L(n) asm volatile("s_waitcnt lgkmcnt(" #n ")" ::: "memory")
; #define PG8_BAR __builtin_amdgcn_s_barrier()
; #define PG8_SCHED __builtin_amdgcn_sched_barrier(0)
; template <class Epi>
; DEVI void gemm_phase(LAS unsigned char* lds, const bf16_t* gA, const bf16_t* gBt, const int lda, const int ldb, const int K, const StaticOrder S_, const Epi E) {
;     ...
;             PG8_BAR; PG8_WAIT_L(0); PG8_MMA(0, 1, At, B1); PG8_BAR;
;             PG8_LDA(At, 1, 1); PG8_STAGE(PG8_SA(1, 0), a3, voffA);
;             PG8_BAR; PG8_WAIT_L(0); PG8_MMA(1, 0, At, B0); PG8_BAR; PG8_SCHED;
;             PG8_STAGE(PG8_SB(1, 1), b3 + hstepB, voffB);
;             PG8_WAIT_V(6); PG8_BAR; PG8_MMA(1, 1, At, B1); PG8_BAR;
;         }
	s_waitcnt lgkmcnt(0)
	s_waitcnt lgkmcnt(0)
	v_mfma_f32_16x16x32_bf16 v[124:127], v[210:213], v[174:177], v[124:127]
	v_mfma_f32_16x16x32_bf16 v[112:115], v[218:221], v[174:177], v[112:115]
	v_mfma_f32_16x16x32_bf16 v[104:107], v[210:213], v[182:185], v[104:107]
	v_mfma_f32_16x16x32_bf16 v[96:99], v[218:221], v[182:185], v[96:99]
	v_mfma_f32_16x16x32_bf16 v[88:91], v[210:213], v[190:193], v[88:91]
	v_mfma_f32_16x16x32_bf16 v[80:83], v[218:221], v[190:193], v[80:83]
	v_mfma_f32_16x16x32_bf16 v[72:75], v[210:213], v[202:205], v[72:75]
	v_mfma_f32_16x16x32_bf16 v[64:67], v[218:221], v[202:205], v[64:67]
	v_mfma_f32_16x16x32_bf16 v[124:127], v[214:217], v[178:181], v[124:127]
	v_mfma_f32_16x16x32_bf16 v[112:115], v[222:225], v[178:181], v[112:115]
	v_mfma_f32_16x16x32_bf16 v[104:107], v[214:217], v[186:189], v[104:107]
	v_mfma_f32_16x16x32_bf16 v[96:99], v[222:225], v[186:189], v[96:99]
	v_mfma_f32_16x16x32_bf16 v[88:91], v[214:217], v[198:201], v[88:91]
	v_mfma_f32_16x16x32_bf16 v[80:83], v[222:225], v[198:201], v[80:83]
	v_mfma_f32_16x16x32_bf16 v[72:75], v[214:217], v[206:209], v[72:75]
	v_mfma_f32_16x16x32_bf16 v[64:67], v[222:225], v[206:209], v[64:67]
	s_mov_b32 m0, s23
	v_lshl_add_u64 v[144:145], v[226:227], 0, s[44:45]
	s_barrier
	ds_read_b128 v[174:177], v152 offset:49152
	ds_read_b128 v[178:181], v152 offset:50176
	ds_read_b128 v[182:185], v152 offset:51200
	ds_read_b128 v[186:189], v152 offset:52224
	ds_read_b128 v[190:193], v152 offset:53248
	ds_read_b128 v[198:201], v152 offset:54272
	ds_read_b128 v[202:205], v152 offset:55296
	ds_read_b128 v[206:209], v152 offset:56320
	global_load_lds_dwordx4 v[144:145], off
	v_lshl_add_u64 v[144:145], v[228:229], 0, s[44:45]
	s_mov_b32 m0, s24
	s_nop 0
	global_load_lds_dwordx4 v[144:145], off
	s_barrier
	s_waitcnt lgkmcnt(0)
	s_waitcnt lgkmcnt(0)
	v_mfma_f32_16x16x32_bf16 v[60:63], v[158:161], v[174:177], v[60:63]
	v_mfma_f32_16x16x32_bf16 v[56:59], v[166:169], v[174:177], v[56:59]
	v_mfma_f32_16x16x32_bf16 v[44:47], v[158:161], v[182:185], v[44:47]
	v_mfma_f32_16x16x32_bf16 v[40:43], v[166:169], v[182:185], v[40:43]
	v_mfma_f32_16x16x32_bf16 v[28:31], v[158:161], v[190:193], v[28:31]
	v_mfma_f32_16x16x32_bf16 v[24:27], v[166:169], v[190:193], v[24:27]
	v_mfma_f32_16x16x32_bf16 v[12:15], v[158:161], v[202:205], v[12:15]
	v_mfma_f32_16x16x32_bf16 v[8:11], v[166:169], v[202:205], v[8:11]
	v_mfma_f32_16x16x32_bf16 v[60:63], v[162:165], v[178:181], v[60:63]
	v_mfma_f32_16x16x32_bf16 v[56:59], v[170:173], v[178:181], v[56:59]
	v_mfma_f32_16x16x32_bf16 v[44:47], v[162:165], v[186:189], v[44:47]
	v_mfma_f32_16x16x32_bf16 v[40:43], v[170:173], v[186:189], v[40:43]
	v_mfma_f32_16x16x32_bf16 v[28:31], v[162:165], v[198:201], v[28:31]
	v_mfma_f32_16x16x32_bf16 v[24:27], v[170:173], v[198:201], v[24:27]
	v_mfma_f32_16x16x32_bf16 v[12:15], v[162:165], v[206:209], v[12:15]
	v_mfma_f32_16x16x32_bf16 v[8:11], v[170:173], v[206:209], v[8:11]
	s_barrier
	s_add_i32 s16, s31, s18
	v_lshl_add_u64 v[144:145], v[230:231], 0, s[44:45]
	s_mov_b32 m0, s16
	s_nop 0
	global_load_lds_dwordx4 v[144:145], off
	v_lshl_add_u64 v[144:145], v[232:233], 0, s[44:45]
	s_add_i32 m0, s16, 0x2000
	s_nop 0
	global_load_lds_dwordx4 v[144:145], off
	s_waitcnt vmcnt(6)
	s_barrier
	v_mfma_f32_16x16x32_bf16 v[52:55], v[210:213], v[174:177], v[52:55]
	v_mfma_f32_16x16x32_bf16 v[48:51], v[218:221], v[174:177], v[48:51]
	v_mfma_f32_16x16x32_bf16 v[36:39], v[210:213], v[182:185], v[36:39]
	v_mfma_f32_16x16x32_bf16 v[32:35], v[218:221], v[182:185], v[32:35]
	v_mfma_f32_16x16x32_bf16 v[20:23], v[210:213], v[190:193], v[20:23]
	v_mfma_f32_16x16x32_bf16 v[16:19], v[218:221], v[190:193], v[16:19]
	v_mfma_f32_16x16x32_bf16 v[4:7], v[210:213], v[202:205], v[4:7]
	v_mfma_f32_16x16x32_bf16 v[0:3], v[218:221], v[202:205], v[0:3]
	v_mfma_f32_16x16x32_bf16 v[52:55], v[214:217], v[178:181], v[52:55]
	v_mfma_f32_16x16x32_bf16 v[48:51], v[222:225], v[178:181], v[48:51]
	v_mfma_f32_16x16x32_bf16 v[36:39], v[214:217], v[186:189], v[36:39]
	v_mfma_f32_16x16x32_bf16 v[32:35], v[222:225], v[186:189], v[32:35]
	v_mfma_f32_16x16x32_bf16 v[20:23], v[214:217], v[198:201], v[20:23]
	v_mfma_f32_16x16x32_bf16 v[16:19], v[222:225], v[198:201], v[16:19]
	v_mfma_f32_16x16x32_bf16 v[4:7], v[214:217], v[206:209], v[4:7]
	v_mfma_f32_16x16x32_bf16 v[0:3], v[222:225], v[206:209], v[0:3]
	s_add_u32 s14, s14, 0x100
	s_addc_u32 s15, s15, 0
	s_add_u32 s59, s59, 0x100
	s_addc_u32 s60, s60, 0
	s_cmp_ge_i32 s61, s25
	s_mov_b32 s16, s61
	s_barrier
	s_cbranch_scc0 .LBB0_2510

; #define PG8_STAGE(bufoff, gbase, voff) do { _Pragma("unroll") for (int _i = 0; _i < 2; ++_i) \
;         __builtin_amdgcn_global_load_lds((const unsigned*)((const char*)(gbase) + (voff)[_i]), (LAS unsigned*)(lds + (bufoff) + ldsw + _i * 8192), 16, 0, 0); } while (0)
; #define PG8_LDA(dst, b, h) do { _Pragma("unroll") for (int m = 0; m < 4; ++m) _Pragma("unroll") for (int k = 0; k < 2; ++k) dst[m][k] = *(const LAS bf16x8*)(lds + PG8_SA(b, h) + aoff + m * 2048 + k * 1024); } while (0)
; #define PG8_LDB(dst, b, h) do { _Pragma("unroll") for (int n = 0; n < 2; ++n) _Pragma("unroll") for (int k = 0; k < 2; ++k) dst[n][k] = *(const LAS bf16x8*)(lds + PG8_SB(b, h) + boff + n * 2048 + k * 1024); } while (0)
; #define PG8_MMA(ai, bj, At, Bt) do { __builtin_amdgcn_s_setprio(1); _Pragma("unroll") for (int m = 0; m < 4; ++m) _Pragma("unroll") for (int n = 0; n < 2; ++n) _Pragma("unroll") for (int k = 0; k < 2; ++k) \
;         acc[ai][bj][m][n] = __builtin_amdgcn_mfma_f32_16x16x32_bf16(Bt[n][k], At[m][k], acc[ai][bj][m][n], 0, 0, 0); __builtin_amdgcn_s_setprio(0); } while (0)
; #define PG8_WAIT_L(n) asm volatile("s_waitcnt lgkmcnt(" #n ")" ::: "memory")
; #define PG8_BAR __builtin_amdgcn_s_barrier()
; #define PG8_SCHED __builtin_amdgcn_sched_barrier(0)
; template <class Epi>
; DEVI void gemm_phase(LAS unsigned char* lds, const bf16_t* gA, const bf16_t* gBt, const int lda, const int ldb, const int K, const StaticOrder S_, const Epi E) {
;     ...
;             const bool last = (t == nt - 2);
;             const char* a1 = cA + (size_t)(t + 1) * kstep;
;             const char* a2 = last ? nA : cA + (size_t)(t + 2) * kstep; const char* b2 = last ? nB : cB + (size_t)(t + 2) * kstep;
;             const char* a3 = a2 + kstep; const char* b3 = b2 + kstep;
;             PG8_LDB(B0, 0, 0); PG8_SCHED; PG8_LDA(At, 0, 0); PG8_STAGE(PG8_SA(1, 1), a1 + hstepA, voffA);
;             PG8_WAIT_L(8); PG8_BAR; PG8_WAIT_L(0); PG8_MMA(0, 0, At, B0); PG8_BAR; PG8_SCHED;
;             PG8_LDB(B1, 0, 1); PG8_STAGE(PG8_SB(0, 0), b2, voffB);
;             PG8_BAR; PG8_WAIT_L(0); PG8_MMA(0, 1, At, B1); PG8_BAR;
;             PG8_LDA(At, 0, 1); PG8_STAGE(PG8_SA(0, 0), a2, voffA);
;             PG8_BAR; PG8_WAIT_L(0); PG8_MMA(1, 0, At, B0); PG8_BAR; PG8_SCHED;
.LBB0_2589:
	ds_read_b128 v[128:131], v200
	ds_read_b128 v[132:135], v200 offset:1024
	ds_read_b128 v[136:139], v200 offset:2048
	ds_read_b128 v[140:143], v200 offset:3072
	s_add_i32 s56, s24, 2
	s_add_u32 s26, s4, 0x80
	s_addc_u32 s25, s5, 0
	s_cmp_eq_u32 s43, s24
	s_cselect_b32 s24, s22, s26
	s_cselect_b32 s25, s23, s25
	s_cselect_b32 s27, s7, s55
	s_cselect_b32 s26, s6, s54
	v_lshl_add_u64 v[164:165], s[4:5], 0, v[174:175]
	s_add_i32 m0, s34, 0xc000
	ds_read_b128 v[144:147], v201
	ds_read_b128 v[148:151], v201 offset:1024
	ds_read_b128 v[152:155], v201 offset:2048
	ds_read_b128 v[156:159], v201 offset:3072
	ds_read_b128 v[160:163], v201 offset:4096
	ds_read_b128 v[180:183], v201 offset:5120
	ds_read_b128 v[184:187], v201 offset:6144
	ds_read_b128 v[188:191], v201 offset:7168
	global_load_lds_dwordx4 v[164:165], off
	v_lshl_add_u64 v[164:165], s[4:5], 0, v[176:177]
	s_add_i32 m0, s34, 0xe000
	s_nop 0
	global_load_lds_dwordx4 v[164:165], off
	s_waitcnt lgkmcnt(8)
	s_barrier
	s_waitcnt lgkmcnt(0)
	s_waitcnt lgkmcnt(0)
	v_mfma_f32_16x16x32_bf16 v[124:127], v[128:131], v[144:147], v[124:127]
	v_mfma_f32_16x16x32_bf16 v[120:123], v[136:139], v[144:147], v[120:123]
	v_mfma_f32_16x16x32_bf16 v[108:111], v[128:131], v[152:155], v[108:111]
	v_mfma_f32_16x16x32_bf16 v[104:107], v[136:139], v[152:155], v[104:107]
	v_mfma_f32_16x16x32_bf16 v[92:95], v[128:131], v[160:163], v[92:95]
	v_mfma_f32_16x16x32_bf16 v[88:91], v[136:139], v[160:163], v[88:91]
	v_mfma_f32_16x16x32_bf16 v[76:79], v[128:131], v[184:187], v[76:79]
	v_mfma_f32_16x16x32_bf16 v[72:75], v[136:139], v[184:187], v[72:75]
	v_mfma_f32_16x16x32_bf16 v[124:127], v[132:135], v[148:151], v[124:127]
	v_mfma_f32_16x16x32_bf16 v[120:123], v[140:143], v[148:151], v[120:123]
	v_mfma_f32_16x16x32_bf16 v[108:111], v[132:135], v[156:159], v[108:111]
	v_mfma_f32_16x16x32_bf16 v[104:107], v[140:143], v[156:159], v[104:107]
	v_mfma_f32_16x16x32_bf16 v[92:95], v[132:135], v[180:183], v[92:95]
	v_mfma_f32_16x16x32_bf16 v[88:91], v[140:143], v[180:183], v[88:91]
	v_mfma_f32_16x16x32_bf16 v[76:79], v[132:135], v[188:191], v[76:79]
	v_mfma_f32_16x16x32_bf16 v[72:75], v[140:143], v[188:191], v[72:75]
	s_barrier
	s_add_i32 s57, s49, s30
	v_lshl_add_u64 v[164:165], s[26:27], 0, v[168:169]
	s_mov_b32 m0, s57
	ds_read_b128 v[192:195], v202
	ds_read_b128 v[204:207], v202 offset:1024
	ds_read_b128 v[208:211], v202 offset:2048
	ds_read_b128 v[212:215], v202 offset:3072
	global_load_lds_dwordx4 v[164:165], off
	v_lshl_add_u64 v[216:217], s[26:27], 0, v[172:173]
	s_add_i32 m0, s57, 0x2000
	s_nop 0
	global_load_lds_dwordx4 v[216:217], off
	s_barrier
	s_waitcnt lgkmcnt(0)
	s_waitcnt lgkmcnt(0)
	v_mfma_f32_16x16x32_bf16 v[116:119], v[192:195], v[144:147], v[116:119]
	v_mfma_f32_16x16x32_bf16 v[112:115], v[208:211], v[144:147], v[112:115]
	v_mfma_f32_16x16x32_bf16 v[100:103], v[192:195], v[152:155], v[100:103]
	v_mfma_f32_16x16x32_bf16 v[96:99], v[208:211], v[152:155], v[96:99]
	v_mfma_f32_16x16x32_bf16 v[84:87], v[192:195], v[160:163], v[84:87]
	v_mfma_f32_16x16x32_bf16 v[80:83], v[208:211], v[160:163], v[80:83]
	v_mfma_f32_16x16x32_bf16 v[68:71], v[192:195], v[184:187], v[68:71]
	v_mfma_f32_16x16x32_bf16 v[64:67], v[208:211], v[184:187], v[64:67]
	v_mfma_f32_16x16x32_bf16 v[116:119], v[204:207], v[148:151], v[116:119]
	v_mfma_f32_16x16x32_bf16 v[112:115], v[212:215], v[148:151], v[112:115]
	v_mfma_f32_16x16x32_bf16 v[100:103], v[204:207], v[156:159], v[100:103]
	v_mfma_f32_16x16x32_bf16 v[96:99], v[212:215], v[156:159], v[96:99]
	v_mfma_f32_16x16x32_bf16 v[84:87], v[204:207], v[180:183], v[84:87]
	v_mfma_f32_16x16x32_bf16 v[80:83], v[212:215], v[180:183], v[80:83]
	v_mfma_f32_16x16x32_bf16 v[68:71], v[204:207], v[188:191], v[68:71]
	v_mfma_f32_16x16x32_bf16 v[64:67], v[212:215], v[188:191], v[64:67]
	s_mov_b32 m0, s34
	v_lshl_add_u64 v[218:219], s[24:25], 0, v[166:167]
	s_barrier
	ds_read_b128 v[144:147], v201 offset:16384
	ds_read_b128 v[148:151], v201 offset:17408
	ds_read_b128 v[152:155], v201 offset:18432
	ds_read_b128 v[156:159], v201 offset:19456
	ds_read_b128 v[160:163], v201 offset:20480
	ds_read_b128 v[180:183], v201 offset:21504
	ds_read_b128 v[184:187], v201 offset:22528
	ds_read_b128 v[188:191], v201 offset:23552
	global_load_lds_dwordx4 v[218:219], off
	v_lshl_add_u64 v[220:221], s[24:25], 0, v[170:171]
	s_mov_b32 m0, s35
	s_nop 0
	global_load_lds_dwordx4 v[220:221], off
	s_barrier
	s_waitcnt lgkmcnt(0)
	s_waitcnt lgkmcnt(0)
	v_mfma_f32_16x16x32_bf16 v[60:63], v[128:131], v[144:147], v[60:63]
	v_mfma_f32_16x16x32_bf16 v[56:59], v[136:139], v[144:147], v[56:59]
	v_mfma_f32_16x16x32_bf16 v[44:47], v[128:131], v[152:155], v[44:47]
	v_mfma_f32_16x16x32_bf16 v[40:43], v[136:139], v[152:155], v[40:43]
	v_mfma_f32_16x16x32_bf16 v[28:31], v[128:131], v[160:163], v[28:31]
	v_mfma_f32_16x16x32_bf16 v[24:27], v[136:139], v[160:163], v[24:27]
	v_mfma_f32_16x16x32_bf16 v[12:15], v[128:131], v[184:187], v[12:15]
	v_mfma_f32_16x16x32_bf16 v[8:11], v[136:139], v[184:187], v[8:11]
	v_mfma_f32_16x16x32_bf16 v[60:63], v[132:135], v[148:151], v[60:63]
	v_mfma_f32_16x16x32_bf16 v[56:59], v[140:143], v[148:151], v[56:59]
	v_mfma_f32_16x16x32_bf16 v[44:47], v[132:135], v[156:159], v[44:47]
	v_mfma_f32_16x16x32_bf16 v[40:43], v[140:143], v[156:159], v[40:43]
	v_mfma_f32_16x16x32_bf16 v[28:31], v[132:135], v[180:183], v[28:31]
	v_mfma_f32_16x16x32_bf16 v[24:27], v[140:143], v[180:183], v[24:27]
	v_mfma_f32_16x16x32_bf16 v[12:15], v[132:135], v[188:191], v[12:15]
	v_mfma_f32_16x16x32_bf16 v[8:11], v[140:143], v[188:191], v[8:11]
	s_barrier
; #define PG8_STAGE(bufoff, gbase, voff) do { _Pragma("unroll") for (int _i = 0; _i < 2; ++_i) \
;         __builtin_amdgcn_global_load_lds((const unsigned*)((const char*)(gbase) + (voff)[_i]), (LAS unsigned*)(lds + (bufoff) + ldsw + _i * 8192), 16, 0, 0); } while (0)
; #define PG8_LDA(dst, b, h) do { _Pragma("unroll") for (int m = 0; m < 4; ++m) _Pragma("unroll") for (int k = 0; k < 2; ++k) dst[m][k] = *(const LAS bf16x8*)(lds + PG8_SA(b, h) + aoff + m * 2048 + k * 1024); } while (0)
; #define PG8_LDB(dst, b, h) do { _Pragma("unroll") for (int n = 0; n < 2; ++n) _Pragma("unroll") for (int k = 0; k < 2; ++k) dst[n][k] = *(const LAS bf16x8*)(lds + PG8_SB(b, h) + boff + n * 2048 + k * 1024); } while (0)
; #define PG8_MMA(ai, bj, At, Bt) do { __builtin_amdgcn_s_setprio(1); _Pragma("unroll") for (int m = 0; m < 4; ++m) _Pragma("unroll") for (int n = 0; n < 2; ++n) _Pragma("unroll") for (int k = 0; k < 2; ++k) \
;         acc[ai][bj][m][n] = __builtin_amdgcn_mfma_f32_16x16x32_bf16(Bt[n][k], At[m][k], acc[ai][bj][m][n], 0, 0, 0); __builtin_amdgcn_s_setprio(0); } while (0)
; #define PG8_WAIT_V(n) asm volatile("s_waitcnt vmcnt(" #n ")" ::: "memory")
; #define PG8_WAIT_L(n) asm volatile("s_waitcnt lgkmcnt(" #n ")" ::: "memory")
; #define PG8_BAR __builtin_amdgcn_s_barrier()
; #define PG8_SCHED __builtin_amdgcn_sched_barrier(0)
; template <class Epi>
; DEVI void gemm_phase(LAS unsigned char* lds, const bf16_t* gA, const bf16_t* gBt, const int lda, const int ldb, const int K, const StaticOrder S_, const Epi E) {
;     ...
;             PG8_STAGE(PG8_SB(0, 1), b2 + hstepB, voffB);
;             PG8_WAIT_V(6); PG8_BAR; PG8_MMA(1, 1, At, B1); PG8_BAR;
;             PG8_LDB(B0, 1, 0); PG8_SCHED; PG8_LDA(At, 1, 0); PG8_STAGE(PG8_SA(0, 1), a2 + hstepA, voffA);
;             PG8_WAIT_L(8); PG8_BAR; PG8_WAIT_L(0); PG8_MMA(0, 0, At, B0); PG8_BAR; PG8_SCHED;
;             PG8_LDB(B1, 1, 1); PG8_STAGE(PG8_SB(1, 0), b3, voffB);
	s_add_u32 s26, s26, s10
	s_addc_u32 s27, s27, s11
	s_add_i32 s57, s50, s30
	v_lshl_add_u64 v[222:223], s[26:27], 0, v[168:169]
	s_mov_b32 m0, s57
	v_lshl_add_u64 v[224:225], s[26:27], 0, v[172:173]
	global_load_lds_dwordx4 v[222:223], off
	s_add_i32 m0, s57, 0x2000
	s_nop 0
	global_load_lds_dwordx4 v[224:225], off
	s_waitcnt vmcnt(6)
	s_barrier
	v_mfma_f32_16x16x32_bf16 v[52:55], v[192:195], v[144:147], v[52:55]
	v_mfma_f32_16x16x32_bf16 v[48:51], v[208:211], v[144:147], v[48:51]
	v_mfma_f32_16x16x32_bf16 v[36:39], v[192:195], v[152:155], v[36:39]
	v_mfma_f32_16x16x32_bf16 v[32:35], v[208:211], v[152:155], v[32:35]
	v_mfma_f32_16x16x32_bf16 v[20:23], v[192:195], v[160:163], v[20:23]
	v_mfma_f32_16x16x32_bf16 v[16:19], v[208:211], v[160:163], v[16:19]
	v_mfma_f32_16x16x32_bf16 v[4:7], v[192:195], v[184:187], v[4:7]
	v_mfma_f32_16x16x32_bf16 v[0:3], v[208:211], v[184:187], v[0:3]
	v_mfma_f32_16x16x32_bf16 v[52:55], v[204:207], v[148:151], v[52:55]
	v_mfma_f32_16x16x32_bf16 v[48:51], v[212:215], v[148:151], v[48:51]
	v_mfma_f32_16x16x32_bf16 v[36:39], v[204:207], v[156:159], v[36:39]
	v_mfma_f32_16x16x32_bf16 v[32:35], v[212:215], v[156:159], v[32:35]
	v_mfma_f32_16x16x32_bf16 v[20:23], v[204:207], v[180:183], v[20:23]
	v_mfma_f32_16x16x32_bf16 v[16:19], v[212:215], v[180:183], v[16:19]
	v_mfma_f32_16x16x32_bf16 v[4:7], v[204:207], v[188:191], v[4:7]
	v_mfma_f32_16x16x32_bf16 v[0:3], v[212:215], v[188:191], v[0:3]
	s_add_i32 s26, 0, 0x18000
	v_add_u32_e32 v140, s26, v196
	s_barrier
	ds_read_b128 v[128:131], v140
	ds_read_b128 v[132:135], v140 offset:1024
	ds_read_b128 v[136:139], v140 offset:2048
	ds_read_b128 v[140:143], v140 offset:3072
	s_add_u32 s24, s24, s2
	s_addc_u32 s25, s25, s3
	s_mov_b32 m0, s36
	v_lshl_add_u64 v[192:193], s[24:25], 0, v[166:167]
	ds_read_b128 v[144:147], v201 offset:32768
	ds_read_b128 v[148:151], v201 offset:33792
	ds_read_b128 v[152:155], v201 offset:34816
	ds_read_b128 v[156:159], v201 offset:35840
	ds_read_b128 v[160:163], v201 offset:36864
	ds_read_b128 v[180:183], v201 offset:37888
	ds_read_b128 v[184:187], v201 offset:38912
	ds_read_b128 v[188:191], v201 offset:39936
	global_load_lds_dwordx4 v[192:193], off
	v_lshl_add_u64 v[192:193], s[24:25], 0, v[170:171]
	s_mov_b32 m0, s37
	s_nop 0
	global_load_lds_dwordx4 v[192:193], off
	s_waitcnt lgkmcnt(8)
	s_barrier
	s_waitcnt lgkmcnt(0)
	s_waitcnt lgkmcnt(0)
	v_mfma_f32_16x16x32_bf16 v[124:127], v[128:131], v[144:147], v[124:127]
	v_mfma_f32_16x16x32_bf16 v[120:123], v[136:139], v[144:147], v[120:123]
	v_mfma_f32_16x16x32_bf16 v[108:111], v[128:131], v[152:155], v[108:111]
	v_mfma_f32_16x16x32_bf16 v[104:107], v[136:139], v[152:155], v[104:107]
	v_mfma_f32_16x16x32_bf16 v[92:95], v[128:131], v[160:163], v[92:95]
	v_mfma_f32_16x16x32_bf16 v[88:91], v[136:139], v[160:163], v[88:91]
	v_mfma_f32_16x16x32_bf16 v[76:79], v[128:131], v[184:187], v[76:79]
	v_mfma_f32_16x16x32_bf16 v[72:75], v[136:139], v[184:187], v[72:75]
	v_mfma_f32_16x16x32_bf16 v[124:127], v[132:135], v[148:151], v[124:127]
	v_mfma_f32_16x16x32_bf16 v[120:123], v[140:143], v[148:151], v[120:123]
	v_mfma_f32_16x16x32_bf16 v[108:111], v[132:135], v[156:159], v[108:111]
	v_mfma_f32_16x16x32_bf16 v[104:107], v[140:143], v[156:159], v[104:107]
	v_mfma_f32_16x16x32_bf16 v[92:95], v[132:135], v[180:183], v[92:95]
	v_mfma_f32_16x16x32_bf16 v[88:91], v[140:143], v[180:183], v[88:91]
	v_mfma_f32_16x16x32_bf16 v[76:79], v[132:135], v[188:191], v[76:79]
	v_mfma_f32_16x16x32_bf16 v[72:75], v[140:143], v[188:191], v[72:75]
	s_barrier
	s_add_i32 s24, 0, 0x1c000
	s_add_i32 s25, s26, s30
	v_add_u32_e32 v212, s24, v196
	v_lshl_add_u64 v[164:165], v[164:165], 0, s[16:17]
	s_mov_b32 m0, s25
	ds_read_b128 v[192:195], v212
	ds_read_b128 v[204:207], v212 offset:1024
	ds_read_b128 v[208:211], v212 offset:2048
	ds_read_b128 v[212:215], v212 offset:3072
	global_load_lds_dwordx4 v[164:165], off
	v_lshl_add_u64 v[164:165], v[216:217], 0, s[16:17]
	s_add_i32 m0, s25, 0x2000
	s_nop 0
	global_load_lds_dwordx4 v[164:165], off
	s_barrier
; #define PG8_STAGE(bufoff, gbase, voff) do { _Pragma("unroll") for (int _i = 0; _i < 2; ++_i) \
;         __builtin_amdgcn_global_load_lds((const unsigned*)((const char*)(gbase) + (voff)[_i]), (LAS unsigned*)(lds + (bufoff) + ldsw + _i * 8192), 16, 0, 0); } while (0)
; #define PG8_LDA(dst, b, h) do { _Pragma("unroll") for (int m = 0; m < 4; ++m) _Pragma("unroll") for (int k = 0; k < 2; ++k) dst[m][k] = *(const LAS bf16x8*)(lds + PG8_SA(b, h) + aoff + m * 2048 + k * 1024); } while (0)
; #define PG8_MMA(ai, bj, At, Bt) do { __builtin_amdgcn_s_setprio(1); _Pragma("unroll") for (int m = 0; m < 4; ++m) _Pragma("unroll") for (int n = 0; n < 2; ++n) _Pragma("unroll") for (int k = 0; k < 2; ++k) \
;         acc[ai][bj][m][n] = __builtin_amdgcn_mfma_f32_16x16x32_bf16(Bt[n][k], At[m][k], acc[ai][bj][m][n], 0, 0, 0); __builtin_amdgcn_s_setprio(0); } while (0)
; #define PG8_WAIT_V(n) asm volatile("s_waitcnt vmcnt(" #n ")" ::: "memory")
; #define PG8_WAIT_L(n) asm volatile("s_waitcnt lgkmcnt(" #n ")" ::: "memory")
; #define PG8_BAR __builtin_amdgcn_s_barrier()
; #define PG8_SCHED __builtin_amdgcn_sched_barrier(0)
; template <class Epi>
; DEVI void gemm_phase(LAS unsigned char* lds, const bf16_t* gA, const bf16_t* gBt, const int lda, const int ldb, const int K, const StaticOrder S_, const Epi E) {
;     ...
;             PG8_BAR; PG8_WAIT_L(0); PG8_MMA(0, 1, At, B1); PG8_BAR;
;             PG8_LDA(At, 1, 1); PG8_STAGE(PG8_SA(1, 0), a3, voffA);
;             PG8_BAR; PG8_WAIT_L(0); PG8_MMA(1, 0, At, B0); PG8_BAR; PG8_SCHED;
;             PG8_STAGE(PG8_SB(1, 1), b3 + hstepB, voffB);
;             PG8_WAIT_V(6); PG8_BAR; PG8_MMA(1, 1, At, B1); PG8_BAR;
;         }
	s_waitcnt lgkmcnt(0)
	s_waitcnt lgkmcnt(0)
	v_mfma_f32_16x16x32_bf16 v[116:119], v[192:195], v[144:147], v[116:119]
	v_mfma_f32_16x16x32_bf16 v[112:115], v[208:211], v[144:147], v[112:115]
	v_mfma_f32_16x16x32_bf16 v[100:103], v[192:195], v[152:155], v[100:103]
	v_mfma_f32_16x16x32_bf16 v[96:99], v[208:211], v[152:155], v[96:99]
	v_mfma_f32_16x16x32_bf16 v[84:87], v[192:195], v[160:163], v[84:87]
	v_mfma_f32_16x16x32_bf16 v[80:83], v[208:211], v[160:163], v[80:83]
	v_mfma_f32_16x16x32_bf16 v[68:71], v[192:195], v[184:187], v[68:71]
	v_mfma_f32_16x16x32_bf16 v[64:67], v[208:211], v[184:187], v[64:67]
	v_mfma_f32_16x16x32_bf16 v[116:119], v[204:207], v[148:151], v[116:119]
	v_mfma_f32_16x16x32_bf16 v[112:115], v[212:215], v[148:151], v[112:115]
	v_mfma_f32_16x16x32_bf16 v[100:103], v[204:207], v[156:159], v[100:103]
	v_mfma_f32_16x16x32_bf16 v[96:99], v[212:215], v[156:159], v[96:99]
	v_mfma_f32_16x16x32_bf16 v[84:87], v[204:207], v[180:183], v[84:87]
	v_mfma_f32_16x16x32_bf16 v[80:83], v[212:215], v[180:183], v[80:83]
	v_mfma_f32_16x16x32_bf16 v[68:71], v[204:207], v[188:191], v[68:71]
	v_mfma_f32_16x16x32_bf16 v[64:67], v[212:215], v[188:191], v[64:67]
	s_mov_b32 m0, s39
	v_lshl_add_u64 v[164:165], v[218:219], 0, s[16:17]
	s_barrier
	ds_read_b128 v[144:147], v201 offset:49152
	ds_read_b128 v[148:151], v201 offset:50176
	ds_read_b128 v[152:155], v201 offset:51200
	ds_read_b128 v[156:159], v201 offset:52224
	ds_read_b128 v[160:163], v201 offset:53248
	ds_read_b128 v[180:183], v201 offset:54272
	ds_read_b128 v[184:187], v201 offset:55296
	ds_read_b128 v[188:191], v201 offset:56320
	global_load_lds_dwordx4 v[164:165], off
	v_lshl_add_u64 v[164:165], v[220:221], 0, s[16:17]
	s_mov_b32 m0, s40
	s_nop 0
	global_load_lds_dwordx4 v[164:165], off
	s_barrier
	s_waitcnt lgkmcnt(0)
	s_waitcnt lgkmcnt(0)
	v_mfma_f32_16x16x32_bf16 v[60:63], v[128:131], v[144:147], v[60:63]
	v_mfma_f32_16x16x32_bf16 v[56:59], v[136:139], v[144:147], v[56:59]
	v_mfma_f32_16x16x32_bf16 v[44:47], v[128:131], v[152:155], v[44:47]
	v_mfma_f32_16x16x32_bf16 v[40:43], v[136:139], v[152:155], v[40:43]
	v_mfma_f32_16x16x32_bf16 v[28:31], v[128:131], v[160:163], v[28:31]
	v_mfma_f32_16x16x32_bf16 v[24:27], v[136:139], v[160:163], v[24:27]
	v_mfma_f32_16x16x32_bf16 v[12:15], v[128:131], v[184:187], v[12:15]
	v_mfma_f32_16x16x32_bf16 v[8:11], v[136:139], v[184:187], v[8:11]
	v_mfma_f32_16x16x32_bf16 v[60:63], v[132:135], v[148:151], v[60:63]
	v_mfma_f32_16x16x32_bf16 v[56:59], v[140:143], v[148:151], v[56:59]
	v_mfma_f32_16x16x32_bf16 v[44:47], v[132:135], v[156:159], v[44:47]
	v_mfma_f32_16x16x32_bf16 v[40:43], v[140:143], v[156:159], v[40:43]
	v_mfma_f32_16x16x32_bf16 v[28:31], v[132:135], v[180:183], v[28:31]
	v_mfma_f32_16x16x32_bf16 v[24:27], v[140:143], v[180:183], v[24:27]
	v_mfma_f32_16x16x32_bf16 v[12:15], v[132:135], v[188:191], v[12:15]
	v_mfma_f32_16x16x32_bf16 v[8:11], v[140:143], v[188:191], v[8:11]
	s_barrier
	s_add_i32 s24, s24, s30
	v_lshl_add_u64 v[128:129], v[222:223], 0, s[16:17]
	s_mov_b32 m0, s24
	s_nop 0
	global_load_lds_dwordx4 v[128:129], off
	v_lshl_add_u64 v[128:129], v[224:225], 0, s[16:17]
	s_add_i32 m0, s24, 0x2000
	s_nop 0
	global_load_lds_dwordx4 v[128:129], off
	s_waitcnt vmcnt(6)
	s_barrier
	v_mfma_f32_16x16x32_bf16 v[52:55], v[192:195], v[144:147], v[52:55]
	v_mfma_f32_16x16x32_bf16 v[48:51], v[208:211], v[144:147], v[48:51]
	v_mfma_f32_16x16x32_bf16 v[36:39], v[192:195], v[152:155], v[36:39]
	v_mfma_f32_16x16x32_bf16 v[32:35], v[208:211], v[152:155], v[32:35]
	v_mfma_f32_16x16x32_bf16 v[20:23], v[192:195], v[160:163], v[20:23]
	v_mfma_f32_16x16x32_bf16 v[16:19], v[208:211], v[160:163], v[16:19]
	v_mfma_f32_16x16x32_bf16 v[4:7], v[192:195], v[184:187], v[4:7]
	v_mfma_f32_16x16x32_bf16 v[0:3], v[208:211], v[184:187], v[0:3]
	v_mfma_f32_16x16x32_bf16 v[52:55], v[204:207], v[148:151], v[52:55]
	v_mfma_f32_16x16x32_bf16 v[48:51], v[212:215], v[148:151], v[48:51]
	v_mfma_f32_16x16x32_bf16 v[36:39], v[204:207], v[156:159], v[36:39]
	v_mfma_f32_16x16x32_bf16 v[32:35], v[212:215], v[156:159], v[32:35]
	v_mfma_f32_16x16x32_bf16 v[20:23], v[204:207], v[180:183], v[20:23]
	v_mfma_f32_16x16x32_bf16 v[16:19], v[212:215], v[180:183], v[16:19]
	v_mfma_f32_16x16x32_bf16 v[4:7], v[204:207], v[188:191], v[4:7]
	v_mfma_f32_16x16x32_bf16 v[0:3], v[212:215], v[188:191], v[0:3]
	s_add_u32 s4, s4, 0x100
	s_addc_u32 s5, s5, 0
	s_add_u32 s54, s54, 0x100
	s_addc_u32 s55, s55, 0
	s_cmp_ge_i32 s56, s41
	s_mov_b32 s24, s56
	s_barrier
	s_cbranch_scc0 .LBB0_2589
	v_readlane_b32 s56, v241, 26
	v_readlane_b32 s58, v241, 28
	v_readlane_b32 s57, v241, 27
	v_readlane_b32 s59, v241, 29
